# GEMM K-loops: the two A-half-1 MFMA phases of each k-step run as one 32-MFMA phase (12 instead of 16 barriers per K iteration)
# speedup vs baseline: 1.0004x; 1.0004x over previous
; #define PG8_STAGE(bufoff, gbase, voff) do { _Pragma("unroll") for (int _i = 0; _i < 2; ++_i) \
;         __builtin_amdgcn_global_load_lds((const unsigned*)((const char*)(gbase) + (voff)[_i]), (LAS unsigned*)(lds + (bufoff) + ldsw + _i * 8192), 16, 0, 0); } while (0)
; #define PG8_LDA(dst, b, h) do { _Pragma("unroll") for (int m = 0; m < 4; ++m) _Pragma("unroll") for (int k = 0; k < 2; ++k) dst[m][k] = *(const LAS bf16x8*)(lds + PG8_SA(b, h) + aoff + m * 2048 + k * 1024); } while (0)
; #define PG8_LDB(dst, b, h) do { _Pragma("unroll") for (int n = 0; n < 2; ++n) _Pragma("unroll") for (int k = 0; k < 2; ++k) dst[n][k] = *(const LAS bf16x8*)(lds + PG8_SB(b, h) + boff + n * 2048 + k * 1024); } while (0)
; #define PG8_MMA(ai, bj, At, Bt) do { __builtin_amdgcn_s_setprio(1); _Pragma("unroll") for (int m = 0; m < 4; ++m) _Pragma("unroll") for (int n = 0; n < 2; ++n) _Pragma("unroll") for (int k = 0; k < 2; ++k) \
;         acc[ai][bj][m][n] = __builtin_amdgcn_mfma_f32_16x16x32_bf16(Bt[n][k], At[m][k], acc[ai][bj][m][n], 0, 0, 0); __builtin_amdgcn_s_setprio(0); } while (0)
; #define PG8_WAIT_V(n) asm volatile("s_waitcnt vmcnt(" #n ")" ::: "memory")
; template <class Epi>
; __device__ __forceinline__ void gemm_phase(LAS unsigned char* lds, const Gemm g, const StaticOrder& S, const Epi& E) {
;     ...
;         for (int t = 0; t < nt; t += 2) {
;             const bool last = (t == nt - 2);
;             const char* a1 = cA + (size_t)(t + 1) * kstep;
;             const char* a2 = last ? nA : cA + (size_t)(t + 2) * kstep; const char* b2 = last ? nB : cB + (size_t)(t + 2) * kstep;
;             const char* a3 = a2 + kstep; const char* b3 = b2 + kstep;
;             PG8_LDB(B0, 0, 0); PG8_SCHED; PG8_LDA(At, 0, 0); PG8_STAGE(PG8_SA(1, 1), a1 + hstep, voffA);
;             PG8_WAIT_L(8); PG8_BAR; PG8_WAIT_L(0); PG8_MMA(0, 0, At, B0); PG8_BAR; PG8_SCHED;
;             PG8_LDB(B1, 0, 1); PG8_STAGE(PG8_SB(0, 0), b2, voffB);
;             PG8_BAR; PG8_WAIT_L(0); PG8_MMA(0, 1, At, B1); PG8_BAR;
;             PG8_LDA(At, 0, 1); PG8_STAGE(PG8_SA(0, 0), a2, voffA);
;             PG8_BAR; PG8_WAIT_L(0); PG8_MMA(1, 0, At, B0); PG8_BAR; PG8_SCHED;
;             PG8_STAGE(PG8_SB(0, 1), b2 + hstep, voffB);
;             PG8_WAIT_V(6); PG8_BAR; PG8_MMA(1, 1, At, B1); PG8_BAR;
;             PG8_LDB(B0, 1, 0); PG8_SCHED; PG8_LDA(At, 1, 0); PG8_STAGE(PG8_SA(0, 1), a2 + hstep, voffA);
.LBB0_203:
	ds_read_b128 v[144:147], v153
	ds_read_b128 v[160:163], v153 offset:1024
	ds_read_b128 v[164:167], v153 offset:2048
	ds_read_b128 v[168:171], v153 offset:3072
	s_add_u32 s44, s42, 0xfff80080
	s_addc_u32 s45, s43, -1
	s_cmp_eq_u32 s54, 28
	s_cselect_b32 s47, s25, s45
	s_cselect_b32 s46, s50, s44
	s_cselect_b32 s45, s23, s53
	s_cselect_b32 s44, s51, s52
	s_add_i32 m0, s11, 0xc000
	ds_read_b128 v[172:175], v154
	ds_read_b128 v[176:179], v154 offset:1024
	ds_read_b128 v[180:183], v154 offset:2048
	ds_read_b128 v[184:187], v154 offset:3072
	ds_read_b128 v[188:191], v154 offset:4096
	ds_read_b128 v[192:195], v154 offset:5120
	ds_read_b128 v[196:199], v154 offset:6144
	ds_read_b128 v[200:203], v154 offset:7168
	global_load_lds_dwordx4 v136, s[42:43]
	s_add_i32 m0, s11, 0xe000
	s_nop 0
	global_load_lds_dwordx4 v138, s[42:43]
	s_waitcnt lgkmcnt(8)
	s_barrier
	s_waitcnt lgkmcnt(0)
	v_mfma_f32_16x16x32_bf16 v[124:127], v[144:147], v[172:175], v[124:127]
	v_mfma_f32_16x16x32_bf16 v[120:123], v[164:167], v[172:175], v[120:123]
	v_mfma_f32_16x16x32_bf16 v[108:111], v[144:147], v[180:183], v[108:111]
	v_mfma_f32_16x16x32_bf16 v[104:107], v[164:167], v[180:183], v[104:107]
	v_mfma_f32_16x16x32_bf16 v[92:95], v[144:147], v[188:191], v[92:95]
	v_mfma_f32_16x16x32_bf16 v[88:91], v[164:167], v[188:191], v[88:91]
	v_mfma_f32_16x16x32_bf16 v[76:79], v[144:147], v[196:199], v[76:79]
	v_mfma_f32_16x16x32_bf16 v[72:75], v[164:167], v[196:199], v[72:75]
	v_mfma_f32_16x16x32_bf16 v[124:127], v[160:163], v[176:179], v[124:127]
	v_mfma_f32_16x16x32_bf16 v[120:123], v[168:171], v[176:179], v[120:123]
	v_mfma_f32_16x16x32_bf16 v[108:111], v[160:163], v[184:187], v[108:111]
	v_mfma_f32_16x16x32_bf16 v[104:107], v[168:171], v[184:187], v[104:107]
	v_mfma_f32_16x16x32_bf16 v[92:95], v[160:163], v[192:195], v[92:95]
	v_mfma_f32_16x16x32_bf16 v[88:91], v[168:171], v[192:195], v[88:91]
	v_mfma_f32_16x16x32_bf16 v[76:79], v[160:163], v[200:203], v[76:79]
	v_mfma_f32_16x16x32_bf16 v[72:75], v[168:171], v[200:203], v[72:75]
	s_barrier
	s_add_i32 s55, s41, s10
	s_add_u32 s98, s44, s8
	s_addc_u32 s99, s45, s9
	s_mov_b32 m0, s55
	ds_read_b128 v[204:207], v155
	ds_read_b128 v[208:211], v155 offset:1024
	ds_read_b128 v[212:215], v155 offset:2048
	ds_read_b128 v[216:219], v155 offset:3072
	global_load_lds_dwordx4 v132, s[44:45]
	s_add_i32 m0, s55, 0x2000
	s_nop 0
	global_load_lds_dwordx4 v128, s[44:45]
	s_waitcnt lgkmcnt(0)
	s_barrier
	s_waitcnt lgkmcnt(0)
	v_mfma_f32_16x16x32_bf16 v[116:119], v[204:207], v[172:175], v[116:119]
	v_mfma_f32_16x16x32_bf16 v[112:115], v[212:215], v[172:175], v[112:115]
	v_mfma_f32_16x16x32_bf16 v[100:103], v[204:207], v[180:183], v[100:103]
	v_mfma_f32_16x16x32_bf16 v[96:99], v[212:215], v[180:183], v[96:99]
	v_mfma_f32_16x16x32_bf16 v[84:87], v[204:207], v[188:191], v[84:87]
	v_mfma_f32_16x16x32_bf16 v[80:83], v[212:215], v[188:191], v[80:83]
	v_mfma_f32_16x16x32_bf16 v[68:71], v[204:207], v[196:199], v[68:71]
	v_mfma_f32_16x16x32_bf16 v[64:67], v[212:215], v[196:199], v[64:67]
	v_mfma_f32_16x16x32_bf16 v[116:119], v[208:211], v[176:179], v[116:119]
	v_mfma_f32_16x16x32_bf16 v[112:115], v[216:219], v[176:179], v[112:115]
	v_mfma_f32_16x16x32_bf16 v[100:103], v[208:211], v[184:187], v[100:103]
	v_mfma_f32_16x16x32_bf16 v[96:99], v[216:219], v[184:187], v[96:99]
	v_mfma_f32_16x16x32_bf16 v[84:87], v[208:211], v[192:195], v[84:87]
	v_mfma_f32_16x16x32_bf16 v[80:83], v[216:219], v[192:195], v[80:83]
	v_mfma_f32_16x16x32_bf16 v[68:71], v[208:211], v[200:203], v[68:71]
	v_mfma_f32_16x16x32_bf16 v[64:67], v[216:219], v[200:203], v[64:67]
	s_mov_b32 m0, s11
	s_add_u32 s100, s46, s8
	s_addc_u32 s101, s47, s9
	s_barrier
	ds_read_b128 v[172:175], v154 offset:16384
	ds_read_b128 v[176:179], v154 offset:17408
	ds_read_b128 v[180:183], v154 offset:18432
	ds_read_b128 v[184:187], v154 offset:19456
	ds_read_b128 v[188:191], v154 offset:20480
	ds_read_b128 v[192:195], v154 offset:21504
	ds_read_b128 v[196:199], v154 offset:22528
	ds_read_b128 v[200:203], v154 offset:23552
	global_load_lds_dwordx4 v134, s[46:47]
	s_mov_b32 m0, s13
	s_nop 0
	global_load_lds_dwordx4 v130, s[46:47]
	s_add_u32 s56, s44, 0x80000
	s_addc_u32 s57, s45, 0
	s_add_i32 s55, s48, s10
	s_mov_b32 m0, s55
	s_nop 0
	global_load_lds_dwordx4 v132, s[56:57]
	s_add_i32 m0, s55, 0x2000
	s_nop 0
	global_load_lds_dwordx4 v128, s[56:57]
	s_waitcnt vmcnt(6)
	s_barrier
	s_waitcnt lgkmcnt(0)
	v_mfma_f32_16x16x32_bf16 v[60:63], v[144:147], v[172:175], v[60:63]
	v_mfma_f32_16x16x32_bf16 v[56:59], v[164:167], v[172:175], v[56:59]
	v_mfma_f32_16x16x32_bf16 v[44:47], v[144:147], v[180:183], v[44:47]
	v_mfma_f32_16x16x32_bf16 v[40:43], v[164:167], v[180:183], v[40:43]
	v_mfma_f32_16x16x32_bf16 v[28:31], v[144:147], v[188:191], v[28:31]
	v_mfma_f32_16x16x32_bf16 v[24:27], v[164:167], v[188:191], v[24:27]
	v_mfma_f32_16x16x32_bf16 v[12:15], v[144:147], v[196:199], v[12:15]
	v_mfma_f32_16x16x32_bf16 v[8:11], v[164:167], v[196:199], v[8:11]
	v_mfma_f32_16x16x32_bf16 v[60:63], v[160:163], v[176:179], v[60:63]
	v_mfma_f32_16x16x32_bf16 v[56:59], v[168:171], v[176:179], v[56:59]
	v_mfma_f32_16x16x32_bf16 v[44:47], v[160:163], v[184:187], v[44:47]
	v_mfma_f32_16x16x32_bf16 v[40:43], v[168:171], v[184:187], v[40:43]
	v_mfma_f32_16x16x32_bf16 v[28:31], v[160:163], v[192:195], v[28:31]
	v_mfma_f32_16x16x32_bf16 v[24:27], v[168:171], v[192:195], v[24:27]
	v_mfma_f32_16x16x32_bf16 v[12:15], v[160:163], v[200:203], v[12:15]
	v_mfma_f32_16x16x32_bf16 v[8:11], v[168:171], v[200:203], v[8:11]
	v_mfma_f32_16x16x32_bf16 v[52:55], v[204:207], v[172:175], v[52:55]
	v_mfma_f32_16x16x32_bf16 v[48:51], v[212:215], v[172:175], v[48:51]
	v_mfma_f32_16x16x32_bf16 v[36:39], v[204:207], v[180:183], v[36:39]
	v_mfma_f32_16x16x32_bf16 v[32:35], v[212:215], v[180:183], v[32:35]
	v_mfma_f32_16x16x32_bf16 v[20:23], v[204:207], v[188:191], v[20:23]
	v_mfma_f32_16x16x32_bf16 v[16:19], v[212:215], v[188:191], v[16:19]
	v_mfma_f32_16x16x32_bf16 v[4:7], v[204:207], v[196:199], v[4:7]
	v_mfma_f32_16x16x32_bf16 v[0:3], v[212:215], v[196:199], v[0:3]
	v_mfma_f32_16x16x32_bf16 v[52:55], v[208:211], v[176:179], v[52:55]
	v_mfma_f32_16x16x32_bf16 v[48:51], v[216:219], v[176:179], v[48:51]
	v_mfma_f32_16x16x32_bf16 v[36:39], v[208:211], v[184:187], v[36:39]
	v_mfma_f32_16x16x32_bf16 v[32:35], v[216:219], v[184:187], v[32:35]
	v_mfma_f32_16x16x32_bf16 v[20:23], v[208:211], v[192:195], v[20:23]
	v_mfma_f32_16x16x32_bf16 v[16:19], v[216:219], v[192:195], v[16:19]
	v_mfma_f32_16x16x32_bf16 v[4:7], v[208:211], v[200:203], v[4:7]
	v_mfma_f32_16x16x32_bf16 v[0:3], v[216:219], v[200:203], v[0:3]
	s_add_i32 s55, 0, 0x18000
	v_add_u32_e32 v168, s55, v151
	s_barrier
; #define PG8_STAGE(bufoff, gbase, voff) do { _Pragma("unroll") for (int _i = 0; _i < 2; ++_i) \
;         __builtin_amdgcn_global_load_lds((const unsigned*)((const char*)(gbase) + (voff)[_i]), (LAS unsigned*)(lds + (bufoff) + ldsw + _i * 8192), 16, 0, 0); } while (0)
; #define PG8_LDA(dst, b, h) do { _Pragma("unroll") for (int m = 0; m < 4; ++m) _Pragma("unroll") for (int k = 0; k < 2; ++k) dst[m][k] = *(const LAS bf16x8*)(lds + PG8_SA(b, h) + aoff + m * 2048 + k * 1024); } while (0)
; #define PG8_LDB(dst, b, h) do { _Pragma("unroll") for (int n = 0; n < 2; ++n) _Pragma("unroll") for (int k = 0; k < 2; ++k) dst[n][k] = *(const LAS bf16x8*)(lds + PG8_SB(b, h) + boff + n * 2048 + k * 1024); } while (0)
; #define PG8_MMA(ai, bj, At, Bt) do { __builtin_amdgcn_s_setprio(1); _Pragma("unroll") for (int m = 0; m < 4; ++m) _Pragma("unroll") for (int n = 0; n < 2; ++n) _Pragma("unroll") for (int k = 0; k < 2; ++k) \
;         acc[ai][bj][m][n] = __builtin_amdgcn_mfma_f32_16x16x32_bf16(Bt[n][k], At[m][k], acc[ai][bj][m][n], 0, 0, 0); __builtin_amdgcn_s_setprio(0); } while (0)
; #define PG8_WAIT_V(n) asm volatile("s_waitcnt vmcnt(" #n ")" ::: "memory")
; #define PG8_WAIT_L(n) asm volatile("s_waitcnt lgkmcnt(" #n ")" ::: "memory")
; #define PG8_BAR __builtin_amdgcn_s_barrier()
; #define PG8_SCHED __builtin_amdgcn_sched_barrier(0)
; template <class Epi>
; __device__ __forceinline__ void gemm_phase(LAS unsigned char* lds, const Gemm g, const StaticOrder& S, const Epi& E) {
;     ...
;             PG8_LDB(B0, 1, 0); PG8_SCHED; PG8_LDA(At, 1, 0); PG8_STAGE(PG8_SA(0, 1), a2 + hstep, voffA);
;             PG8_WAIT_L(8); PG8_BAR; PG8_WAIT_L(0); PG8_MMA(0, 0, At, B0); PG8_BAR; PG8_SCHED;
;             PG8_LDB(B1, 1, 1); PG8_STAGE(PG8_SB(1, 0), b3, voffB);
;             PG8_BAR; PG8_WAIT_L(0); PG8_MMA(0, 1, At, B1); PG8_BAR;
;             PG8_LDA(At, 1, 1); PG8_STAGE(PG8_SA(1, 0), a3, voffA);
;             PG8_BAR; PG8_WAIT_L(0); PG8_MMA(1, 0, At, B0); PG8_BAR; PG8_SCHED;
;             PG8_STAGE(PG8_SB(1, 1), b3 + hstep, voffB);
;             PG8_WAIT_V(6); PG8_BAR; PG8_MMA(1, 1, At, B1); PG8_BAR;
	ds_read_b128 v[144:147], v168
	ds_read_b128 v[160:163], v168 offset:1024
	ds_read_b128 v[164:167], v168 offset:2048
	ds_read_b128 v[168:171], v168 offset:3072
	s_add_u32 s46, s46, 0x80000
	s_addc_u32 s47, s47, 0
	s_mov_b32 m0, s30
	ds_read_b128 v[172:175], v154 offset:32768
	ds_read_b128 v[176:179], v154 offset:33792
	ds_read_b128 v[180:183], v154 offset:34816
	ds_read_b128 v[184:187], v154 offset:35840
	ds_read_b128 v[188:191], v154 offset:36864
	ds_read_b128 v[192:195], v154 offset:37888
	ds_read_b128 v[196:199], v154 offset:38912
	ds_read_b128 v[200:203], v154 offset:39936
	global_load_lds_dwordx4 v134, s[46:47]
	s_mov_b32 m0, s31
	s_nop 0
	global_load_lds_dwordx4 v130, s[46:47]
	s_waitcnt lgkmcnt(8)
	s_barrier
	s_waitcnt lgkmcnt(0)
	v_mfma_f32_16x16x32_bf16 v[124:127], v[144:147], v[172:175], v[124:127]
	v_mfma_f32_16x16x32_bf16 v[120:123], v[164:167], v[172:175], v[120:123]
	v_mfma_f32_16x16x32_bf16 v[108:111], v[144:147], v[180:183], v[108:111]
	v_mfma_f32_16x16x32_bf16 v[104:107], v[164:167], v[180:183], v[104:107]
	v_mfma_f32_16x16x32_bf16 v[92:95], v[144:147], v[188:191], v[92:95]
	v_mfma_f32_16x16x32_bf16 v[88:91], v[164:167], v[188:191], v[88:91]
	v_mfma_f32_16x16x32_bf16 v[76:79], v[144:147], v[196:199], v[76:79]
	v_mfma_f32_16x16x32_bf16 v[72:75], v[164:167], v[196:199], v[72:75]
	v_mfma_f32_16x16x32_bf16 v[124:127], v[160:163], v[176:179], v[124:127]
	v_mfma_f32_16x16x32_bf16 v[120:123], v[168:171], v[176:179], v[120:123]
	v_mfma_f32_16x16x32_bf16 v[108:111], v[160:163], v[184:187], v[108:111]
	v_mfma_f32_16x16x32_bf16 v[104:107], v[168:171], v[184:187], v[104:107]
	v_mfma_f32_16x16x32_bf16 v[92:95], v[160:163], v[192:195], v[92:95]
	v_mfma_f32_16x16x32_bf16 v[88:91], v[168:171], v[192:195], v[88:91]
	v_mfma_f32_16x16x32_bf16 v[76:79], v[160:163], v[200:203], v[76:79]
	v_mfma_f32_16x16x32_bf16 v[72:75], v[168:171], v[200:203], v[72:75]
	s_barrier
	s_add_i32 s46, 0, 0x1c000
	s_add_i32 s47, s55, s10
	v_add_u32_e32 v216, s46, v151
	s_mov_b32 m0, s47
	ds_read_b128 v[204:207], v216
	ds_read_b128 v[208:211], v216 offset:1024
	ds_read_b128 v[212:215], v216 offset:2048
	ds_read_b128 v[216:219], v216 offset:3072
	global_load_lds_dwordx4 v132, s[98:99]
	s_add_i32 m0, s47, 0x2000
	s_nop 0
	global_load_lds_dwordx4 v128, s[98:99]
	s_waitcnt lgkmcnt(0)
	s_barrier
	s_waitcnt lgkmcnt(0)
	v_mfma_f32_16x16x32_bf16 v[116:119], v[204:207], v[172:175], v[116:119]
	v_mfma_f32_16x16x32_bf16 v[112:115], v[212:215], v[172:175], v[112:115]
	v_mfma_f32_16x16x32_bf16 v[100:103], v[204:207], v[180:183], v[100:103]
	v_mfma_f32_16x16x32_bf16 v[96:99], v[212:215], v[180:183], v[96:99]
	v_mfma_f32_16x16x32_bf16 v[84:87], v[204:207], v[188:191], v[84:87]
	v_mfma_f32_16x16x32_bf16 v[80:83], v[212:215], v[188:191], v[80:83]
	v_mfma_f32_16x16x32_bf16 v[68:71], v[204:207], v[196:199], v[68:71]
	v_mfma_f32_16x16x32_bf16 v[64:67], v[212:215], v[196:199], v[64:67]
	v_mfma_f32_16x16x32_bf16 v[116:119], v[208:211], v[176:179], v[116:119]
	v_mfma_f32_16x16x32_bf16 v[112:115], v[216:219], v[176:179], v[112:115]
	v_mfma_f32_16x16x32_bf16 v[100:103], v[208:211], v[184:187], v[100:103]
	v_mfma_f32_16x16x32_bf16 v[96:99], v[216:219], v[184:187], v[96:99]
	v_mfma_f32_16x16x32_bf16 v[84:87], v[208:211], v[192:195], v[84:87]
	v_mfma_f32_16x16x32_bf16 v[80:83], v[216:219], v[192:195], v[80:83]
	v_mfma_f32_16x16x32_bf16 v[68:71], v[208:211], v[200:203], v[68:71]
	v_mfma_f32_16x16x32_bf16 v[64:67], v[216:219], v[200:203], v[64:67]
	s_mov_b32 m0, s36
	s_barrier
	ds_read_b128 v[172:175], v154 offset:49152
	ds_read_b128 v[176:179], v154 offset:50176
	ds_read_b128 v[180:183], v154 offset:51200
	ds_read_b128 v[184:187], v154 offset:52224
	ds_read_b128 v[188:191], v154 offset:53248
	ds_read_b128 v[192:195], v154 offset:54272
	ds_read_b128 v[196:199], v154 offset:55296
	ds_read_b128 v[200:203], v154 offset:56320
	global_load_lds_dwordx4 v134, s[100:101]
	s_mov_b32 m0, s37
	s_nop 0
	global_load_lds_dwordx4 v130, s[100:101]
	s_add_u32 s44, s44, 0x80080
	s_addc_u32 s45, s45, 0
	s_add_i32 s46, s46, s10
	s_mov_b32 m0, s46
	s_nop 0
	global_load_lds_dwordx4 v132, s[44:45]
	s_add_i32 m0, s46, 0x2000
	s_nop 0
	global_load_lds_dwordx4 v128, s[44:45]
	s_waitcnt vmcnt(6)
	s_barrier
	s_waitcnt lgkmcnt(0)
	v_mfma_f32_16x16x32_bf16 v[60:63], v[144:147], v[172:175], v[60:63]
	v_mfma_f32_16x16x32_bf16 v[56:59], v[164:167], v[172:175], v[56:59]
	v_mfma_f32_16x16x32_bf16 v[44:47], v[144:147], v[180:183], v[44:47]
	v_mfma_f32_16x16x32_bf16 v[40:43], v[164:167], v[180:183], v[40:43]
	v_mfma_f32_16x16x32_bf16 v[28:31], v[144:147], v[188:191], v[28:31]
	v_mfma_f32_16x16x32_bf16 v[24:27], v[164:167], v[188:191], v[24:27]
	v_mfma_f32_16x16x32_bf16 v[12:15], v[144:147], v[196:199], v[12:15]
	v_mfma_f32_16x16x32_bf16 v[8:11], v[164:167], v[196:199], v[8:11]
	v_mfma_f32_16x16x32_bf16 v[60:63], v[160:163], v[176:179], v[60:63]
	v_mfma_f32_16x16x32_bf16 v[56:59], v[168:171], v[176:179], v[56:59]
	v_mfma_f32_16x16x32_bf16 v[44:47], v[160:163], v[184:187], v[44:47]
	v_mfma_f32_16x16x32_bf16 v[40:43], v[168:171], v[184:187], v[40:43]
	v_mfma_f32_16x16x32_bf16 v[28:31], v[160:163], v[192:195], v[28:31]
	v_mfma_f32_16x16x32_bf16 v[24:27], v[168:171], v[192:195], v[24:27]
	v_mfma_f32_16x16x32_bf16 v[12:15], v[160:163], v[200:203], v[12:15]
	v_mfma_f32_16x16x32_bf16 v[8:11], v[168:171], v[200:203], v[8:11]
	v_mfma_f32_16x16x32_bf16 v[52:55], v[204:207], v[172:175], v[52:55]
	v_mfma_f32_16x16x32_bf16 v[48:51], v[212:215], v[172:175], v[48:51]
	v_mfma_f32_16x16x32_bf16 v[36:39], v[204:207], v[180:183], v[36:39]
	v_mfma_f32_16x16x32_bf16 v[32:35], v[212:215], v[180:183], v[32:35]
	v_mfma_f32_16x16x32_bf16 v[20:23], v[204:207], v[188:191], v[20:23]
	v_mfma_f32_16x16x32_bf16 v[16:19], v[212:215], v[188:191], v[16:19]
	v_mfma_f32_16x16x32_bf16 v[4:7], v[204:207], v[196:199], v[4:7]
	v_mfma_f32_16x16x32_bf16 v[0:3], v[212:215], v[196:199], v[0:3]
	v_mfma_f32_16x16x32_bf16 v[52:55], v[208:211], v[176:179], v[52:55]
	v_mfma_f32_16x16x32_bf16 v[48:51], v[216:219], v[176:179], v[48:51]
	v_mfma_f32_16x16x32_bf16 v[36:39], v[208:211], v[184:187], v[36:39]
	v_mfma_f32_16x16x32_bf16 v[32:35], v[216:219], v[184:187], v[32:35]
	v_mfma_f32_16x16x32_bf16 v[20:23], v[208:211], v[192:195], v[20:23]
	v_mfma_f32_16x16x32_bf16 v[16:19], v[216:219], v[192:195], v[16:19]
	v_mfma_f32_16x16x32_bf16 v[4:7], v[208:211], v[200:203], v[4:7]
	v_mfma_f32_16x16x32_bf16 v[0:3], v[216:219], v[200:203], v[0:3]
	s_add_i32 s54, s54, 2
	s_add_u32 s42, s42, 0x100
	s_addc_u32 s43, s43, 0
	s_add_u32 s52, s52, 0x100
	s_addc_u32 s53, s53, 0
	s_cmp_gt_u32 s54, 29
	s_barrier
; __device__ __forceinline__ float fast_rcp(float x) { return __builtin_amdgcn_rcpf(x); }
; __device__ __forceinline__ float fast_exp2(float x) { return __builtin_amdgcn_exp2f(x); }
; #define PG8_MMA(ai, bj, At, Bt) do { __builtin_amdgcn_s_setprio(1); _Pragma("unroll") for (int m = 0; m < 4; ++m) _Pragma("unroll") for (int n = 0; n < 2; ++n) _Pragma("unroll") for (int k = 0; k < 2; ++k) \
;         acc[ai][bj][m][n] = __builtin_amdgcn_mfma_f32_16x16x32_bf16(Bt[n][k], At[m][k], acc[ai][bj][m][n], 0, 0, 0); __builtin_amdgcn_s_setprio(0); } while (0)
; #define PG8_WAIT_V(n) asm volatile("s_waitcnt vmcnt(" #n ")" ::: "memory")
; #define PG8_BAR __builtin_amdgcn_s_barrier()
; __device__ __forceinline__ u32x4 pack8(f32x4 v0, f32x4 v1) { u32x4 w; w.x = cvt_pk_bf16(v0[0], v0[1]); w.y = cvt_pk_bf16(v0[2], v0[3]); w.z = cvt_pk_bf16(v1[0], v1[1]); w.w = cvt_pk_bf16(v1[2], v1[3]); return w; }
; template <class Epi>
; __device__ __forceinline__ void gemm_phase(LAS unsigned char* lds, const Gemm g, const StaticOrder& S, const Epi& E) {
;     ...
;             PG8_WAIT_V(6); PG8_BAR; PG8_MMA(1, 1, At, B1); PG8_BAR;
;         }
;     __device__ __forceinline__ void operator()(const f32x4 (&acc)[2][2][4][2], const Unit& u, int wr, int wc, int fr, int fq) const {
;         const int row0 = u.pm * BM + wr * 64 + fr, col0 = u.pn * HALF + wc * 32 + 8 * fq;
; #pragma unroll
;         for (int ai = 0; ai < 2; ++ai)
; #pragma unroll
;             for (int m = 0; m < 4; ++m) { bf16_t* rowp = O + (size_t)(row0 + ai * HALF + m * 16) * DFF + col0;
;                 const float r = rs[row0 + ai * HALF + m * 16], r2 = r * r;
;                 f32x4 h0, h1;
; #pragma unroll
;                 for (int j = 0; j < 4; ++j) {
;                     const float g0 = acc[ai][0][m][0][j], g1 = acc[ai][0][m][1][j];
;                     h0[j] = g0 * r2 * fast_rcp(1.0f + fast_exp2(g0 * (-LOG2E * r))) * acc[ai][1][m][0][j];
;                     h1[j] = g1 * r2 * fast_rcp(1.0f + fast_exp2(g1 * (-LOG2E * r))) * acc[ai][1][m][1][j]; }
;                 *(u32x4*)rowp = pack8(h0, h1); }
	s_cbranch_scc0 .LBB0_203
	v_lshl_add_u32 v144, s40, 8, v150
	v_ashrrev_i32_e32 v145, 31, v144
	v_lshl_add_u64 v[148:149], v[144:145], 2, s[14:15]
	v_mov_b32_e32 v145, v224
	v_mov_b32_e32 v204, v225
	v_mov_b32_e32 v205, v226
	v_mov_b32_e32 v206, v227
	v_mov_b32_e32 v207, v228
	v_mov_b32_e32 v208, v229
	v_mov_b32_e32 v209, v230
	v_mov_b32_e32 v210, v231
	v_lshl_or_b32 v156, s34, 7, v152
	v_ashrrev_i32_e32 v157, 31, v156
	v_mov_b64_e32 v[146:147], s[20:21]
	v_mad_i64_i32 v[160:161], s[42:43], v144, s49, v[146:147]
	s_and_b64 vcc, exec, s[4:5]
	s_mov_b32 s34, s22
	s_mov_b32 s40, s24
	s_mov_b64 s[44:45], s[28:29]
	v_mul_f32_e32 v162, v145, v145
	v_mul_f32_e32 v145, 0xbfb8aa3b, v145
	v_mul_f32_e32 v163, v124, v162
	v_mul_f32_e32 v124, v124, v145
	v_exp_f32_e32 v124, v124
	s_nop 0
	v_add_f32_e32 v124, 1.0, v124
	v_rcp_f32_e32 v124, v124
	s_nop 0
	v_mul_f32_e32 v124, v163, v124
	v_mul_f32_e32 v116, v116, v124
	v_mul_f32_e32 v124, v120, v162
	v_mul_f32_e32 v120, v120, v145
	v_exp_f32_e32 v120, v120
	s_nop 0
	v_add_f32_e32 v120, 1.0, v120
	v_rcp_f32_e32 v120, v120
	s_nop 0
	v_mul_f32_e32 v120, v124, v120
	v_mul_f32_e32 v124, v125, v145
	v_exp_f32_e32 v124, v124
	v_mul_f32_e32 v120, v112, v120
	v_mul_f32_e32 v112, v125, v162
	v_add_f32_e32 v124, 1.0, v124
	v_rcp_f32_e32 v124, v124
	s_nop 0
	v_mul_f32_e32 v112, v112, v124
	v_mul_f32_e32 v117, v117, v112
	v_mul_f32_e32 v112, v121, v162
	v_mul_f32_e32 v121, v121, v145
	v_exp_f32_e32 v121, v121
	s_nop 0
	v_add_f32_e32 v121, 1.0, v121
	v_rcp_f32_e32 v121, v121
	s_nop 0
	v_mul_f32_e32 v112, v112, v121
	v_mul_f32_e32 v121, v113, v112
	v_mul_f32_e32 v113, v126, v145
	v_exp_f32_e32 v113, v113
	v_mul_f32_e32 v112, v126, v162
	v_add_f32_e32 v113, 1.0, v113
	v_rcp_f32_e32 v113, v113
	s_nop 0
	v_mul_f32_e32 v112, v112, v113
	v_mul_f32_e32 v113, v122, v145
	v_exp_f32_e32 v113, v113
	v_mul_f32_e32 v124, v118, v112
	v_mul_f32_e32 v112, v122, v162
	v_add_f32_e32 v113, 1.0, v113
	v_rcp_f32_e32 v113, v113
	s_nop 0
	v_mul_f32_e32 v112, v112, v113
	v_mul_f32_e32 v113, v127, v145
	v_exp_f32_e32 v113, v113
	v_mul_f32_e32 v122, v114, v112
	v_mul_f32_e32 v112, v127, v162
	v_cvt_pk_bf16_f32 v114, v116, v117
	v_add_f32_e32 v113, 1.0, v113
	v_rcp_f32_e32 v113, v113
	s_nop 0
	v_mul_f32_e32 v112, v112, v113
	v_mul_f32_e32 v113, v123, v145
	v_exp_f32_e32 v113, v113
	v_mul_f32_e32 v125, v119, v112
	v_mul_f32_e32 v112, v123, v162
	v_add_f32_e32 v113, 1.0, v113
	v_rcp_f32_e32 v113, v113
	s_nop 0
	v_mul_f32_e32 v112, v112, v113
	v_mul_f32_e32 v123, v115, v112
	v_lshlrev_b64 v[112:113], 1, v[156:157]
	v_lshl_add_u64 v[118:119], v[160:161], 0, v[112:113]
	v_cvt_pk_bf16_f32 v115, v124, v125
	v_cvt_pk_bf16_f32 v116, v120, v121
	v_cvt_pk_bf16_f32 v117, v122, v123
	global_store_dwordx4 v[118:119], v[114:117], off
	s_nop 1
	v_mov_b32_e32 v116, v204
	s_nop 0
	v_or_b32_e32 v114, 16, v144
	v_mad_i64_i32 v[114:115], s[42:43], v114, s49, v[146:147]
	v_mul_f32_e32 v117, v116, v116
	v_mul_f32_e32 v116, 0xbfb8aa3b, v116
	v_mul_f32_e32 v118, v108, v117
	v_mul_f32_e32 v108, v108, v116
	v_exp_f32_e32 v108, v108
	s_nop 0
	v_add_f32_e32 v108, 1.0, v108
	v_rcp_f32_e32 v108, v108
	s_nop 0
	v_mul_f32_e32 v108, v118, v108
	v_mul_f32_e32 v108, v100, v108
	v_mul_f32_e32 v100, v104, v117
	v_mul_f32_e32 v104, v104, v116
	v_exp_f32_e32 v104, v104
	s_nop 0
	v_add_f32_e32 v104, 1.0, v104
	v_rcp_f32_e32 v104, v104
	s_nop 0
	v_mul_f32_e32 v100, v100, v104
	v_mul_f32_e32 v104, v96, v100
	v_mul_f32_e32 v100, v109, v116
	v_exp_f32_e32 v100, v100
	v_mul_f32_e32 v96, v109, v117
	v_add_f32_e32 v100, 1.0, v100
	v_rcp_f32_e32 v100, v100
	s_nop 0
	v_mul_f32_e32 v96, v96, v100
	v_mul_f32_e32 v96, v101, v96
	v_mul_f32_e32 v101, v105, v116
	v_exp_f32_e32 v101, v101
	v_mul_f32_e32 v100, v105, v117
	v_cvt_pk_bf16_f32 v96, v108, v96
	v_add_f32_e32 v101, 1.0, v101
	v_rcp_f32_e32 v101, v101
	s_nop 0
	v_mul_f32_e32 v100, v100, v101
	v_mul_f32_e32 v105, v97, v100
	v_mul_f32_e32 v100, v110, v116
	v_exp_f32_e32 v100, v100
	v_mul_f32_e32 v101, v106, v116
	v_exp_f32_e32 v101, v101
	v_mul_f32_e32 v97, v110, v117
	v_add_f32_e32 v100, 1.0, v100
	v_rcp_f32_e32 v100, v100
	v_add_f32_e32 v101, 1.0, v101
	v_rcp_f32_e32 v101, v101
	v_mul_f32_e32 v97, v97, v100
	v_mul_f32_e32 v100, v106, v117
	v_mul_f32_e32 v100, v100, v101
	v_mul_f32_e32 v97, v102, v97
	v_mul_f32_e32 v102, v98, v100
	v_mul_f32_e32 v100, v111, v116
	v_exp_f32_e32 v100, v100
	v_mul_f32_e32 v101, v107, v116
	v_exp_f32_e32 v101, v101
	v_mul_f32_e32 v98, v111, v117
	v_add_f32_e32 v100, 1.0, v100
	v_rcp_f32_e32 v100, v100
	v_add_f32_e32 v101, 1.0, v101
	v_rcp_f32_e32 v101, v101
	v_mul_f32_e32 v98, v98, v100
	v_mul_f32_e32 v100, v107, v117
	v_mul_f32_e32 v100, v100, v101
	v_mul_f32_e32 v98, v103, v98
	v_mul_f32_e32 v99, v99, v100
	v_lshl_add_u64 v[100:101], v[114:115], 0, v[112:113]
	v_cvt_pk_bf16_f32 v97, v97, v98
	v_cvt_pk_bf16_f32 v98, v104, v105
	v_cvt_pk_bf16_f32 v99, v102, v99
	global_store_dwordx4 v[100:101], v[96:99], off
	s_nop 1
	v_mov_b32_e32 v98, v205
	s_nop 0
	v_or_b32_e32 v96, 32, v144
	v_mad_i64_i32 v[96:97], s[42:43], v96, s49, v[146:147]
	v_mul_f32_e32 v99, v98, v98
	v_mul_f32_e32 v98, 0xbfb8aa3b, v98
	v_mul_f32_e32 v100, v92, v99
	v_mul_f32_e32 v92, v92, v98
	v_exp_f32_e32 v92, v92
	s_nop 0
	v_add_f32_e32 v92, 1.0, v92
	v_rcp_f32_e32 v92, v92
	s_nop 0
	v_mul_f32_e32 v92, v100, v92
	v_mul_f32_e32 v92, v84, v92
	v_mul_f32_e32 v84, v88, v99
	v_mul_f32_e32 v88, v88, v98
	v_exp_f32_e32 v88, v88
	s_nop 0
	v_add_f32_e32 v88, 1.0, v88
	v_rcp_f32_e32 v88, v88
	s_nop 0
	v_mul_f32_e32 v84, v84, v88
	v_mul_f32_e32 v88, v80, v84
	v_mul_f32_e32 v84, v93, v98
	v_exp_f32_e32 v84, v84
	v_mul_f32_e32 v80, v93, v99
	v_add_f32_e32 v84, 1.0, v84
; __device__ __forceinline__ float fast_rcp(float x) { return __builtin_amdgcn_rcpf(x); }
; __device__ __forceinline__ float fast_exp2(float x) { return __builtin_amdgcn_exp2f(x); }
; __device__ __forceinline__ u32x4 pack8(f32x4 v0, f32x4 v1) { u32x4 w; w.x = cvt_pk_bf16(v0[0], v0[1]); w.y = cvt_pk_bf16(v0[2], v0[3]); w.z = cvt_pk_bf16(v1[0], v1[1]); w.w = cvt_pk_bf16(v1[2], v1[3]); return w; }
;     __device__ __forceinline__ void operator()(const f32x4 (&acc)[2][2][4][2], const Unit& u, int wr, int wc, int fr, int fq) const {
;         const int row0 = u.pm * BM + wr * 64 + fr, col0 = u.pn * HALF + wc * 32 + 8 * fq;
; #pragma unroll
;         for (int ai = 0; ai < 2; ++ai)
; #pragma unroll
;             for (int m = 0; m < 4; ++m) { bf16_t* rowp = O + (size_t)(row0 + ai * HALF + m * 16) * DFF + col0;
;                 const float r = rs[row0 + ai * HALF + m * 16], r2 = r * r;
;                 f32x4 h0, h1;
; #pragma unroll
;                 for (int j = 0; j < 4; ++j) {
;                     const float g0 = acc[ai][0][m][0][j], g1 = acc[ai][0][m][1][j];
;                     h0[j] = g0 * r2 * fast_rcp(1.0f + fast_exp2(g0 * (-LOG2E * r))) * acc[ai][1][m][0][j];
;                     h1[j] = g1 * r2 * fast_rcp(1.0f + fast_exp2(g1 * (-LOG2E * r))) * acc[ai][1][m][1][j]; }
;                 *(u32x4*)rowp = pack8(h0, h1); }
	v_rcp_f32_e32 v84, v84
	s_nop 0
	v_mul_f32_e32 v80, v80, v84
	v_mul_f32_e32 v80, v85, v80
	v_mul_f32_e32 v85, v89, v98
	v_exp_f32_e32 v85, v85
	v_mul_f32_e32 v84, v89, v99
	v_cvt_pk_bf16_f32 v80, v92, v80
	v_add_f32_e32 v85, 1.0, v85
	v_rcp_f32_e32 v85, v85
	s_nop 0
	v_mul_f32_e32 v84, v84, v85
	v_mul_f32_e32 v89, v81, v84
	v_mul_f32_e32 v84, v94, v98
	v_exp_f32_e32 v84, v84
	v_mul_f32_e32 v85, v90, v98
	v_exp_f32_e32 v85, v85
	v_mul_f32_e32 v81, v94, v99
	v_add_f32_e32 v84, 1.0, v84
	v_rcp_f32_e32 v84, v84
	v_add_f32_e32 v85, 1.0, v85
	v_rcp_f32_e32 v85, v85
	v_mul_f32_e32 v81, v81, v84
	v_mul_f32_e32 v84, v90, v99
	v_mul_f32_e32 v84, v84, v85
	v_mul_f32_e32 v81, v86, v81
	v_mul_f32_e32 v86, v82, v84
	v_mul_f32_e32 v84, v95, v98
	v_exp_f32_e32 v84, v84
	v_mul_f32_e32 v85, v91, v98
	v_exp_f32_e32 v85, v85
	v_mul_f32_e32 v82, v95, v99
	v_add_f32_e32 v84, 1.0, v84
	v_rcp_f32_e32 v84, v84
	v_add_f32_e32 v85, 1.0, v85
	v_rcp_f32_e32 v85, v85
	v_mul_f32_e32 v82, v82, v84
	v_mul_f32_e32 v84, v91, v99
	v_mul_f32_e32 v84, v84, v85
	v_mul_f32_e32 v82, v87, v82
	v_mul_f32_e32 v83, v83, v84
	v_lshl_add_u64 v[84:85], v[96:97], 0, v[112:113]
	v_cvt_pk_bf16_f32 v81, v81, v82
	v_cvt_pk_bf16_f32 v82, v88, v89
	v_cvt_pk_bf16_f32 v83, v86, v83
	global_store_dwordx4 v[84:85], v[80:83], off
	s_nop 1
	v_mov_b32_e32 v82, v206
	s_nop 0
	v_or_b32_e32 v80, 48, v144
	v_mad_i64_i32 v[80:81], s[42:43], v80, s49, v[146:147]
	v_mul_f32_e32 v83, v82, v82
	v_mul_f32_e32 v82, 0xbfb8aa3b, v82
	v_mul_f32_e32 v84, v76, v83
	v_mul_f32_e32 v76, v76, v82
	v_exp_f32_e32 v76, v76
	s_nop 0
	v_add_f32_e32 v76, 1.0, v76
	v_rcp_f32_e32 v76, v76
	s_nop 0
	v_mul_f32_e32 v76, v84, v76
	v_mul_f32_e32 v76, v68, v76
	v_mul_f32_e32 v68, v72, v83
	v_mul_f32_e32 v72, v72, v82
	v_exp_f32_e32 v72, v72
	s_nop 0
	v_add_f32_e32 v72, 1.0, v72
	v_rcp_f32_e32 v72, v72
	s_nop 0
	v_mul_f32_e32 v68, v68, v72
	v_mul_f32_e32 v72, v64, v68
	v_mul_f32_e32 v68, v77, v82
	v_exp_f32_e32 v68, v68
	v_mul_f32_e32 v64, v77, v83
	v_add_f32_e32 v68, 1.0, v68
	v_rcp_f32_e32 v68, v68
	s_nop 0
	v_mul_f32_e32 v64, v64, v68
	v_mul_f32_e32 v64, v69, v64
	v_mul_f32_e32 v69, v73, v82
	v_exp_f32_e32 v69, v69
	v_mul_f32_e32 v68, v73, v83
	v_cvt_pk_bf16_f32 v64, v76, v64
	v_add_f32_e32 v69, 1.0, v69
	v_rcp_f32_e32 v69, v69
	s_nop 0
	v_mul_f32_e32 v68, v68, v69
	v_mul_f32_e32 v73, v65, v68
	v_mul_f32_e32 v68, v78, v82
	v_exp_f32_e32 v68, v68
	v_mul_f32_e32 v69, v74, v82
	v_exp_f32_e32 v69, v69
	v_mul_f32_e32 v65, v78, v83
	v_add_f32_e32 v68, 1.0, v68
	v_rcp_f32_e32 v68, v68
	v_add_f32_e32 v69, 1.0, v69
	v_rcp_f32_e32 v69, v69
	v_mul_f32_e32 v65, v65, v68
	v_mul_f32_e32 v68, v74, v83
	v_mul_f32_e32 v68, v68, v69
	v_mul_f32_e32 v65, v70, v65
	v_mul_f32_e32 v70, v66, v68
	v_mul_f32_e32 v68, v79, v82
	v_exp_f32_e32 v68, v68
	v_mul_f32_e32 v69, v75, v82
	v_exp_f32_e32 v69, v69
	v_mul_f32_e32 v66, v79, v83
	v_add_f32_e32 v68, 1.0, v68
	v_rcp_f32_e32 v68, v68
	v_add_f32_e32 v69, 1.0, v69
	v_rcp_f32_e32 v69, v69
	v_mul_f32_e32 v66, v66, v68
	v_mul_f32_e32 v68, v75, v83
	v_mul_f32_e32 v68, v68, v69
	v_mul_f32_e32 v66, v71, v66
	v_mul_f32_e32 v67, v67, v68
	v_lshl_add_u64 v[68:69], v[80:81], 0, v[112:113]
	v_cvt_pk_bf16_f32 v65, v65, v66
	v_cvt_pk_bf16_f32 v66, v72, v73
	v_cvt_pk_bf16_f32 v67, v70, v67
	global_store_dwordx4 v[68:69], v[64:67], off
	s_nop 1
	v_mov_b32_e32 v66, v207
	s_nop 0
	v_add_u32_e32 v64, 0x80, v144
	v_mad_i64_i32 v[64:65], s[42:43], v64, s49, v[146:147]
	v_mul_f32_e32 v67, v66, v66
	v_mul_f32_e32 v66, 0xbfb8aa3b, v66
	v_mul_f32_e32 v68, v60, v67
	v_mul_f32_e32 v60, v60, v66
	v_exp_f32_e32 v60, v60
	s_nop 0
	v_add_f32_e32 v60, 1.0, v60
	v_rcp_f32_e32 v60, v60
	s_nop 0
	v_mul_f32_e32 v60, v68, v60
	v_mul_f32_e32 v60, v52, v60
	v_mul_f32_e32 v52, v56, v67
	v_mul_f32_e32 v56, v56, v66
	v_exp_f32_e32 v56, v56
	s_nop 0
	v_add_f32_e32 v56, 1.0, v56
	v_rcp_f32_e32 v56, v56
	s_nop 0
	v_mul_f32_e32 v52, v52, v56
	v_mul_f32_e32 v56, v48, v52
	v_mul_f32_e32 v52, v61, v66
	v_exp_f32_e32 v52, v52
	v_mul_f32_e32 v48, v61, v67
	v_add_f32_e32 v52, 1.0, v52
	v_rcp_f32_e32 v52, v52
	s_nop 0
	v_mul_f32_e32 v48, v48, v52
	v_mul_f32_e32 v48, v53, v48
	v_mul_f32_e32 v53, v57, v66
	v_exp_f32_e32 v53, v53
	v_mul_f32_e32 v52, v57, v67
	v_cvt_pk_bf16_f32 v48, v60, v48
	v_add_f32_e32 v53, 1.0, v53
	v_rcp_f32_e32 v53, v53
	s_nop 0
	v_mul_f32_e32 v52, v52, v53
	v_mul_f32_e32 v57, v49, v52
	v_mul_f32_e32 v52, v62, v66
	v_exp_f32_e32 v52, v52
	v_mul_f32_e32 v53, v58, v66
	v_exp_f32_e32 v53, v53
	v_mul_f32_e32 v49, v62, v67
	v_add_f32_e32 v52, 1.0, v52
	v_rcp_f32_e32 v52, v52
	v_add_f32_e32 v53, 1.0, v53
	v_rcp_f32_e32 v53, v53
	v_mul_f32_e32 v49, v49, v52
	v_mul_f32_e32 v52, v58, v67
	v_mul_f32_e32 v52, v52, v53
	v_mul_f32_e32 v49, v54, v49
	v_mul_f32_e32 v54, v50, v52
	v_mul_f32_e32 v52, v63, v66
	v_exp_f32_e32 v52, v52
	v_mul_f32_e32 v53, v59, v66
	v_exp_f32_e32 v53, v53
	v_mul_f32_e32 v50, v63, v67
	v_add_f32_e32 v52, 1.0, v52
	v_rcp_f32_e32 v52, v52
	v_add_f32_e32 v53, 1.0, v53
	v_rcp_f32_e32 v53, v53
	v_mul_f32_e32 v50, v50, v52
	v_mul_f32_e32 v52, v59, v67
	v_mul_f32_e32 v52, v52, v53
	v_mul_f32_e32 v50, v55, v50
	v_mul_f32_e32 v51, v51, v52
	v_lshl_add_u64 v[52:53], v[64:65], 0, v[112:113]
	v_cvt_pk_bf16_f32 v49, v49, v50
	v_cvt_pk_bf16_f32 v50, v56, v57
	v_cvt_pk_bf16_f32 v51, v54, v51
	global_store_dwordx4 v[52:53], v[48:51], off
	s_nop 1
	v_mov_b32_e32 v50, v208
	s_nop 0
	v_add_u32_e32 v48, 0x90, v144
	v_mad_i64_i32 v[48:49], s[42:43], v48, s49, v[146:147]
	v_mul_f32_e32 v51, v50, v50
	v_mul_f32_e32 v50, 0xbfb8aa3b, v50
	v_mul_f32_e32 v52, v44, v51
	v_mul_f32_e32 v44, v44, v50
	v_exp_f32_e32 v44, v44
	s_nop 0
	v_add_f32_e32 v44, 1.0, v44
; __device__ __forceinline__ float fast_rcp(float x) { return __builtin_amdgcn_rcpf(x); }
; __device__ __forceinline__ float fast_exp2(float x) { return __builtin_amdgcn_exp2f(x); }
; __device__ __forceinline__ u32x4 pack8(f32x4 v0, f32x4 v1) { u32x4 w; w.x = cvt_pk_bf16(v0[0], v0[1]); w.y = cvt_pk_bf16(v0[2], v0[3]); w.z = cvt_pk_bf16(v1[0], v1[1]); w.w = cvt_pk_bf16(v1[2], v1[3]); return w; }
;     __device__ __forceinline__ void operator()(const f32x4 (&acc)[2][2][4][2], const Unit& u, int wr, int wc, int fr, int fq) const {
;         const int row0 = u.pm * BM + wr * 64 + fr, col0 = u.pn * HALF + wc * 32 + 8 * fq;
; #pragma unroll
;         for (int ai = 0; ai < 2; ++ai)
; #pragma unroll
;             for (int m = 0; m < 4; ++m) { bf16_t* rowp = O + (size_t)(row0 + ai * HALF + m * 16) * DFF + col0;
;                 const float r = rs[row0 + ai * HALF + m * 16], r2 = r * r;
;                 f32x4 h0, h1;
; #pragma unroll
;                 for (int j = 0; j < 4; ++j) {
;                     const float g0 = acc[ai][0][m][0][j], g1 = acc[ai][0][m][1][j];
;                     h0[j] = g0 * r2 * fast_rcp(1.0f + fast_exp2(g0 * (-LOG2E * r))) * acc[ai][1][m][0][j];
;                     h1[j] = g1 * r2 * fast_rcp(1.0f + fast_exp2(g1 * (-LOG2E * r))) * acc[ai][1][m][1][j]; }
;                 *(u32x4*)rowp = pack8(h0, h1); }
	v_rcp_f32_e32 v44, v44
	s_nop 0
	v_mul_f32_e32 v44, v52, v44
	v_mul_f32_e32 v44, v36, v44
	v_mul_f32_e32 v36, v40, v51
	v_mul_f32_e32 v40, v40, v50
	v_exp_f32_e32 v40, v40
	s_nop 0
	v_add_f32_e32 v40, 1.0, v40
	v_rcp_f32_e32 v40, v40
	s_nop 0
	v_mul_f32_e32 v36, v36, v40
	v_mul_f32_e32 v40, v32, v36
	v_mul_f32_e32 v36, v45, v50
	v_exp_f32_e32 v36, v36
	v_mul_f32_e32 v32, v45, v51
	v_add_f32_e32 v36, 1.0, v36
	v_rcp_f32_e32 v36, v36
	s_nop 0
	v_mul_f32_e32 v32, v32, v36
	v_mul_f32_e32 v32, v37, v32
	v_mul_f32_e32 v37, v41, v50
	v_exp_f32_e32 v37, v37
	v_mul_f32_e32 v36, v41, v51
	v_cvt_pk_bf16_f32 v32, v44, v32
	v_add_f32_e32 v37, 1.0, v37
	v_rcp_f32_e32 v37, v37
	s_nop 0
	v_mul_f32_e32 v36, v36, v37
	v_mul_f32_e32 v41, v33, v36
	v_mul_f32_e32 v36, v46, v50
	v_exp_f32_e32 v36, v36
	v_mul_f32_e32 v37, v42, v50
	v_exp_f32_e32 v37, v37
	v_mul_f32_e32 v33, v46, v51
	v_add_f32_e32 v36, 1.0, v36
	v_rcp_f32_e32 v36, v36
	v_add_f32_e32 v37, 1.0, v37
	v_rcp_f32_e32 v37, v37
	v_mul_f32_e32 v33, v33, v36
	v_mul_f32_e32 v36, v42, v51
	v_mul_f32_e32 v36, v36, v37
	v_mul_f32_e32 v33, v38, v33
	v_mul_f32_e32 v38, v34, v36
	v_mul_f32_e32 v36, v47, v50
	v_exp_f32_e32 v36, v36
	v_mul_f32_e32 v37, v43, v50
	v_exp_f32_e32 v37, v37
	v_mul_f32_e32 v34, v47, v51
	v_add_f32_e32 v36, 1.0, v36
	v_rcp_f32_e32 v36, v36
	v_add_f32_e32 v37, 1.0, v37
	v_rcp_f32_e32 v37, v37
	v_mul_f32_e32 v34, v34, v36
	v_mul_f32_e32 v36, v43, v51
	v_mul_f32_e32 v36, v36, v37
	v_mul_f32_e32 v34, v39, v34
	v_mul_f32_e32 v35, v35, v36
	v_lshl_add_u64 v[36:37], v[48:49], 0, v[112:113]
	v_cvt_pk_bf16_f32 v33, v33, v34
	v_cvt_pk_bf16_f32 v34, v40, v41
	v_cvt_pk_bf16_f32 v35, v38, v35
	global_store_dwordx4 v[36:37], v[32:35], off
	s_nop 1
	v_mov_b32_e32 v34, v209
	s_nop 0
	v_add_u32_e32 v32, 0xa0, v144
	v_mad_i64_i32 v[32:33], s[42:43], v32, s49, v[146:147]
	v_mul_f32_e32 v35, v34, v34
	v_mul_f32_e32 v34, 0xbfb8aa3b, v34
	v_mul_f32_e32 v36, v28, v35
	v_mul_f32_e32 v28, v28, v34
	v_exp_f32_e32 v28, v28
	s_nop 0
	v_add_f32_e32 v28, 1.0, v28
	v_rcp_f32_e32 v28, v28
	s_nop 0
	v_mul_f32_e32 v28, v36, v28
	v_mul_f32_e32 v28, v20, v28
	v_mul_f32_e32 v20, v24, v35
	v_mul_f32_e32 v24, v24, v34
	v_exp_f32_e32 v24, v24
	s_nop 0
	v_add_f32_e32 v24, 1.0, v24
	v_rcp_f32_e32 v24, v24
	s_nop 0
	v_mul_f32_e32 v20, v20, v24
	v_mul_f32_e32 v24, v16, v20
	v_mul_f32_e32 v20, v29, v34
	v_exp_f32_e32 v20, v20
	v_mul_f32_e32 v16, v29, v35
	v_add_f32_e32 v20, 1.0, v20
	v_rcp_f32_e32 v20, v20
	s_nop 0
	v_mul_f32_e32 v16, v16, v20
	v_mul_f32_e32 v16, v21, v16
	v_mul_f32_e32 v21, v25, v34
	v_exp_f32_e32 v21, v21
	v_mul_f32_e32 v20, v25, v35
	v_cvt_pk_bf16_f32 v16, v28, v16
	v_add_f32_e32 v21, 1.0, v21
	v_rcp_f32_e32 v21, v21
	s_nop 0
	v_mul_f32_e32 v20, v20, v21
	v_mul_f32_e32 v25, v17, v20
	v_mul_f32_e32 v20, v30, v34
	v_exp_f32_e32 v20, v20
	v_mul_f32_e32 v21, v26, v34
	v_exp_f32_e32 v21, v21
	v_mul_f32_e32 v17, v30, v35
	v_add_f32_e32 v20, 1.0, v20
	v_rcp_f32_e32 v20, v20
	v_add_f32_e32 v21, 1.0, v21
	v_rcp_f32_e32 v21, v21
	v_mul_f32_e32 v17, v17, v20
	v_mul_f32_e32 v20, v26, v35
	v_mul_f32_e32 v20, v20, v21
	v_mul_f32_e32 v17, v22, v17
	v_mul_f32_e32 v22, v18, v20
	v_mul_f32_e32 v20, v31, v34
	v_exp_f32_e32 v20, v20
	v_mul_f32_e32 v21, v27, v34
	v_exp_f32_e32 v21, v21
	v_mul_f32_e32 v18, v31, v35
	v_add_f32_e32 v20, 1.0, v20
	v_rcp_f32_e32 v20, v20
	v_add_f32_e32 v21, 1.0, v21
	v_rcp_f32_e32 v21, v21
	v_mul_f32_e32 v18, v18, v20
	v_mul_f32_e32 v20, v27, v35
	v_mul_f32_e32 v20, v20, v21
	v_mul_f32_e32 v18, v23, v18
	v_mul_f32_e32 v19, v19, v20
	v_lshl_add_u64 v[20:21], v[32:33], 0, v[112:113]
	v_cvt_pk_bf16_f32 v17, v17, v18
	v_cvt_pk_bf16_f32 v18, v24, v25
	v_cvt_pk_bf16_f32 v19, v22, v19
	global_store_dwordx4 v[20:21], v[16:19], off
	s_nop 1
	v_mov_b32_e32 v18, v210
	s_nop 0
	v_add_u32_e32 v16, 0xb0, v144
	v_mad_i64_i32 v[16:17], s[42:43], v16, s49, v[146:147]
	s_mov_b64 s[42:43], s[26:27]
	v_mul_f32_e32 v19, v18, v18
	v_mul_f32_e32 v18, 0xbfb8aa3b, v18
	v_mul_f32_e32 v20, v12, v19
	v_mul_f32_e32 v12, v12, v18
	v_exp_f32_e32 v12, v12
	s_nop 0
	v_add_f32_e32 v12, 1.0, v12
	v_rcp_f32_e32 v12, v12
	s_nop 0
	v_mul_f32_e32 v12, v20, v12
	v_mul_f32_e32 v12, v4, v12
	v_mul_f32_e32 v4, v8, v19
	v_mul_f32_e32 v8, v8, v18
	v_exp_f32_e32 v8, v8
	s_nop 0
	v_add_f32_e32 v8, 1.0, v8
	v_rcp_f32_e32 v8, v8
	s_nop 0
	v_mul_f32_e32 v4, v4, v8
	v_mul_f32_e32 v8, v0, v4
	v_mul_f32_e32 v4, v13, v18
	v_exp_f32_e32 v4, v4
	v_mul_f32_e32 v0, v13, v19
	v_add_f32_e32 v4, 1.0, v4
	v_rcp_f32_e32 v4, v4
	s_nop 0
	v_mul_f32_e32 v0, v0, v4
	v_mul_f32_e32 v0, v5, v0
	v_mul_f32_e32 v5, v9, v18
	v_exp_f32_e32 v5, v5
	v_mul_f32_e32 v4, v9, v19
	v_cvt_pk_bf16_f32 v0, v12, v0
	v_add_f32_e32 v5, 1.0, v5
	v_rcp_f32_e32 v5, v5
	s_nop 0
	v_mul_f32_e32 v4, v4, v5
	v_mul_f32_e32 v9, v1, v4
	v_mul_f32_e32 v4, v14, v18
	v_exp_f32_e32 v4, v4
	v_mul_f32_e32 v5, v10, v18
	v_exp_f32_e32 v5, v5
	v_mul_f32_e32 v1, v14, v19
	v_add_f32_e32 v4, 1.0, v4
	v_rcp_f32_e32 v4, v4
	v_add_f32_e32 v5, 1.0, v5
	v_rcp_f32_e32 v5, v5
	v_mul_f32_e32 v1, v1, v4
	v_mul_f32_e32 v4, v10, v19
	v_mul_f32_e32 v4, v4, v5
	v_mul_f32_e32 v1, v6, v1
	v_mul_f32_e32 v6, v2, v4
	v_mul_f32_e32 v4, v15, v18
	v_exp_f32_e32 v4, v4
	v_mul_f32_e32 v5, v11, v18
	v_exp_f32_e32 v5, v5
	v_mul_f32_e32 v2, v15, v19
	v_add_f32_e32 v4, 1.0, v4
	v_rcp_f32_e32 v4, v4
	v_add_f32_e32 v5, 1.0, v5
	v_rcp_f32_e32 v5, v5
	v_mul_f32_e32 v2, v2, v4
	v_mul_f32_e32 v4, v11, v19
	v_mul_f32_e32 v4, v4, v5
	v_mul_f32_e32 v2, v7, v2
	v_mul_f32_e32 v3, v3, v4
	v_lshl_add_u64 v[4:5], v[16:17], 0, v[112:113]
	v_cvt_pk_bf16_f32 v1, v1, v2
	v_cvt_pk_bf16_f32 v2, v8, v9
	v_cvt_pk_bf16_f32 v3, v6, v3
	global_store_dwordx4 v[4:5], v[0:3], off
	s_cbranch_vccz .LBB0_200
	s_waitcnt vmcnt(0)
	s_cmpk_gt_u32 s3, 0xff
	s_cbranch_scc1 .LBB0_207
	s_barrier

; #define PG8_STAGE(bufoff, gbase, voff) do { _Pragma("unroll") for (int _i = 0; _i < 2; ++_i) \
;         __builtin_amdgcn_global_load_lds((const unsigned*)((const char*)(gbase) + (voff)[_i]), (LAS unsigned*)(lds + (bufoff) + ldsw + _i * 8192), 16, 0, 0); } while (0)
; #define PG8_LDA(dst, b, h) do { _Pragma("unroll") for (int m = 0; m < 4; ++m) _Pragma("unroll") for (int k = 0; k < 2; ++k) dst[m][k] = *(const LAS bf16x8*)(lds + PG8_SA(b, h) + aoff + m * 2048 + k * 1024); } while (0)
; #define PG8_LDB(dst, b, h) do { _Pragma("unroll") for (int n = 0; n < 2; ++n) _Pragma("unroll") for (int k = 0; k < 2; ++k) dst[n][k] = *(const LAS bf16x8*)(lds + PG8_SB(b, h) + boff + n * 2048 + k * 1024); } while (0)
; #define PG8_MMA(ai, bj, At, Bt) do { __builtin_amdgcn_s_setprio(1); _Pragma("unroll") for (int m = 0; m < 4; ++m) _Pragma("unroll") for (int n = 0; n < 2; ++n) _Pragma("unroll") for (int k = 0; k < 2; ++k) \
;         acc[ai][bj][m][n] = __builtin_amdgcn_mfma_f32_16x16x32_bf16(Bt[n][k], At[m][k], acc[ai][bj][m][n], 0, 0, 0); __builtin_amdgcn_s_setprio(0); } while (0)
; #define PG8_WAIT_V(n) asm volatile("s_waitcnt vmcnt(" #n ")" ::: "memory")
; #define PG8_WAIT_L(n) asm volatile("s_waitcnt lgkmcnt(" #n ")" ::: "memory")
; #define PG8_BAR __builtin_amdgcn_s_barrier()
; #define PG8_SCHED __builtin_amdgcn_sched_barrier(0)
; template <class Epi>
; __device__ __forceinline__ void gemm_phase(LAS unsigned char* lds, const Gemm g, const StaticOrder& S, const Epi& E) {
;     ...
;             const char* a1 = cA + (size_t)(t + 1) * kstep;
;             const char* a2 = last ? nA : cA + (size_t)(t + 2) * kstep; const char* b2 = last ? nB : cB + (size_t)(t + 2) * kstep;
;             const char* a3 = a2 + kstep; const char* b3 = b2 + kstep;
;             PG8_LDB(B0, 0, 0); PG8_SCHED; PG8_LDA(At, 0, 0); PG8_STAGE(PG8_SA(1, 1), a1 + hstep, voffA);
;             PG8_WAIT_L(8); PG8_BAR; PG8_WAIT_L(0); PG8_MMA(0, 0, At, B0); PG8_BAR; PG8_SCHED;
;             PG8_LDB(B1, 0, 1); PG8_STAGE(PG8_SB(0, 0), b2, voffB);
;             PG8_BAR; PG8_WAIT_L(0); PG8_MMA(0, 1, At, B1); PG8_BAR;
;             PG8_LDA(At, 0, 1); PG8_STAGE(PG8_SA(0, 0), a2, voffA);
;             PG8_BAR; PG8_WAIT_L(0); PG8_MMA(1, 0, At, B0); PG8_BAR; PG8_SCHED;
;             PG8_STAGE(PG8_SB(0, 1), b2 + hstep, voffB);
;             PG8_WAIT_V(6); PG8_BAR; PG8_MMA(1, 1, At, B1); PG8_BAR;
.LBB0_283:
	ds_read_b128 v[148:151], v145
	ds_read_b128 v[152:155], v145 offset:1024
	ds_read_b128 v[160:163], v145 offset:2048
	ds_read_b128 v[164:167], v145 offset:3072
	s_add_u32 s50, s48, 0x100
	s_addc_u32 s51, s49, 0
	s_cmpk_eq_i32 s65, 0x54
	s_cselect_b32 s55, s47, s51
	s_cselect_b32 s54, s46, s50
	s_cselect_b32 s53, s5, s64
	s_cselect_b32 s52, s4, s63
	s_add_i32 m0, s23, 0xc000
	ds_read_b128 v[168:171], v146
	ds_read_b128 v[172:175], v146 offset:1024
	ds_read_b128 v[176:179], v146 offset:2048
	ds_read_b128 v[180:183], v146 offset:3072
	ds_read_b128 v[184:187], v146 offset:4096
	ds_read_b128 v[188:191], v146 offset:5120
	ds_read_b128 v[192:195], v146 offset:6144
	ds_read_b128 v[196:199], v146 offset:7168
	global_load_lds_dwordx4 v136, s[48:49]
	s_add_i32 m0, s23, 0xe000
	s_nop 0
	global_load_lds_dwordx4 v138, s[48:49]
	s_waitcnt lgkmcnt(8)
	s_barrier
	s_waitcnt lgkmcnt(0)
	v_mfma_f32_16x16x32_bf16 v[124:127], v[148:151], v[168:171], v[124:127]
	v_mfma_f32_16x16x32_bf16 v[120:123], v[160:163], v[168:171], v[120:123]
	v_mfma_f32_16x16x32_bf16 v[112:115], v[148:151], v[176:179], v[112:115]
	v_mfma_f32_16x16x32_bf16 v[104:107], v[160:163], v[176:179], v[104:107]
	v_mfma_f32_16x16x32_bf16 v[96:99], v[148:151], v[184:187], v[96:99]
	v_mfma_f32_16x16x32_bf16 v[88:91], v[160:163], v[184:187], v[88:91]
	v_mfma_f32_16x16x32_bf16 v[80:83], v[148:151], v[192:195], v[80:83]
	v_mfma_f32_16x16x32_bf16 v[72:75], v[160:163], v[192:195], v[72:75]
	v_mfma_f32_16x16x32_bf16 v[124:127], v[152:155], v[172:175], v[124:127]
	v_mfma_f32_16x16x32_bf16 v[120:123], v[164:167], v[172:175], v[120:123]
	v_mfma_f32_16x16x32_bf16 v[112:115], v[152:155], v[180:183], v[112:115]
	v_mfma_f32_16x16x32_bf16 v[104:107], v[164:167], v[180:183], v[104:107]
	v_mfma_f32_16x16x32_bf16 v[96:99], v[152:155], v[188:191], v[96:99]
	v_mfma_f32_16x16x32_bf16 v[88:91], v[164:167], v[188:191], v[88:91]
	v_mfma_f32_16x16x32_bf16 v[80:83], v[152:155], v[196:199], v[80:83]
	v_mfma_f32_16x16x32_bf16 v[72:75], v[164:167], v[196:199], v[72:75]
	s_barrier
	s_add_i32 s48, s39, s13
	s_add_u32 s98, s52, s6
	s_addc_u32 s99, s53, s7
	s_mov_b32 m0, s48
	ds_read_b128 v[200:203], v147
	ds_read_b128 v[204:207], v147 offset:1024
	ds_read_b128 v[208:211], v147 offset:2048
	ds_read_b128 v[212:215], v147 offset:3072
	global_load_lds_dwordx4 v132, s[52:53]
	s_add_i32 m0, s48, 0x2000
	s_nop 0
	global_load_lds_dwordx4 v128, s[52:53]
	s_waitcnt lgkmcnt(0)
	s_barrier
	s_waitcnt lgkmcnt(0)
	v_mfma_f32_16x16x32_bf16 v[116:119], v[200:203], v[168:171], v[116:119]
	v_mfma_f32_16x16x32_bf16 v[108:111], v[208:211], v[168:171], v[108:111]
	v_mfma_f32_16x16x32_bf16 v[100:103], v[200:203], v[176:179], v[100:103]
	v_mfma_f32_16x16x32_bf16 v[92:95], v[208:211], v[176:179], v[92:95]
	v_mfma_f32_16x16x32_bf16 v[84:87], v[200:203], v[184:187], v[84:87]
	v_mfma_f32_16x16x32_bf16 v[76:79], v[208:211], v[184:187], v[76:79]
	v_mfma_f32_16x16x32_bf16 v[68:71], v[200:203], v[192:195], v[68:71]
	v_mfma_f32_16x16x32_bf16 v[64:67], v[208:211], v[192:195], v[64:67]
	v_mfma_f32_16x16x32_bf16 v[116:119], v[204:207], v[172:175], v[116:119]
	v_mfma_f32_16x16x32_bf16 v[108:111], v[212:215], v[172:175], v[108:111]
	v_mfma_f32_16x16x32_bf16 v[100:103], v[204:207], v[180:183], v[100:103]
	v_mfma_f32_16x16x32_bf16 v[92:95], v[212:215], v[180:183], v[92:95]
	v_mfma_f32_16x16x32_bf16 v[84:87], v[204:207], v[188:191], v[84:87]
	v_mfma_f32_16x16x32_bf16 v[76:79], v[212:215], v[188:191], v[76:79]
	v_mfma_f32_16x16x32_bf16 v[68:71], v[204:207], v[196:199], v[68:71]
	v_mfma_f32_16x16x32_bf16 v[64:67], v[212:215], v[196:199], v[64:67]
	s_mov_b32 m0, s23
	s_add_u32 s100, s54, s6
	s_addc_u32 s101, s55, s7
	s_barrier
	ds_read_b128 v[168:171], v146 offset:16384
	ds_read_b128 v[172:175], v146 offset:17408
	ds_read_b128 v[176:179], v146 offset:18432
	ds_read_b128 v[180:183], v146 offset:19456
	ds_read_b128 v[184:187], v146 offset:20480
	ds_read_b128 v[188:191], v146 offset:21504
	ds_read_b128 v[192:195], v146 offset:22528
	ds_read_b128 v[196:199], v146 offset:23552
	global_load_lds_dwordx4 v134, s[54:55]
	s_mov_b32 m0, s30
	s_nop 0
	global_load_lds_dwordx4 v130, s[54:55]
	s_add_u32 s48, s52, 0x160000
	s_addc_u32 s49, s53, 0
	s_add_i32 s66, s40, s13
	s_mov_b32 m0, s66
	s_nop 0
	global_load_lds_dwordx4 v132, s[48:49]
	s_add_i32 m0, s66, 0x2000
	s_nop 0
	global_load_lds_dwordx4 v128, s[48:49]
	s_waitcnt vmcnt(6)
	s_barrier
	s_waitcnt lgkmcnt(0)
	v_mfma_f32_16x16x32_bf16 v[60:63], v[148:151], v[168:171], v[60:63]
	v_mfma_f32_16x16x32_bf16 v[56:59], v[160:163], v[168:171], v[56:59]
	v_mfma_f32_16x16x32_bf16 v[52:55], v[148:151], v[176:179], v[52:55]
	v_mfma_f32_16x16x32_bf16 v[44:47], v[160:163], v[176:179], v[44:47]
	v_mfma_f32_16x16x32_bf16 v[36:39], v[148:151], v[184:187], v[36:39]
	v_mfma_f32_16x16x32_bf16 v[28:31], v[160:163], v[184:187], v[28:31]
	v_mfma_f32_16x16x32_bf16 v[20:23], v[148:151], v[192:195], v[20:23]
	v_mfma_f32_16x16x32_bf16 v[12:15], v[160:163], v[192:195], v[12:15]
	v_mfma_f32_16x16x32_bf16 v[60:63], v[152:155], v[172:175], v[60:63]
	v_mfma_f32_16x16x32_bf16 v[56:59], v[164:167], v[172:175], v[56:59]
	v_mfma_f32_16x16x32_bf16 v[52:55], v[152:155], v[180:183], v[52:55]
	v_mfma_f32_16x16x32_bf16 v[44:47], v[164:167], v[180:183], v[44:47]
	v_mfma_f32_16x16x32_bf16 v[36:39], v[152:155], v[188:191], v[36:39]
	v_mfma_f32_16x16x32_bf16 v[28:31], v[164:167], v[188:191], v[28:31]
	v_mfma_f32_16x16x32_bf16 v[20:23], v[152:155], v[196:199], v[20:23]
	v_mfma_f32_16x16x32_bf16 v[12:15], v[164:167], v[196:199], v[12:15]
	v_mfma_f32_16x16x32_bf16 v[48:51], v[200:203], v[168:171], v[48:51]
	v_mfma_f32_16x16x32_bf16 v[40:43], v[208:211], v[168:171], v[40:43]
	v_mfma_f32_16x16x32_bf16 v[32:35], v[200:203], v[176:179], v[32:35]
	v_mfma_f32_16x16x32_bf16 v[24:27], v[208:211], v[176:179], v[24:27]
	v_mfma_f32_16x16x32_bf16 v[16:19], v[200:203], v[184:187], v[16:19]
	v_mfma_f32_16x16x32_bf16 v[8:11], v[208:211], v[184:187], v[8:11]
	v_mfma_f32_16x16x32_bf16 v[4:7], v[200:203], v[192:195], v[4:7]
	v_mfma_f32_16x16x32_bf16 v[0:3], v[208:211], v[192:195], v[0:3]
	v_mfma_f32_16x16x32_bf16 v[48:51], v[204:207], v[172:175], v[48:51]
	v_mfma_f32_16x16x32_bf16 v[40:43], v[212:215], v[172:175], v[40:43]
	v_mfma_f32_16x16x32_bf16 v[32:35], v[204:207], v[180:183], v[32:35]
	v_mfma_f32_16x16x32_bf16 v[24:27], v[212:215], v[180:183], v[24:27]
	v_mfma_f32_16x16x32_bf16 v[16:19], v[204:207], v[188:191], v[16:19]
	v_mfma_f32_16x16x32_bf16 v[8:11], v[212:215], v[188:191], v[8:11]
	v_mfma_f32_16x16x32_bf16 v[4:7], v[204:207], v[196:199], v[4:7]
	v_mfma_f32_16x16x32_bf16 v[0:3], v[212:215], v[196:199], v[0:3]
	s_add_i32 s66, 0, 0x18000
	v_add_u32_e32 v164, s66, v143
	s_barrier
; #define PG8_STAGE(bufoff, gbase, voff) do { _Pragma("unroll") for (int _i = 0; _i < 2; ++_i) \
;         __builtin_amdgcn_global_load_lds((const unsigned*)((const char*)(gbase) + (voff)[_i]), (LAS unsigned*)(lds + (bufoff) + ldsw + _i * 8192), 16, 0, 0); } while (0)
; #define PG8_LDA(dst, b, h) do { _Pragma("unroll") for (int m = 0; m < 4; ++m) _Pragma("unroll") for (int k = 0; k < 2; ++k) dst[m][k] = *(const LAS bf16x8*)(lds + PG8_SA(b, h) + aoff + m * 2048 + k * 1024); } while (0)
; #define PG8_LDB(dst, b, h) do { _Pragma("unroll") for (int n = 0; n < 2; ++n) _Pragma("unroll") for (int k = 0; k < 2; ++k) dst[n][k] = *(const LAS bf16x8*)(lds + PG8_SB(b, h) + boff + n * 2048 + k * 1024); } while (0)
; #define PG8_MMA(ai, bj, At, Bt) do { __builtin_amdgcn_s_setprio(1); _Pragma("unroll") for (int m = 0; m < 4; ++m) _Pragma("unroll") for (int n = 0; n < 2; ++n) _Pragma("unroll") for (int k = 0; k < 2; ++k) \
;         acc[ai][bj][m][n] = __builtin_amdgcn_mfma_f32_16x16x32_bf16(Bt[n][k], At[m][k], acc[ai][bj][m][n], 0, 0, 0); __builtin_amdgcn_s_setprio(0); } while (0)
; #define PG8_WAIT_V(n) asm volatile("s_waitcnt vmcnt(" #n ")" ::: "memory")
; #define PG8_WAIT_L(n) asm volatile("s_waitcnt lgkmcnt(" #n ")" ::: "memory")
; #define PG8_BAR __builtin_amdgcn_s_barrier()
; #define PG8_SCHED __builtin_amdgcn_sched_barrier(0)
; template <class Epi>
; __device__ __forceinline__ void gemm_phase(LAS unsigned char* lds, const Gemm g, const StaticOrder& S, const Epi& E) {
;     ...
;             PG8_LDB(B0, 1, 0); PG8_SCHED; PG8_LDA(At, 1, 0); PG8_STAGE(PG8_SA(0, 1), a2 + hstep, voffA);
;             PG8_WAIT_L(8); PG8_BAR; PG8_WAIT_L(0); PG8_MMA(0, 0, At, B0); PG8_BAR; PG8_SCHED;
;             PG8_LDB(B1, 1, 1); PG8_STAGE(PG8_SB(1, 0), b3, voffB);
;             PG8_BAR; PG8_WAIT_L(0); PG8_MMA(0, 1, At, B1); PG8_BAR;
;             PG8_LDA(At, 1, 1); PG8_STAGE(PG8_SA(1, 0), a3, voffA);
;             PG8_BAR; PG8_WAIT_L(0); PG8_MMA(1, 0, At, B0); PG8_BAR; PG8_SCHED;
;             PG8_STAGE(PG8_SB(1, 1), b3 + hstep, voffB);
;             PG8_WAIT_V(6); PG8_BAR; PG8_MMA(1, 1, At, B1); PG8_BAR;
;         }
	ds_read_b128 v[148:151], v164
	ds_read_b128 v[152:155], v164 offset:1024
	ds_read_b128 v[160:163], v164 offset:2048
	ds_read_b128 v[164:167], v164 offset:3072
	s_add_u32 s48, s54, 0x160000
	s_addc_u32 s49, s55, 0
	s_mov_b32 m0, s31
	ds_read_b128 v[168:171], v146 offset:32768
	ds_read_b128 v[172:175], v146 offset:33792
	ds_read_b128 v[176:179], v146 offset:34816
	ds_read_b128 v[180:183], v146 offset:35840
	ds_read_b128 v[184:187], v146 offset:36864
	ds_read_b128 v[188:191], v146 offset:37888
	ds_read_b128 v[192:195], v146 offset:38912
	ds_read_b128 v[196:199], v146 offset:39936
	global_load_lds_dwordx4 v134, s[48:49]
	s_mov_b32 m0, s33
	s_nop 0
	global_load_lds_dwordx4 v130, s[48:49]
	s_waitcnt lgkmcnt(8)
	s_barrier
	s_waitcnt lgkmcnt(0)
	v_mfma_f32_16x16x32_bf16 v[124:127], v[148:151], v[168:171], v[124:127]
	v_mfma_f32_16x16x32_bf16 v[120:123], v[160:163], v[168:171], v[120:123]
	v_mfma_f32_16x16x32_bf16 v[112:115], v[148:151], v[176:179], v[112:115]
	v_mfma_f32_16x16x32_bf16 v[104:107], v[160:163], v[176:179], v[104:107]
	v_mfma_f32_16x16x32_bf16 v[96:99], v[148:151], v[184:187], v[96:99]
	v_mfma_f32_16x16x32_bf16 v[88:91], v[160:163], v[184:187], v[88:91]
	v_mfma_f32_16x16x32_bf16 v[80:83], v[148:151], v[192:195], v[80:83]
	v_mfma_f32_16x16x32_bf16 v[72:75], v[160:163], v[192:195], v[72:75]
	v_mfma_f32_16x16x32_bf16 v[124:127], v[152:155], v[172:175], v[124:127]
	v_mfma_f32_16x16x32_bf16 v[120:123], v[164:167], v[172:175], v[120:123]
	v_mfma_f32_16x16x32_bf16 v[112:115], v[152:155], v[180:183], v[112:115]
	v_mfma_f32_16x16x32_bf16 v[104:107], v[164:167], v[180:183], v[104:107]
	v_mfma_f32_16x16x32_bf16 v[96:99], v[152:155], v[188:191], v[96:99]
	v_mfma_f32_16x16x32_bf16 v[88:91], v[164:167], v[188:191], v[88:91]
	v_mfma_f32_16x16x32_bf16 v[80:83], v[152:155], v[196:199], v[80:83]
	v_mfma_f32_16x16x32_bf16 v[72:75], v[164:167], v[196:199], v[72:75]
	s_barrier
	s_add_i32 s54, 0, 0x1c000
	s_add_i32 s48, s66, s13
	v_add_u32_e32 v212, s54, v143
	s_mov_b32 m0, s48
	ds_read_b128 v[200:203], v212
	ds_read_b128 v[204:207], v212 offset:1024
	ds_read_b128 v[208:211], v212 offset:2048
	ds_read_b128 v[212:215], v212 offset:3072
	global_load_lds_dwordx4 v132, s[98:99]
	s_add_i32 m0, s48, 0x2000
	s_nop 0
	global_load_lds_dwordx4 v128, s[98:99]
	s_waitcnt lgkmcnt(0)
	s_barrier
	s_waitcnt lgkmcnt(0)
	v_mfma_f32_16x16x32_bf16 v[116:119], v[200:203], v[168:171], v[116:119]
	v_mfma_f32_16x16x32_bf16 v[108:111], v[208:211], v[168:171], v[108:111]
	v_mfma_f32_16x16x32_bf16 v[100:103], v[200:203], v[176:179], v[100:103]
	v_mfma_f32_16x16x32_bf16 v[92:95], v[208:211], v[176:179], v[92:95]
	v_mfma_f32_16x16x32_bf16 v[84:87], v[200:203], v[184:187], v[84:87]
	v_mfma_f32_16x16x32_bf16 v[76:79], v[208:211], v[184:187], v[76:79]
	v_mfma_f32_16x16x32_bf16 v[68:71], v[200:203], v[192:195], v[68:71]
	v_mfma_f32_16x16x32_bf16 v[64:67], v[208:211], v[192:195], v[64:67]
	v_mfma_f32_16x16x32_bf16 v[116:119], v[204:207], v[172:175], v[116:119]
	v_mfma_f32_16x16x32_bf16 v[108:111], v[212:215], v[172:175], v[108:111]
	v_mfma_f32_16x16x32_bf16 v[100:103], v[204:207], v[180:183], v[100:103]
	v_mfma_f32_16x16x32_bf16 v[92:95], v[212:215], v[180:183], v[92:95]
	v_mfma_f32_16x16x32_bf16 v[84:87], v[204:207], v[188:191], v[84:87]
	v_mfma_f32_16x16x32_bf16 v[76:79], v[212:215], v[188:191], v[76:79]
	v_mfma_f32_16x16x32_bf16 v[68:71], v[204:207], v[196:199], v[68:71]
	v_mfma_f32_16x16x32_bf16 v[64:67], v[212:215], v[196:199], v[64:67]
	s_mov_b32 m0, s34
	s_barrier
	ds_read_b128 v[168:171], v146 offset:49152
	ds_read_b128 v[172:175], v146 offset:50176
	ds_read_b128 v[176:179], v146 offset:51200
	ds_read_b128 v[180:183], v146 offset:52224
	ds_read_b128 v[184:187], v146 offset:53248
	ds_read_b128 v[188:191], v146 offset:54272
	ds_read_b128 v[192:195], v146 offset:55296
	ds_read_b128 v[196:199], v146 offset:56320
	global_load_lds_dwordx4 v134, s[100:101]
	s_mov_b32 m0, s36
	s_nop 0
	global_load_lds_dwordx4 v130, s[100:101]
	s_add_u32 s48, s52, 0x160080
	s_addc_u32 s49, s53, 0
	s_add_i32 s52, s54, s13
	s_mov_b32 m0, s52
	s_nop 0
	global_load_lds_dwordx4 v132, s[48:49]
	s_add_i32 m0, s52, 0x2000
	s_nop 0
	global_load_lds_dwordx4 v128, s[48:49]
	s_waitcnt vmcnt(6)
	s_barrier
	s_waitcnt lgkmcnt(0)
	v_mfma_f32_16x16x32_bf16 v[60:63], v[148:151], v[168:171], v[60:63]
	v_mfma_f32_16x16x32_bf16 v[56:59], v[160:163], v[168:171], v[56:59]
	v_mfma_f32_16x16x32_bf16 v[52:55], v[148:151], v[176:179], v[52:55]
	v_mfma_f32_16x16x32_bf16 v[44:47], v[160:163], v[176:179], v[44:47]
	v_mfma_f32_16x16x32_bf16 v[36:39], v[148:151], v[184:187], v[36:39]
	v_mfma_f32_16x16x32_bf16 v[28:31], v[160:163], v[184:187], v[28:31]
	v_mfma_f32_16x16x32_bf16 v[20:23], v[148:151], v[192:195], v[20:23]
	v_mfma_f32_16x16x32_bf16 v[12:15], v[160:163], v[192:195], v[12:15]
	v_mfma_f32_16x16x32_bf16 v[60:63], v[152:155], v[172:175], v[60:63]
	v_mfma_f32_16x16x32_bf16 v[56:59], v[164:167], v[172:175], v[56:59]
	v_mfma_f32_16x16x32_bf16 v[52:55], v[152:155], v[180:183], v[52:55]
	v_mfma_f32_16x16x32_bf16 v[44:47], v[164:167], v[180:183], v[44:47]
	v_mfma_f32_16x16x32_bf16 v[36:39], v[152:155], v[188:191], v[36:39]
	v_mfma_f32_16x16x32_bf16 v[28:31], v[164:167], v[188:191], v[28:31]
	v_mfma_f32_16x16x32_bf16 v[20:23], v[152:155], v[196:199], v[20:23]
	v_mfma_f32_16x16x32_bf16 v[12:15], v[164:167], v[196:199], v[12:15]
	v_mfma_f32_16x16x32_bf16 v[48:51], v[200:203], v[168:171], v[48:51]
	v_mfma_f32_16x16x32_bf16 v[40:43], v[208:211], v[168:171], v[40:43]
	v_mfma_f32_16x16x32_bf16 v[32:35], v[200:203], v[176:179], v[32:35]
	v_mfma_f32_16x16x32_bf16 v[24:27], v[208:211], v[176:179], v[24:27]
	v_mfma_f32_16x16x32_bf16 v[16:19], v[200:203], v[184:187], v[16:19]
	v_mfma_f32_16x16x32_bf16 v[8:11], v[208:211], v[184:187], v[8:11]
	v_mfma_f32_16x16x32_bf16 v[4:7], v[200:203], v[192:195], v[4:7]
	v_mfma_f32_16x16x32_bf16 v[0:3], v[208:211], v[192:195], v[0:3]
	v_mfma_f32_16x16x32_bf16 v[48:51], v[204:207], v[172:175], v[48:51]
	v_mfma_f32_16x16x32_bf16 v[40:43], v[212:215], v[172:175], v[40:43]
	v_mfma_f32_16x16x32_bf16 v[32:35], v[204:207], v[180:183], v[32:35]
	v_mfma_f32_16x16x32_bf16 v[24:27], v[212:215], v[180:183], v[24:27]
	v_mfma_f32_16x16x32_bf16 v[16:19], v[204:207], v[188:191], v[16:19]
	v_mfma_f32_16x16x32_bf16 v[8:11], v[212:215], v[188:191], v[8:11]
	v_mfma_f32_16x16x32_bf16 v[4:7], v[204:207], v[196:199], v[4:7]
	v_mfma_f32_16x16x32_bf16 v[0:3], v[212:215], v[196:199], v[0:3]
	s_add_i32 s65, s65, 2
	s_add_u32 s63, s63, 0x100
	s_addc_u32 s64, s64, 0
	s_cmpk_gt_u32 s65, 0x55
	s_mov_b64 s[48:49], s[50:51]
	s_barrier
; #define PG8_WAIT_V(n) asm volatile("s_waitcnt vmcnt(" #n ")" ::: "memory")
; #define PG8_BAR __builtin_amdgcn_s_barrier()
; __device__ __forceinline__ u32x4 pack8(f32x4 v0, f32x4 v1) { u32x4 w; w.x = cvt_pk_bf16(v0[0], v0[1]); w.y = cvt_pk_bf16(v0[2], v0[3]); w.z = cvt_pk_bf16(v1[0], v1[1]); w.w = cvt_pk_bf16(v1[2], v1[3]); return w; }
; template <class Epi>
; __device__ __forceinline__ void gemm_phase(LAS unsigned char* lds, const Gemm g, const StaticOrder& S, const Epi& E) {
;     ...
;         E(acc, cur, wr, wc, fr, fq);
;         if (!has_next) break;
; #pragma unroll
;         for (int a = 0; a < 2; ++a)
; #pragma unroll
;             for (int b = 0; b < 2; ++b)
; #pragma unroll
;                 for (int m = 0; m < 4; ++m)
; #pragma unroll
;                     for (int n = 0; n < 2; ++n) acc[a][b][m][n] = (f32x4){0.f, 0.f, 0.f, 0.f};
;         cur = nxt; cA = nA; cB = nB; ++ui;
;     }
;     PG8_WAIT_V(0);
;     if (wr == 0) PG8_BAR;
;     PG8_BAR;
;     __device__ __forceinline__ void operator()(const f32x4 (&acc)[2][2][4][2], const Unit& u, int wr, int wc, int fr, int fq) const {
;         const int row0 = u.pm * BM + wr * 64 + fr, col0 = u.pn * BM + wc * 32 + 8 * fq;
; #pragma unroll
;         for (int ai = 0; ai < 2; ++ai)
; #pragma unroll
;             for (int m = 0; m < 4; ++m) { bf16_t* rowp = O + (size_t)(row0 + ai * HALF + m * 16) * ldc + col0;
; #pragma unroll
;                 for (int bj = 0; bj < 2; ++bj) *(u32x4*)(rowp + bj * HALF) = pack8(acc[ai][bj][m][0], acc[ai][bj][m][1]); }
;     }
	s_cbranch_scc0 .LBB0_283
	v_lshl_add_u32 v148, s61, 8, v142
	v_lshl_or_b32 v140, s62, 8, v144
	v_ashrrev_i32_e32 v149, 31, v148
	v_ashrrev_i32_e32 v141, 31, v140
	v_lshlrev_b64 v[150:151], 12, v[148:149]
	v_lshl_add_u64 v[150:151], s[24:25], 0, v[150:151]
	v_lshlrev_b64 v[152:153], 1, v[140:141]
	v_lshl_add_u64 v[140:141], v[150:151], 0, v[152:153]
	v_cvt_pk_bf16_f32 v124, v124, v125
	v_cvt_pk_bf16_f32 v125, v126, v127
	v_cvt_pk_bf16_f32 v126, v120, v121
	v_cvt_pk_bf16_f32 v127, v122, v123
	global_store_dwordx4 v[140:141], v[124:127], off
	v_cvt_pk_bf16_f32 v116, v116, v117
	v_cvt_pk_bf16_f32 v117, v118, v119
	v_cvt_pk_bf16_f32 v118, v108, v109
	v_or_b32_e32 v108, 16, v148
	v_ashrrev_i32_e32 v109, 31, v108
	v_lshlrev_b64 v[108:109], 12, v[108:109]
	v_lshl_add_u64 v[108:109], s[24:25], 0, v[108:109]
	v_cvt_pk_bf16_f32 v119, v110, v111
	global_store_dwordx4 v[140:141], v[116:119], off offset:256
	s_mov_b32 s62, s59
	s_mov_b32 s61, s60
	v_lshl_add_u64 v[116:117], v[108:109], 0, v[152:153]
	v_cvt_pk_bf16_f32 v108, v112, v113
	v_cvt_pk_bf16_f32 v109, v114, v115
	v_cvt_pk_bf16_f32 v110, v104, v105
	v_cvt_pk_bf16_f32 v111, v106, v107
	global_store_dwordx4 v[116:117], v[108:111], off
	v_cvt_pk_bf16_f32 v100, v100, v101
	v_cvt_pk_bf16_f32 v101, v102, v103
	v_cvt_pk_bf16_f32 v102, v92, v93
	v_or_b32_e32 v92, 32, v148
	v_ashrrev_i32_e32 v93, 31, v92
	v_lshlrev_b64 v[92:93], 12, v[92:93]
	v_lshl_add_u64 v[92:93], s[24:25], 0, v[92:93]
	v_cvt_pk_bf16_f32 v103, v94, v95
	global_store_dwordx4 v[116:117], v[100:103], off offset:256
	s_mov_b64 s[50:51], s[4:5]
	s_mov_b64 s[48:49], s[46:47]
	v_lshl_add_u64 v[100:101], v[92:93], 0, v[152:153]
	v_cvt_pk_bf16_f32 v92, v96, v97
	v_cvt_pk_bf16_f32 v93, v98, v99
	v_cvt_pk_bf16_f32 v94, v88, v89
	v_cvt_pk_bf16_f32 v95, v90, v91
	global_store_dwordx4 v[100:101], v[92:95], off
	v_cvt_pk_bf16_f32 v84, v84, v85
	v_cvt_pk_bf16_f32 v85, v86, v87
	v_cvt_pk_bf16_f32 v86, v76, v77
	v_or_b32_e32 v76, 48, v148
	v_ashrrev_i32_e32 v77, 31, v76
	v_lshlrev_b64 v[76:77], 12, v[76:77]
	v_lshl_add_u64 v[76:77], s[24:25], 0, v[76:77]
	v_cvt_pk_bf16_f32 v87, v78, v79
	global_store_dwordx4 v[100:101], v[84:87], off offset:256
	s_nop 1
	v_lshl_add_u64 v[84:85], v[76:77], 0, v[152:153]
	v_cvt_pk_bf16_f32 v76, v80, v81
	v_cvt_pk_bf16_f32 v77, v82, v83
	v_cvt_pk_bf16_f32 v78, v72, v73
	v_cvt_pk_bf16_f32 v79, v74, v75
	global_store_dwordx4 v[84:85], v[76:79], off
	v_cvt_pk_bf16_f32 v68, v68, v69
	v_cvt_pk_bf16_f32 v69, v70, v71
	v_cvt_pk_bf16_f32 v70, v64, v65
	v_cvt_pk_bf16_f32 v71, v66, v67
	global_store_dwordx4 v[84:85], v[68:71], off offset:256
	v_cvt_pk_bf16_f32 v60, v60, v61
	v_cvt_pk_bf16_f32 v61, v62, v63
	v_cvt_pk_bf16_f32 v62, v56, v57
	v_add_co_u32_e32 v56, vcc, s41, v140
	v_lshl_add_u64 v[64:65], v[140:141], 0, s[8:9]
	s_nop 0
	v_addc_co_u32_e32 v57, vcc, 0, v141, vcc
	v_cvt_pk_bf16_f32 v63, v58, v59
	global_store_dwordx4 v[56:57], v[60:63], off
	v_cvt_pk_bf16_f32 v48, v48, v49
	v_cvt_pk_bf16_f32 v49, v50, v51
	v_cvt_pk_bf16_f32 v50, v40, v41
	v_cvt_pk_bf16_f32 v51, v42, v43
	global_store_dwordx4 v[64:65], v[48:51], off offset:256
	v_cvt_pk_bf16_f32 v40, v52, v53
	v_cvt_pk_bf16_f32 v41, v54, v55
	v_cvt_pk_bf16_f32 v42, v44, v45
	v_add_co_u32_e32 v44, vcc, s56, v140
	s_nop 0
	v_lshl_add_u64 v[48:49], v[140:141], 0, s[26:27]
	v_addc_co_u32_e32 v45, vcc, 0, v141, vcc
	v_cvt_pk_bf16_f32 v43, v46, v47
	global_store_dwordx4 v[44:45], v[40:43], off
	v_cvt_pk_bf16_f32 v32, v32, v33
	v_cvt_pk_bf16_f32 v33, v34, v35
	v_cvt_pk_bf16_f32 v34, v24, v25
	v_cvt_pk_bf16_f32 v35, v26, v27
	global_store_dwordx4 v[48:49], v[32:35], off offset:256
	v_cvt_pk_bf16_f32 v24, v36, v37
	v_cvt_pk_bf16_f32 v25, v38, v39
	v_cvt_pk_bf16_f32 v26, v28, v29
	v_add_co_u32_e32 v28, vcc, s57, v140
	s_nop 0
	v_lshl_add_u64 v[32:33], v[140:141], 0, s[28:29]
	v_addc_co_u32_e32 v29, vcc, 0, v141, vcc
	v_cvt_pk_bf16_f32 v27, v30, v31
	global_store_dwordx4 v[28:29], v[24:27], off
	v_cvt_pk_bf16_f32 v16, v16, v17
	v_cvt_pk_bf16_f32 v17, v18, v19
	v_cvt_pk_bf16_f32 v18, v8, v9
	v_cvt_pk_bf16_f32 v19, v10, v11
	global_store_dwordx4 v[32:33], v[16:19], off offset:256
	v_cvt_pk_bf16_f32 v8, v20, v21
	v_cvt_pk_bf16_f32 v9, v22, v23
	v_cvt_pk_bf16_f32 v10, v12, v13
	v_add_co_u32_e32 v12, vcc, s58, v140
	s_nop 0
	v_lshl_add_u64 v[16:17], v[140:141], 0, s[42:43]
	v_addc_co_u32_e32 v13, vcc, 0, v141, vcc
	s_and_b64 vcc, exec, s[44:45]
	v_cvt_pk_bf16_f32 v11, v14, v15
	global_store_dwordx4 v[12:13], v[8:11], off
	v_cvt_pk_bf16_f32 v4, v4, v5
	v_cvt_pk_bf16_f32 v5, v6, v7
	v_cvt_pk_bf16_f32 v6, v0, v1
	v_cvt_pk_bf16_f32 v7, v2, v3
	global_store_dwordx4 v[16:17], v[4:7], off offset:256
	s_cbranch_vccz .LBB0_276
	s_waitcnt vmcnt(0)
	s_cmpk_gt_u32 s3, 0xff
	v_readlane_b32 s62, v232, 20
	s_cbranch_scc1 .LBB0_287
	s_barrier

; #define PG8_STAGE(bufoff, gbase, voff) do { _Pragma("unroll") for (int _i = 0; _i < 2; ++_i) \
;         __builtin_amdgcn_global_load_lds((const unsigned*)((const char*)(gbase) + (voff)[_i]), (LAS unsigned*)(lds + (bufoff) + ldsw + _i * 8192), 16, 0, 0); } while (0)
; #define PG8_LDA(dst, b, h) do { _Pragma("unroll") for (int m = 0; m < 4; ++m) _Pragma("unroll") for (int k = 0; k < 2; ++k) dst[m][k] = *(const LAS bf16x8*)(lds + PG8_SA(b, h) + aoff + m * 2048 + k * 1024); } while (0)
; #define PG8_LDB(dst, b, h) do { _Pragma("unroll") for (int n = 0; n < 2; ++n) _Pragma("unroll") for (int k = 0; k < 2; ++k) dst[n][k] = *(const LAS bf16x8*)(lds + PG8_SB(b, h) + boff + n * 2048 + k * 1024); } while (0)
; #define PG8_MMA(ai, bj, At, Bt) do { __builtin_amdgcn_s_setprio(1); _Pragma("unroll") for (int m = 0; m < 4; ++m) _Pragma("unroll") for (int n = 0; n < 2; ++n) _Pragma("unroll") for (int k = 0; k < 2; ++k) \
;         acc[ai][bj][m][n] = __builtin_amdgcn_mfma_f32_16x16x32_bf16(Bt[n][k], At[m][k], acc[ai][bj][m][n], 0, 0, 0); __builtin_amdgcn_s_setprio(0); } while (0)
; #define PG8_WAIT_V(n) asm volatile("s_waitcnt vmcnt(" #n ")" ::: "memory")
; #define PG8_WAIT_L(n) asm volatile("s_waitcnt lgkmcnt(" #n ")" ::: "memory")
; #define PG8_BAR __builtin_amdgcn_s_barrier()
; #define PG8_SCHED __builtin_amdgcn_sched_barrier(0)
; template <class Epi>
; __device__ __forceinline__ void gemm_phase(LAS unsigned char* lds, const Gemm g, const StaticOrder& S, const Epi& E) {
;     ...
;             const char* a1 = cA + (size_t)(t + 1) * kstep;
;             const char* a2 = last ? nA : cA + (size_t)(t + 2) * kstep; const char* b2 = last ? nB : cB + (size_t)(t + 2) * kstep;
;             const char* a3 = a2 + kstep; const char* b3 = b2 + kstep;
;             PG8_LDB(B0, 0, 0); PG8_SCHED; PG8_LDA(At, 0, 0); PG8_STAGE(PG8_SA(1, 1), a1 + hstep, voffA);
;             PG8_WAIT_L(8); PG8_BAR; PG8_WAIT_L(0); PG8_MMA(0, 0, At, B0); PG8_BAR; PG8_SCHED;
;             PG8_LDB(B1, 0, 1); PG8_STAGE(PG8_SB(0, 0), b2, voffB);
;             PG8_BAR; PG8_WAIT_L(0); PG8_MMA(0, 1, At, B1); PG8_BAR;
;             PG8_LDA(At, 0, 1); PG8_STAGE(PG8_SA(0, 0), a2, voffA);
;             PG8_BAR; PG8_WAIT_L(0); PG8_MMA(1, 0, At, B0); PG8_BAR; PG8_SCHED;
;             PG8_STAGE(PG8_SB(0, 1), b2 + hstep, voffB);
;             PG8_WAIT_V(6); PG8_BAR; PG8_MMA(1, 1, At, B1); PG8_BAR;
.LBB0_407:
	ds_read_b128 v[150:153], v164
	ds_read_b128 v[154:157], v164 offset:1024
	ds_read_b128 v[168:171], v164 offset:2048
	ds_read_b128 v[172:175], v164 offset:3072
	s_add_u32 s48, s46, 0xfff80080
	s_addc_u32 s49, s47, -1
	s_cmp_eq_u32 s57, 28
	s_cselect_b32 s51, s9, s49
	s_cselect_b32 s50, s45, s48
	s_cselect_b32 s49, s7, s56
	s_cselect_b32 s48, s54, s55
	s_add_i32 m0, s27, 0xc000
	ds_read_b128 v[176:179], v165
	ds_read_b128 v[180:183], v165 offset:1024
	ds_read_b128 v[184:187], v165 offset:2048
	ds_read_b128 v[188:191], v165 offset:3072
	ds_read_b128 v[192:195], v165 offset:4096
	ds_read_b128 v[196:199], v165 offset:5120
	ds_read_b128 v[200:203], v165 offset:6144
	ds_read_b128 v[204:207], v165 offset:7168
	global_load_lds_dwordx4 v142, s[46:47]
	s_add_i32 m0, s27, 0xe000
	s_nop 0
	global_load_lds_dwordx4 v144, s[46:47]
	s_waitcnt lgkmcnt(8)
	s_barrier
	s_waitcnt lgkmcnt(0)
	v_mfma_f32_16x16x32_bf16 v[124:127], v[150:153], v[176:179], v[124:127]
	v_mfma_f32_16x16x32_bf16 v[120:123], v[168:171], v[176:179], v[120:123]
	v_mfma_f32_16x16x32_bf16 v[108:111], v[150:153], v[184:187], v[108:111]
	v_mfma_f32_16x16x32_bf16 v[104:107], v[168:171], v[184:187], v[104:107]
	v_mfma_f32_16x16x32_bf16 v[92:95], v[150:153], v[192:195], v[92:95]
	v_mfma_f32_16x16x32_bf16 v[88:91], v[168:171], v[192:195], v[88:91]
	v_mfma_f32_16x16x32_bf16 v[76:79], v[150:153], v[200:203], v[76:79]
	v_mfma_f32_16x16x32_bf16 v[72:75], v[168:171], v[200:203], v[72:75]
	v_mfma_f32_16x16x32_bf16 v[124:127], v[154:157], v[180:183], v[124:127]
	v_mfma_f32_16x16x32_bf16 v[120:123], v[172:175], v[180:183], v[120:123]
	v_mfma_f32_16x16x32_bf16 v[108:111], v[154:157], v[188:191], v[108:111]
	v_mfma_f32_16x16x32_bf16 v[104:107], v[172:175], v[188:191], v[104:107]
	v_mfma_f32_16x16x32_bf16 v[92:95], v[154:157], v[196:199], v[92:95]
	v_mfma_f32_16x16x32_bf16 v[88:91], v[172:175], v[196:199], v[88:91]
	v_mfma_f32_16x16x32_bf16 v[76:79], v[154:157], v[204:207], v[76:79]
	v_mfma_f32_16x16x32_bf16 v[72:75], v[172:175], v[204:207], v[72:75]
	s_barrier
	s_add_i32 s58, s41, s23
	s_add_u32 s98, s48, s2
	s_addc_u32 s99, s49, s3
	s_mov_b32 m0, s58
	ds_read_b128 v[208:211], v166
	ds_read_b128 v[212:215], v166 offset:1024
	ds_read_b128 v[216:219], v166 offset:2048
	ds_read_b128 v[220:223], v166 offset:3072
	global_load_lds_dwordx4 v132, s[48:49]
	s_add_i32 m0, s58, 0x2000
	s_nop 0
	global_load_lds_dwordx4 v128, s[48:49]
	s_waitcnt lgkmcnt(0)
	s_barrier
	s_waitcnt lgkmcnt(0)
	v_mfma_f32_16x16x32_bf16 v[116:119], v[208:211], v[176:179], v[116:119]
	v_mfma_f32_16x16x32_bf16 v[112:115], v[216:219], v[176:179], v[112:115]
	v_mfma_f32_16x16x32_bf16 v[100:103], v[208:211], v[184:187], v[100:103]
	v_mfma_f32_16x16x32_bf16 v[96:99], v[216:219], v[184:187], v[96:99]
	v_mfma_f32_16x16x32_bf16 v[84:87], v[208:211], v[192:195], v[84:87]
	v_mfma_f32_16x16x32_bf16 v[80:83], v[216:219], v[192:195], v[80:83]
	v_mfma_f32_16x16x32_bf16 v[68:71], v[208:211], v[200:203], v[68:71]
	v_mfma_f32_16x16x32_bf16 v[64:67], v[216:219], v[200:203], v[64:67]
	v_mfma_f32_16x16x32_bf16 v[116:119], v[212:215], v[180:183], v[116:119]
	v_mfma_f32_16x16x32_bf16 v[112:115], v[220:223], v[180:183], v[112:115]
	v_mfma_f32_16x16x32_bf16 v[100:103], v[212:215], v[188:191], v[100:103]
	v_mfma_f32_16x16x32_bf16 v[96:99], v[220:223], v[188:191], v[96:99]
	v_mfma_f32_16x16x32_bf16 v[84:87], v[212:215], v[196:199], v[84:87]
	v_mfma_f32_16x16x32_bf16 v[80:83], v[220:223], v[196:199], v[80:83]
	v_mfma_f32_16x16x32_bf16 v[68:71], v[212:215], v[204:207], v[68:71]
	v_mfma_f32_16x16x32_bf16 v[64:67], v[220:223], v[204:207], v[64:67]
	s_mov_b32 m0, s27
	s_add_u32 s100, s50, s2
	s_addc_u32 s101, s51, s3
	s_barrier
	ds_read_b128 v[176:179], v165 offset:16384
	ds_read_b128 v[180:183], v165 offset:17408
	ds_read_b128 v[184:187], v165 offset:18432
	ds_read_b128 v[188:191], v165 offset:19456
	ds_read_b128 v[192:195], v165 offset:20480
	ds_read_b128 v[196:199], v165 offset:21504
	ds_read_b128 v[200:203], v165 offset:22528
	ds_read_b128 v[204:207], v165 offset:23552
	global_load_lds_dwordx4 v134, s[50:51]
	s_mov_b32 m0, s30
	s_nop 0
	global_load_lds_dwordx4 v130, s[50:51]
	s_add_u32 s58, s48, 0x80000
	s_addc_u32 s59, s49, 0
	s_add_i32 s60, s52, s23
	s_mov_b32 m0, s60
	s_nop 0
	global_load_lds_dwordx4 v132, s[58:59]
	s_add_i32 m0, s60, 0x2000
	s_nop 0
	global_load_lds_dwordx4 v128, s[58:59]
	s_waitcnt vmcnt(6)
	s_barrier
	s_waitcnt lgkmcnt(0)
	v_mfma_f32_16x16x32_bf16 v[60:63], v[150:153], v[176:179], v[60:63]
	v_mfma_f32_16x16x32_bf16 v[56:59], v[168:171], v[176:179], v[56:59]
	v_mfma_f32_16x16x32_bf16 v[44:47], v[150:153], v[184:187], v[44:47]
	v_mfma_f32_16x16x32_bf16 v[40:43], v[168:171], v[184:187], v[40:43]
	v_mfma_f32_16x16x32_bf16 v[28:31], v[150:153], v[192:195], v[28:31]
	v_mfma_f32_16x16x32_bf16 v[24:27], v[168:171], v[192:195], v[24:27]
	v_mfma_f32_16x16x32_bf16 v[12:15], v[150:153], v[200:203], v[12:15]
	v_mfma_f32_16x16x32_bf16 v[8:11], v[168:171], v[200:203], v[8:11]
	v_mfma_f32_16x16x32_bf16 v[60:63], v[154:157], v[180:183], v[60:63]
	v_mfma_f32_16x16x32_bf16 v[56:59], v[172:175], v[180:183], v[56:59]
	v_mfma_f32_16x16x32_bf16 v[44:47], v[154:157], v[188:191], v[44:47]
	v_mfma_f32_16x16x32_bf16 v[40:43], v[172:175], v[188:191], v[40:43]
	v_mfma_f32_16x16x32_bf16 v[28:31], v[154:157], v[196:199], v[28:31]
	v_mfma_f32_16x16x32_bf16 v[24:27], v[172:175], v[196:199], v[24:27]
	v_mfma_f32_16x16x32_bf16 v[12:15], v[154:157], v[204:207], v[12:15]
	v_mfma_f32_16x16x32_bf16 v[8:11], v[172:175], v[204:207], v[8:11]
	v_mfma_f32_16x16x32_bf16 v[52:55], v[208:211], v[176:179], v[52:55]
	v_mfma_f32_16x16x32_bf16 v[48:51], v[216:219], v[176:179], v[48:51]
	v_mfma_f32_16x16x32_bf16 v[36:39], v[208:211], v[184:187], v[36:39]
	v_mfma_f32_16x16x32_bf16 v[32:35], v[216:219], v[184:187], v[32:35]
	v_mfma_f32_16x16x32_bf16 v[20:23], v[208:211], v[192:195], v[20:23]
	v_mfma_f32_16x16x32_bf16 v[16:19], v[216:219], v[192:195], v[16:19]
	v_mfma_f32_16x16x32_bf16 v[4:7], v[208:211], v[200:203], v[4:7]
	v_mfma_f32_16x16x32_bf16 v[0:3], v[216:219], v[200:203], v[0:3]
	v_mfma_f32_16x16x32_bf16 v[52:55], v[212:215], v[180:183], v[52:55]
	v_mfma_f32_16x16x32_bf16 v[48:51], v[220:223], v[180:183], v[48:51]
	v_mfma_f32_16x16x32_bf16 v[36:39], v[212:215], v[188:191], v[36:39]
	v_mfma_f32_16x16x32_bf16 v[32:35], v[220:223], v[188:191], v[32:35]
	v_mfma_f32_16x16x32_bf16 v[20:23], v[212:215], v[196:199], v[20:23]
	v_mfma_f32_16x16x32_bf16 v[16:19], v[220:223], v[196:199], v[16:19]
	v_mfma_f32_16x16x32_bf16 v[4:7], v[212:215], v[204:207], v[4:7]
	v_mfma_f32_16x16x32_bf16 v[0:3], v[220:223], v[204:207], v[0:3]
	s_add_i32 s58, 0, 0x18000
	v_add_u32_e32 v136, s58, v161
	s_barrier
; #define PG8_STAGE(bufoff, gbase, voff) do { _Pragma("unroll") for (int _i = 0; _i < 2; ++_i) \
;         __builtin_amdgcn_global_load_lds((const unsigned*)((const char*)(gbase) + (voff)[_i]), (LAS unsigned*)(lds + (bufoff) + ldsw + _i * 8192), 16, 0, 0); } while (0)
; #define PG8_LDA(dst, b, h) do { _Pragma("unroll") for (int m = 0; m < 4; ++m) _Pragma("unroll") for (int k = 0; k < 2; ++k) dst[m][k] = *(const LAS bf16x8*)(lds + PG8_SA(b, h) + aoff + m * 2048 + k * 1024); } while (0)
; #define PG8_LDB(dst, b, h) do { _Pragma("unroll") for (int n = 0; n < 2; ++n) _Pragma("unroll") for (int k = 0; k < 2; ++k) dst[n][k] = *(const LAS bf16x8*)(lds + PG8_SB(b, h) + boff + n * 2048 + k * 1024); } while (0)
; #define PG8_MMA(ai, bj, At, Bt) do { __builtin_amdgcn_s_setprio(1); _Pragma("unroll") for (int m = 0; m < 4; ++m) _Pragma("unroll") for (int n = 0; n < 2; ++n) _Pragma("unroll") for (int k = 0; k < 2; ++k) \
;         acc[ai][bj][m][n] = __builtin_amdgcn_mfma_f32_16x16x32_bf16(Bt[n][k], At[m][k], acc[ai][bj][m][n], 0, 0, 0); __builtin_amdgcn_s_setprio(0); } while (0)
; #define PG8_WAIT_V(n) asm volatile("s_waitcnt vmcnt(" #n ")" ::: "memory")
; #define PG8_WAIT_L(n) asm volatile("s_waitcnt lgkmcnt(" #n ")" ::: "memory")
; #define PG8_BAR __builtin_amdgcn_s_barrier()
; #define PG8_SCHED __builtin_amdgcn_sched_barrier(0)
; template <class Epi>
; __device__ __forceinline__ void gemm_phase(LAS unsigned char* lds, const Gemm g, const StaticOrder& S, const Epi& E) {
;     ...
;             PG8_LDB(B0, 1, 0); PG8_SCHED; PG8_LDA(At, 1, 0); PG8_STAGE(PG8_SA(0, 1), a2 + hstep, voffA);
;             PG8_WAIT_L(8); PG8_BAR; PG8_WAIT_L(0); PG8_MMA(0, 0, At, B0); PG8_BAR; PG8_SCHED;
;             PG8_LDB(B1, 1, 1); PG8_STAGE(PG8_SB(1, 0), b3, voffB);
;             PG8_BAR; PG8_WAIT_L(0); PG8_MMA(0, 1, At, B1); PG8_BAR;
;             PG8_LDA(At, 1, 1); PG8_STAGE(PG8_SA(1, 0), a3, voffA);
;             PG8_BAR; PG8_WAIT_L(0); PG8_MMA(1, 0, At, B0); PG8_BAR; PG8_SCHED;
;             PG8_STAGE(PG8_SB(1, 1), b3 + hstep, voffB);
;             PG8_WAIT_V(6); PG8_BAR; PG8_MMA(1, 1, At, B1); PG8_BAR;
;         }
	ds_read_b128 v[150:153], v136
	ds_read_b128 v[154:157], v136 offset:1024
	ds_read_b128 v[168:171], v136 offset:2048
	ds_read_b128 v[172:175], v136 offset:3072
	s_add_u32 s50, s50, 0x80000
	s_addc_u32 s51, s51, 0
	s_mov_b32 m0, s31
	ds_read_b128 v[176:179], v165 offset:32768
	ds_read_b128 v[180:183], v165 offset:33792
	ds_read_b128 v[184:187], v165 offset:34816
	ds_read_b128 v[188:191], v165 offset:35840
	ds_read_b128 v[192:195], v165 offset:36864
	ds_read_b128 v[196:199], v165 offset:37888
	ds_read_b128 v[200:203], v165 offset:38912
	ds_read_b128 v[204:207], v165 offset:39936
	global_load_lds_dwordx4 v134, s[50:51]
	s_mov_b32 m0, s33
	s_nop 0
	global_load_lds_dwordx4 v130, s[50:51]
	s_waitcnt lgkmcnt(8)
	s_barrier
	s_waitcnt lgkmcnt(0)
	v_mfma_f32_16x16x32_bf16 v[124:127], v[150:153], v[176:179], v[124:127]
	v_mfma_f32_16x16x32_bf16 v[120:123], v[168:171], v[176:179], v[120:123]
	v_mfma_f32_16x16x32_bf16 v[108:111], v[150:153], v[184:187], v[108:111]
	v_mfma_f32_16x16x32_bf16 v[104:107], v[168:171], v[184:187], v[104:107]
	v_mfma_f32_16x16x32_bf16 v[92:95], v[150:153], v[192:195], v[92:95]
	v_mfma_f32_16x16x32_bf16 v[88:91], v[168:171], v[192:195], v[88:91]
	v_mfma_f32_16x16x32_bf16 v[76:79], v[150:153], v[200:203], v[76:79]
	v_mfma_f32_16x16x32_bf16 v[72:75], v[168:171], v[200:203], v[72:75]
	v_mfma_f32_16x16x32_bf16 v[124:127], v[154:157], v[180:183], v[124:127]
	v_mfma_f32_16x16x32_bf16 v[120:123], v[172:175], v[180:183], v[120:123]
	v_mfma_f32_16x16x32_bf16 v[108:111], v[154:157], v[188:191], v[108:111]
	v_mfma_f32_16x16x32_bf16 v[104:107], v[172:175], v[188:191], v[104:107]
	v_mfma_f32_16x16x32_bf16 v[92:95], v[154:157], v[196:199], v[92:95]
	v_mfma_f32_16x16x32_bf16 v[88:91], v[172:175], v[196:199], v[88:91]
	v_mfma_f32_16x16x32_bf16 v[76:79], v[154:157], v[204:207], v[76:79]
	v_mfma_f32_16x16x32_bf16 v[72:75], v[172:175], v[204:207], v[72:75]
	s_barrier
	s_add_i32 s50, 0, 0x1c000
	s_add_i32 s51, s58, s23
	v_add_u32_e32 v136, s50, v161
	s_mov_b32 m0, s51
	ds_read_b128 v[208:211], v136
	ds_read_b128 v[212:215], v136 offset:1024
	ds_read_b128 v[216:219], v136 offset:2048
	ds_read_b128 v[220:223], v136 offset:3072
	global_load_lds_dwordx4 v132, s[98:99]
	s_add_i32 m0, s51, 0x2000
	s_nop 0
	global_load_lds_dwordx4 v128, s[98:99]
	s_waitcnt lgkmcnt(0)
	s_barrier
	s_waitcnt lgkmcnt(0)
	v_mfma_f32_16x16x32_bf16 v[116:119], v[208:211], v[176:179], v[116:119]
	v_mfma_f32_16x16x32_bf16 v[112:115], v[216:219], v[176:179], v[112:115]
	v_mfma_f32_16x16x32_bf16 v[100:103], v[208:211], v[184:187], v[100:103]
	v_mfma_f32_16x16x32_bf16 v[96:99], v[216:219], v[184:187], v[96:99]
	v_mfma_f32_16x16x32_bf16 v[84:87], v[208:211], v[192:195], v[84:87]
	v_mfma_f32_16x16x32_bf16 v[80:83], v[216:219], v[192:195], v[80:83]
	v_mfma_f32_16x16x32_bf16 v[68:71], v[208:211], v[200:203], v[68:71]
	v_mfma_f32_16x16x32_bf16 v[64:67], v[216:219], v[200:203], v[64:67]
	v_mfma_f32_16x16x32_bf16 v[116:119], v[212:215], v[180:183], v[116:119]
	v_mfma_f32_16x16x32_bf16 v[112:115], v[220:223], v[180:183], v[112:115]
	v_mfma_f32_16x16x32_bf16 v[100:103], v[212:215], v[188:191], v[100:103]
	v_mfma_f32_16x16x32_bf16 v[96:99], v[220:223], v[188:191], v[96:99]
	v_mfma_f32_16x16x32_bf16 v[84:87], v[212:215], v[196:199], v[84:87]
	v_mfma_f32_16x16x32_bf16 v[80:83], v[220:223], v[196:199], v[80:83]
	v_mfma_f32_16x16x32_bf16 v[68:71], v[212:215], v[204:207], v[68:71]
	v_mfma_f32_16x16x32_bf16 v[64:67], v[220:223], v[204:207], v[64:67]
	s_mov_b32 m0, s37
	s_barrier
	ds_read_b128 v[176:179], v165 offset:49152
	ds_read_b128 v[180:183], v165 offset:50176
	ds_read_b128 v[184:187], v165 offset:51200
	ds_read_b128 v[188:191], v165 offset:52224
	ds_read_b128 v[192:195], v165 offset:53248
	ds_read_b128 v[196:199], v165 offset:54272
	ds_read_b128 v[200:203], v165 offset:55296
	ds_read_b128 v[204:207], v165 offset:56320
	global_load_lds_dwordx4 v134, s[100:101]
	s_mov_b32 m0, s38
	s_nop 0
	global_load_lds_dwordx4 v130, s[100:101]
	s_add_u32 s48, s48, 0x80080
	s_addc_u32 s49, s49, 0
	s_add_i32 s50, s50, s23
	s_mov_b32 m0, s50
	s_nop 0
	global_load_lds_dwordx4 v132, s[48:49]
	s_add_i32 m0, s50, 0x2000
	s_nop 0
	global_load_lds_dwordx4 v128, s[48:49]
	s_waitcnt vmcnt(6)
	s_barrier
	s_waitcnt lgkmcnt(0)
	v_mfma_f32_16x16x32_bf16 v[60:63], v[150:153], v[176:179], v[60:63]
	v_mfma_f32_16x16x32_bf16 v[56:59], v[168:171], v[176:179], v[56:59]
	v_mfma_f32_16x16x32_bf16 v[44:47], v[150:153], v[184:187], v[44:47]
	v_mfma_f32_16x16x32_bf16 v[40:43], v[168:171], v[184:187], v[40:43]
	v_mfma_f32_16x16x32_bf16 v[28:31], v[150:153], v[192:195], v[28:31]
	v_mfma_f32_16x16x32_bf16 v[24:27], v[168:171], v[192:195], v[24:27]
	v_mfma_f32_16x16x32_bf16 v[12:15], v[150:153], v[200:203], v[12:15]
	v_mfma_f32_16x16x32_bf16 v[8:11], v[168:171], v[200:203], v[8:11]
	v_mfma_f32_16x16x32_bf16 v[60:63], v[154:157], v[180:183], v[60:63]
	v_mfma_f32_16x16x32_bf16 v[56:59], v[172:175], v[180:183], v[56:59]
	v_mfma_f32_16x16x32_bf16 v[44:47], v[154:157], v[188:191], v[44:47]
	v_mfma_f32_16x16x32_bf16 v[40:43], v[172:175], v[188:191], v[40:43]
	v_mfma_f32_16x16x32_bf16 v[28:31], v[154:157], v[196:199], v[28:31]
	v_mfma_f32_16x16x32_bf16 v[24:27], v[172:175], v[196:199], v[24:27]
	v_mfma_f32_16x16x32_bf16 v[12:15], v[154:157], v[204:207], v[12:15]
	v_mfma_f32_16x16x32_bf16 v[8:11], v[172:175], v[204:207], v[8:11]
	v_mfma_f32_16x16x32_bf16 v[52:55], v[208:211], v[176:179], v[52:55]
	v_mfma_f32_16x16x32_bf16 v[48:51], v[216:219], v[176:179], v[48:51]
	v_mfma_f32_16x16x32_bf16 v[36:39], v[208:211], v[184:187], v[36:39]
	v_mfma_f32_16x16x32_bf16 v[32:35], v[216:219], v[184:187], v[32:35]
	v_mfma_f32_16x16x32_bf16 v[20:23], v[208:211], v[192:195], v[20:23]
	v_mfma_f32_16x16x32_bf16 v[16:19], v[216:219], v[192:195], v[16:19]
	v_mfma_f32_16x16x32_bf16 v[4:7], v[208:211], v[200:203], v[4:7]
	v_mfma_f32_16x16x32_bf16 v[0:3], v[216:219], v[200:203], v[0:3]
	v_mfma_f32_16x16x32_bf16 v[52:55], v[212:215], v[180:183], v[52:55]
	v_mfma_f32_16x16x32_bf16 v[48:51], v[220:223], v[180:183], v[48:51]
	v_mfma_f32_16x16x32_bf16 v[36:39], v[212:215], v[188:191], v[36:39]
	v_mfma_f32_16x16x32_bf16 v[32:35], v[220:223], v[188:191], v[32:35]
	v_mfma_f32_16x16x32_bf16 v[20:23], v[212:215], v[196:199], v[20:23]
	v_mfma_f32_16x16x32_bf16 v[16:19], v[220:223], v[196:199], v[16:19]
	v_mfma_f32_16x16x32_bf16 v[4:7], v[212:215], v[204:207], v[4:7]
	v_mfma_f32_16x16x32_bf16 v[0:3], v[220:223], v[204:207], v[0:3]
	s_add_i32 s57, s57, 2
	s_add_u32 s46, s46, 0x100
	s_addc_u32 s47, s47, 0
	s_add_u32 s55, s55, 0x100
	s_addc_u32 s56, s56, 0
	s_cmp_gt_u32 s57, 29
	s_barrier
; __device__ __forceinline__ u32x4 pack8(f32x4 v0, f32x4 v1) { u32x4 w; w.x = cvt_pk_bf16(v0[0], v0[1]); w.y = cvt_pk_bf16(v0[2], v0[3]); w.z = cvt_pk_bf16(v1[0], v1[1]); w.w = cvt_pk_bf16(v1[2], v1[3]); return w; }
;     __device__ __forceinline__ void operator()(const f32x4 (&acc)[2][2][4][2], const Unit& u, int wr, int wc, int fr, int fq) const {
;         const int row0 = u.pm * BM + wr * 64 + fr;
;         if (u.pn >= 6 && u.pn < 18) {
;             const int d0 = 32 * (wc & 1) + 8 * fq, col1 = u.pn * BM + HALF * (wc >> 1) + d0;
;             const float sc = (u.pn < 12) ? QSCALE : 1.0f;
;     ...
;             const int col0 = u.pn * BM + wc * 32 + 8 * fq; const float sc = (u.pn < 2) ? QSCALE : 1.0f;
; #pragma unroll
;             for (int ai = 0; ai < 2; ++ai)
; #pragma unroll
;                 for (int m = 0; m < 4; ++m) { bf16_t* rowp = O + (size_t)(row0 + ai * HALF + m * 16) * NQKV + col0; const float scr_ = sc * rowsc[row0 + ai * HALF + m * 16];
; #pragma unroll
;                     for (int bj = 0; bj < 2; ++bj) *(u32x4*)(rowp + bj * HALF) = pack8(acc[ai][bj][m][0] * scr_, acc[ai][bj][m][1] * scr_); }
	s_cbranch_scc0 .LBB0_407
	v_lshl_add_u32 v154, s44, 8, v160
	s_add_i32 s9, s34, -6
	s_lshl_b32 s7, s34, 8
	s_cmp_gt_u32 s9, 11
	s_mov_b64 s[44:45], -1
	v_ashrrev_i32_e32 v155, 31, v154
	v_or_b32_e32 v174, 16, v154
	v_or_b32_e32 v173, 32, v154
	v_or_b32_e32 v172, 48, v154
	v_add_u32_e32 v171, 0x80, v154
	v_add_u32_e32 v170, 0x90, v154
	v_add_u32_e32 v169, 0xa0, v154
	v_add_u32_e32 v168, 0xb0, v154
	s_cbranch_scc0 .LBB0_410
	v_lshl_add_u64 v[150:151], v[154:155], 2, s[14:15]
	global_load_dword v136, v[150:151], off
	global_load_dword v204, v[150:151], off offset:64
	global_load_dword v205, v[150:151], off offset:128
	global_load_dword v206, v[150:151], off offset:192
	global_load_dword v207, v[150:151], off offset:512
	global_load_dword v208, v[150:151], off offset:576
	global_load_dword v209, v[150:151], off offset:640
	global_load_dword v210, v[150:151], off offset:704
	s_cmp_lt_i32 s34, 2
	v_or_b32_e32 v156, s7, v162
	s_cselect_b64 vcc, -1, 0
	v_mov_b64_e32 v[152:153], s[20:21]
	v_cndmask_b32_e32 v175, 1.0, v167, vcc
	v_ashrrev_i32_e32 v157, 31, v156
	v_mad_i64_i32 v[176:177], s[44:45], v154, s53, v[152:153]
	v_lshlrev_b64 v[156:157], 1, v[156:157]
	v_lshl_add_u64 v[180:181], v[176:177], 0, v[156:157]
	s_waitcnt vmcnt(0)
	v_mul_f32_e32 v136, v175, v136
	v_pk_mul_f32 v[178:179], v[126:127], v[136:137] op_sel_hi:[1,0]
	v_pk_mul_f32 v[176:177], v[124:125], v[136:137] op_sel_hi:[1,0]
	v_pk_mul_f32 v[182:183], v[122:123], v[136:137] op_sel_hi:[1,0]
	v_pk_mul_f32 v[184:185], v[120:121], v[136:137] op_sel_hi:[1,0]
	v_cvt_pk_bf16_f32 v176, v176, v177
	v_cvt_pk_bf16_f32 v177, v178, v179
	v_pk_mul_f32 v[186:187], v[118:119], v[136:137] op_sel_hi:[1,0]
	v_cvt_pk_bf16_f32 v178, v184, v185
	v_cvt_pk_bf16_f32 v179, v182, v183
	v_pk_mul_f32 v[188:189], v[116:117], v[136:137] op_sel_hi:[1,0]
	v_pk_mul_f32 v[190:191], v[114:115], v[136:137] op_sel_hi:[1,0]
	v_pk_mul_f32 v[192:193], v[112:113], v[136:137] op_sel_hi:[1,0]
	global_store_dwordx4 v[180:181], v[176:179], off
	s_nop 1
	v_cvt_pk_bf16_f32 v176, v188, v189
	v_cvt_pk_bf16_f32 v177, v186, v187
	v_cvt_pk_bf16_f32 v178, v192, v193
	v_cvt_pk_bf16_f32 v179, v190, v191
	global_store_dwordx4 v[180:181], v[176:179], off offset:256
	s_nop 1
	v_mov_b32_e32 v136, v204
	v_mul_f32_e32 v136, v175, v136
	v_mad_i64_i32 v[176:177], s[44:45], v174, s53, v[152:153]
	v_lshl_add_u64 v[180:181], v[176:177], 0, v[156:157]
	v_pk_mul_f32 v[178:179], v[110:111], v[136:137] op_sel_hi:[1,0]
	v_pk_mul_f32 v[176:177], v[108:109], v[136:137] op_sel_hi:[1,0]
	v_pk_mul_f32 v[182:183], v[106:107], v[136:137] op_sel_hi:[1,0]
	v_pk_mul_f32 v[184:185], v[104:105], v[136:137] op_sel_hi:[1,0]
	v_cvt_pk_bf16_f32 v176, v176, v177
	v_cvt_pk_bf16_f32 v177, v178, v179
	v_pk_mul_f32 v[186:187], v[102:103], v[136:137] op_sel_hi:[1,0]
	v_cvt_pk_bf16_f32 v178, v184, v185
	v_cvt_pk_bf16_f32 v179, v182, v183
	v_pk_mul_f32 v[188:189], v[100:101], v[136:137] op_sel_hi:[1,0]
	v_pk_mul_f32 v[190:191], v[98:99], v[136:137] op_sel_hi:[1,0]
	v_pk_mul_f32 v[192:193], v[96:97], v[136:137] op_sel_hi:[1,0]
	global_store_dwordx4 v[180:181], v[176:179], off
	s_nop 1
	v_cvt_pk_bf16_f32 v176, v188, v189
	v_cvt_pk_bf16_f32 v177, v186, v187
	v_cvt_pk_bf16_f32 v178, v192, v193
	v_cvt_pk_bf16_f32 v179, v190, v191
	global_store_dwordx4 v[180:181], v[176:179], off offset:256
	s_nop 1
	v_mov_b32_e32 v136, v205
	v_mul_f32_e32 v136, v175, v136
	v_mad_i64_i32 v[176:177], s[44:45], v173, s53, v[152:153]
	v_lshl_add_u64 v[180:181], v[176:177], 0, v[156:157]
	v_pk_mul_f32 v[178:179], v[94:95], v[136:137] op_sel_hi:[1,0]
	v_pk_mul_f32 v[176:177], v[92:93], v[136:137] op_sel_hi:[1,0]
	v_pk_mul_f32 v[182:183], v[90:91], v[136:137] op_sel_hi:[1,0]
	v_pk_mul_f32 v[184:185], v[88:89], v[136:137] op_sel_hi:[1,0]
	v_cvt_pk_bf16_f32 v176, v176, v177
	v_cvt_pk_bf16_f32 v177, v178, v179
	v_pk_mul_f32 v[186:187], v[86:87], v[136:137] op_sel_hi:[1,0]
	v_cvt_pk_bf16_f32 v178, v184, v185
	v_cvt_pk_bf16_f32 v179, v182, v183
	v_pk_mul_f32 v[188:189], v[84:85], v[136:137] op_sel_hi:[1,0]
	v_pk_mul_f32 v[190:191], v[82:83], v[136:137] op_sel_hi:[1,0]
	v_pk_mul_f32 v[192:193], v[80:81], v[136:137] op_sel_hi:[1,0]
	global_store_dwordx4 v[180:181], v[176:179], off
	s_nop 1
	v_cvt_pk_bf16_f32 v176, v188, v189
	v_cvt_pk_bf16_f32 v177, v186, v187
	v_cvt_pk_bf16_f32 v178, v192, v193
	v_cvt_pk_bf16_f32 v179, v190, v191
	global_store_dwordx4 v[180:181], v[176:179], off offset:256
	s_nop 1
	v_mov_b32_e32 v136, v206
	v_mul_f32_e32 v136, v175, v136
	v_mad_i64_i32 v[176:177], s[44:45], v172, s53, v[152:153]
	v_lshl_add_u64 v[180:181], v[176:177], 0, v[156:157]
	v_pk_mul_f32 v[178:179], v[78:79], v[136:137] op_sel_hi:[1,0]
	v_pk_mul_f32 v[176:177], v[76:77], v[136:137] op_sel_hi:[1,0]
	v_pk_mul_f32 v[182:183], v[74:75], v[136:137] op_sel_hi:[1,0]
	v_pk_mul_f32 v[184:185], v[72:73], v[136:137] op_sel_hi:[1,0]
	v_cvt_pk_bf16_f32 v176, v176, v177
	v_cvt_pk_bf16_f32 v177, v178, v179
	v_pk_mul_f32 v[186:187], v[70:71], v[136:137] op_sel_hi:[1,0]
; __device__ __forceinline__ u32x4 pack8(f32x4 v0, f32x4 v1) { u32x4 w; w.x = cvt_pk_bf16(v0[0], v0[1]); w.y = cvt_pk_bf16(v0[2], v0[3]); w.z = cvt_pk_bf16(v1[0], v1[1]); w.w = cvt_pk_bf16(v1[2], v1[3]); return w; }
;     __device__ __forceinline__ void operator()(const f32x4 (&acc)[2][2][4][2], const Unit& u, int wr, int wc, int fr, int fq) const {
;     ...
;             const int col0 = u.pn * BM + wc * 32 + 8 * fq; const float sc = (u.pn < 2) ? QSCALE : 1.0f;
; #pragma unroll
;             for (int ai = 0; ai < 2; ++ai)
; #pragma unroll
;                 for (int m = 0; m < 4; ++m) { bf16_t* rowp = O + (size_t)(row0 + ai * HALF + m * 16) * NQKV + col0; const float scr_ = sc * rowsc[row0 + ai * HALF + m * 16];
; #pragma unroll
;                     for (int bj = 0; bj < 2; ++bj) *(u32x4*)(rowp + bj * HALF) = pack8(acc[ai][bj][m][0] * scr_, acc[ai][bj][m][1] * scr_); }
	v_cvt_pk_bf16_f32 v178, v184, v185
	v_cvt_pk_bf16_f32 v179, v182, v183
	v_pk_mul_f32 v[188:189], v[68:69], v[136:137] op_sel_hi:[1,0]
	v_pk_mul_f32 v[190:191], v[66:67], v[136:137] op_sel_hi:[1,0]
	v_pk_mul_f32 v[192:193], v[64:65], v[136:137] op_sel_hi:[1,0]
	global_store_dwordx4 v[180:181], v[176:179], off
	s_nop 1
	v_cvt_pk_bf16_f32 v176, v188, v189
	v_cvt_pk_bf16_f32 v177, v186, v187
	v_cvt_pk_bf16_f32 v178, v192, v193
	v_cvt_pk_bf16_f32 v179, v190, v191
	global_store_dwordx4 v[180:181], v[176:179], off offset:256
	s_nop 1
	v_mov_b32_e32 v136, v207
	v_mul_f32_e32 v136, v175, v136
	v_mad_i64_i32 v[176:177], s[44:45], v171, s53, v[152:153]
	v_lshl_add_u64 v[180:181], v[176:177], 0, v[156:157]
	v_pk_mul_f32 v[178:179], v[62:63], v[136:137] op_sel_hi:[1,0]
	v_pk_mul_f32 v[176:177], v[60:61], v[136:137] op_sel_hi:[1,0]
	v_pk_mul_f32 v[182:183], v[58:59], v[136:137] op_sel_hi:[1,0]
	v_pk_mul_f32 v[184:185], v[56:57], v[136:137] op_sel_hi:[1,0]
	v_cvt_pk_bf16_f32 v176, v176, v177
	v_cvt_pk_bf16_f32 v177, v178, v179
	v_pk_mul_f32 v[186:187], v[54:55], v[136:137] op_sel_hi:[1,0]
	v_cvt_pk_bf16_f32 v178, v184, v185
	v_cvt_pk_bf16_f32 v179, v182, v183
	v_pk_mul_f32 v[188:189], v[52:53], v[136:137] op_sel_hi:[1,0]
	v_pk_mul_f32 v[190:191], v[50:51], v[136:137] op_sel_hi:[1,0]
	v_pk_mul_f32 v[192:193], v[48:49], v[136:137] op_sel_hi:[1,0]
	global_store_dwordx4 v[180:181], v[176:179], off
	s_nop 1
	v_cvt_pk_bf16_f32 v176, v188, v189
	v_cvt_pk_bf16_f32 v177, v186, v187
	v_cvt_pk_bf16_f32 v178, v192, v193
	v_cvt_pk_bf16_f32 v179, v190, v191
	global_store_dwordx4 v[180:181], v[176:179], off offset:256
	s_nop 1
	v_mov_b32_e32 v136, v208
	v_mul_f32_e32 v136, v175, v136
	v_mad_i64_i32 v[176:177], s[44:45], v170, s53, v[152:153]
	v_lshl_add_u64 v[180:181], v[176:177], 0, v[156:157]
	v_pk_mul_f32 v[178:179], v[46:47], v[136:137] op_sel_hi:[1,0]
	v_pk_mul_f32 v[176:177], v[44:45], v[136:137] op_sel_hi:[1,0]
	v_pk_mul_f32 v[182:183], v[42:43], v[136:137] op_sel_hi:[1,0]
	v_pk_mul_f32 v[184:185], v[40:41], v[136:137] op_sel_hi:[1,0]
	v_cvt_pk_bf16_f32 v176, v176, v177
	v_cvt_pk_bf16_f32 v177, v178, v179
	v_pk_mul_f32 v[186:187], v[38:39], v[136:137] op_sel_hi:[1,0]
	v_cvt_pk_bf16_f32 v178, v184, v185
	v_cvt_pk_bf16_f32 v179, v182, v183
	v_pk_mul_f32 v[188:189], v[36:37], v[136:137] op_sel_hi:[1,0]
	v_pk_mul_f32 v[190:191], v[34:35], v[136:137] op_sel_hi:[1,0]
	v_pk_mul_f32 v[192:193], v[32:33], v[136:137] op_sel_hi:[1,0]
	global_store_dwordx4 v[180:181], v[176:179], off
	s_nop 1
	v_cvt_pk_bf16_f32 v176, v188, v189
	v_cvt_pk_bf16_f32 v177, v186, v187
	v_cvt_pk_bf16_f32 v178, v192, v193
	v_cvt_pk_bf16_f32 v179, v190, v191
	global_store_dwordx4 v[180:181], v[176:179], off offset:256
	s_nop 1
	v_mov_b32_e32 v136, v209
	v_mul_f32_e32 v136, v175, v136
	v_mad_i64_i32 v[176:177], s[44:45], v169, s53, v[152:153]
	v_lshl_add_u64 v[180:181], v[176:177], 0, v[156:157]
	v_pk_mul_f32 v[178:179], v[30:31], v[136:137] op_sel_hi:[1,0]
	v_pk_mul_f32 v[176:177], v[28:29], v[136:137] op_sel_hi:[1,0]
	v_pk_mul_f32 v[182:183], v[26:27], v[136:137] op_sel_hi:[1,0]
	v_pk_mul_f32 v[184:185], v[24:25], v[136:137] op_sel_hi:[1,0]
	v_cvt_pk_bf16_f32 v176, v176, v177
	v_cvt_pk_bf16_f32 v177, v178, v179
	v_pk_mul_f32 v[186:187], v[22:23], v[136:137] op_sel_hi:[1,0]
	v_cvt_pk_bf16_f32 v178, v184, v185
	v_cvt_pk_bf16_f32 v179, v182, v183
	v_pk_mul_f32 v[188:189], v[20:21], v[136:137] op_sel_hi:[1,0]
	v_pk_mul_f32 v[190:191], v[18:19], v[136:137] op_sel_hi:[1,0]
	v_pk_mul_f32 v[192:193], v[16:17], v[136:137] op_sel_hi:[1,0]
	global_store_dwordx4 v[180:181], v[176:179], off
	s_nop 1
	v_cvt_pk_bf16_f32 v176, v188, v189
	v_cvt_pk_bf16_f32 v177, v186, v187
	v_cvt_pk_bf16_f32 v178, v192, v193
	v_cvt_pk_bf16_f32 v179, v190, v191
	global_store_dwordx4 v[180:181], v[176:179], off offset:256
	s_nop 1
	v_mov_b32_e32 v136, v210
	v_mad_i64_i32 v[150:151], s[44:45], v168, s53, v[152:153]
	v_lshl_add_u64 v[156:157], v[150:151], 0, v[156:157]
	s_mov_b64 s[44:45], 0
	v_mul_f32_e32 v136, v175, v136
	v_pk_mul_f32 v[152:153], v[14:15], v[136:137] op_sel_hi:[1,0]
	v_pk_mul_f32 v[150:151], v[12:13], v[136:137] op_sel_hi:[1,0]
	v_pk_mul_f32 v[176:177], v[10:11], v[136:137] op_sel_hi:[1,0]
	v_pk_mul_f32 v[178:179], v[8:9], v[136:137] op_sel_hi:[1,0]
	v_cvt_pk_bf16_f32 v150, v150, v151
	v_cvt_pk_bf16_f32 v151, v152, v153
	v_pk_mul_f32 v[180:181], v[6:7], v[136:137] op_sel_hi:[1,0]
	v_cvt_pk_bf16_f32 v152, v178, v179
	v_cvt_pk_bf16_f32 v153, v176, v177
	v_pk_mul_f32 v[182:183], v[4:5], v[136:137] op_sel_hi:[1,0]
	v_pk_mul_f32 v[184:185], v[2:3], v[136:137] op_sel_hi:[1,0]
	v_pk_mul_f32 v[186:187], v[0:1], v[136:137] op_sel_hi:[1,0]
	global_store_dwordx4 v[156:157], v[150:153], off
	s_nop 1
	v_cvt_pk_bf16_f32 v150, v182, v183
	v_cvt_pk_bf16_f32 v151, v180, v181
	v_cvt_pk_bf16_f32 v152, v186, v187
	v_cvt_pk_bf16_f32 v153, v184, v185
	global_store_dwordx4 v[156:157], v[150:153], off offset:256

; #define PG8_STAGE(bufoff, gbase, voff) do { _Pragma("unroll") for (int _i = 0; _i < 2; ++_i) \
;         __builtin_amdgcn_global_load_lds((const unsigned*)((const char*)(gbase) + (voff)[_i]), (LAS unsigned*)(lds + (bufoff) + ldsw + _i * 8192), 16, 0, 0); } while (0)
; #define PG8_LDA(dst, b, h) do { _Pragma("unroll") for (int m = 0; m < 4; ++m) _Pragma("unroll") for (int k = 0; k < 2; ++k) dst[m][k] = *(const LAS bf16x8*)(lds + PG8_SA(b, h) + aoff + m * 2048 + k * 1024); } while (0)
; #define PG8_LDB(dst, b, h) do { _Pragma("unroll") for (int n = 0; n < 2; ++n) _Pragma("unroll") for (int k = 0; k < 2; ++k) dst[n][k] = *(const LAS bf16x8*)(lds + PG8_SB(b, h) + boff + n * 2048 + k * 1024); } while (0)
; #define PG8_MMA(ai, bj, At, Bt) do { __builtin_amdgcn_s_setprio(1); _Pragma("unroll") for (int m = 0; m < 4; ++m) _Pragma("unroll") for (int n = 0; n < 2; ++n) _Pragma("unroll") for (int k = 0; k < 2; ++k) \
;         acc[ai][bj][m][n] = __builtin_amdgcn_mfma_f32_16x16x32_bf16(Bt[n][k], At[m][k], acc[ai][bj][m][n], 0, 0, 0); __builtin_amdgcn_s_setprio(0); } while (0)
; #define PG8_WAIT_V(n) asm volatile("s_waitcnt vmcnt(" #n ")" ::: "memory")
; #define PG8_WAIT_L(n) asm volatile("s_waitcnt lgkmcnt(" #n ")" ::: "memory")
; #define PG8_BAR __builtin_amdgcn_s_barrier()
; #define PG8_SCHED __builtin_amdgcn_sched_barrier(0)
; template <class Epi>
; __device__ __forceinline__ void gemm_phase(LAS unsigned char* lds, const Gemm g, const StaticOrder& S, const Epi& E) {
;     ...
;             const char* a1 = cA + (size_t)(t + 1) * kstep;
;             const char* a2 = last ? nA : cA + (size_t)(t + 2) * kstep; const char* b2 = last ? nB : cB + (size_t)(t + 2) * kstep;
;             const char* a3 = a2 + kstep; const char* b3 = b2 + kstep;
;             PG8_LDB(B0, 0, 0); PG8_SCHED; PG8_LDA(At, 0, 0); PG8_STAGE(PG8_SA(1, 1), a1 + hstep, voffA);
;             PG8_WAIT_L(8); PG8_BAR; PG8_WAIT_L(0); PG8_MMA(0, 0, At, B0); PG8_BAR; PG8_SCHED;
;             PG8_LDB(B1, 0, 1); PG8_STAGE(PG8_SB(0, 0), b2, voffB);
;             PG8_BAR; PG8_WAIT_L(0); PG8_MMA(0, 1, At, B1); PG8_BAR;
;             PG8_LDA(At, 0, 1); PG8_STAGE(PG8_SA(0, 0), a2, voffA);
;             PG8_BAR; PG8_WAIT_L(0); PG8_MMA(1, 0, At, B0); PG8_BAR; PG8_SCHED;
;             PG8_STAGE(PG8_SB(0, 1), b2 + hstep, voffB);
;             PG8_WAIT_V(6); PG8_BAR; PG8_MMA(1, 1, At, B1); PG8_BAR;
.LBB0_673:
	ds_read_b128 v[148:151], v145
	ds_read_b128 v[152:155], v145 offset:1024
	ds_read_b128 v[160:163], v145 offset:2048
	ds_read_b128 v[164:167], v145 offset:3072
	s_add_u32 s52, s50, 0xfff80080
	s_addc_u32 s53, s51, -1
	s_cmp_eq_u32 s69, 28
	s_cselect_b32 s55, s43, s53
	s_cselect_b32 s54, s65, s52
	s_cselect_b32 s53, s41, s68
	s_cselect_b32 s52, s66, s67
	s_add_i32 m0, s28, 0xc000
	ds_read_b128 v[168:171], v146
	ds_read_b128 v[172:175], v146 offset:1024
	ds_read_b128 v[176:179], v146 offset:2048
	ds_read_b128 v[180:183], v146 offset:3072
	ds_read_b128 v[184:187], v146 offset:4096
	ds_read_b128 v[188:191], v146 offset:5120
	ds_read_b128 v[192:195], v146 offset:6144
	ds_read_b128 v[196:199], v146 offset:7168
	global_load_lds_dwordx4 v136, s[50:51]
	s_add_i32 m0, s28, 0xe000
	s_nop 0
	global_load_lds_dwordx4 v138, s[50:51]
	s_waitcnt lgkmcnt(8)
	s_barrier
	s_waitcnt lgkmcnt(0)
	v_mfma_f32_16x16x32_bf16 v[124:127], v[148:151], v[168:171], v[124:127]
	v_mfma_f32_16x16x32_bf16 v[120:123], v[160:163], v[168:171], v[120:123]
	v_mfma_f32_16x16x32_bf16 v[112:115], v[148:151], v[176:179], v[112:115]
	v_mfma_f32_16x16x32_bf16 v[104:107], v[160:163], v[176:179], v[104:107]
	v_mfma_f32_16x16x32_bf16 v[96:99], v[148:151], v[184:187], v[96:99]
	v_mfma_f32_16x16x32_bf16 v[88:91], v[160:163], v[184:187], v[88:91]
	v_mfma_f32_16x16x32_bf16 v[80:83], v[148:151], v[192:195], v[80:83]
	v_mfma_f32_16x16x32_bf16 v[72:75], v[160:163], v[192:195], v[72:75]
	v_mfma_f32_16x16x32_bf16 v[124:127], v[152:155], v[172:175], v[124:127]
	v_mfma_f32_16x16x32_bf16 v[120:123], v[164:167], v[172:175], v[120:123]
	v_mfma_f32_16x16x32_bf16 v[112:115], v[152:155], v[180:183], v[112:115]
	v_mfma_f32_16x16x32_bf16 v[104:107], v[164:167], v[180:183], v[104:107]
	v_mfma_f32_16x16x32_bf16 v[96:99], v[152:155], v[188:191], v[96:99]
	v_mfma_f32_16x16x32_bf16 v[88:91], v[164:167], v[188:191], v[88:91]
	v_mfma_f32_16x16x32_bf16 v[80:83], v[152:155], v[196:199], v[80:83]
	v_mfma_f32_16x16x32_bf16 v[72:75], v[164:167], v[196:199], v[72:75]
	s_barrier
	s_add_i32 s70, s58, s23
	s_add_u32 s98, s52, s6
	s_addc_u32 s99, s53, s7
	s_mov_b32 m0, s70
	ds_read_b128 v[200:203], v147
	ds_read_b128 v[204:207], v147 offset:1024
	ds_read_b128 v[208:211], v147 offset:2048
	ds_read_b128 v[212:215], v147 offset:3072
	global_load_lds_dwordx4 v132, s[52:53]
	s_add_i32 m0, s70, 0x2000
	s_nop 0
	global_load_lds_dwordx4 v128, s[52:53]
	s_waitcnt lgkmcnt(0)
	s_barrier
	s_waitcnt lgkmcnt(0)
	v_mfma_f32_16x16x32_bf16 v[116:119], v[200:203], v[168:171], v[116:119]
	v_mfma_f32_16x16x32_bf16 v[108:111], v[208:211], v[168:171], v[108:111]
	v_mfma_f32_16x16x32_bf16 v[100:103], v[200:203], v[176:179], v[100:103]
	v_mfma_f32_16x16x32_bf16 v[92:95], v[208:211], v[176:179], v[92:95]
	v_mfma_f32_16x16x32_bf16 v[84:87], v[200:203], v[184:187], v[84:87]
	v_mfma_f32_16x16x32_bf16 v[76:79], v[208:211], v[184:187], v[76:79]
	v_mfma_f32_16x16x32_bf16 v[68:71], v[200:203], v[192:195], v[68:71]
	v_mfma_f32_16x16x32_bf16 v[64:67], v[208:211], v[192:195], v[64:67]
	v_mfma_f32_16x16x32_bf16 v[116:119], v[204:207], v[172:175], v[116:119]
	v_mfma_f32_16x16x32_bf16 v[108:111], v[212:215], v[172:175], v[108:111]
	v_mfma_f32_16x16x32_bf16 v[100:103], v[204:207], v[180:183], v[100:103]
	v_mfma_f32_16x16x32_bf16 v[92:95], v[212:215], v[180:183], v[92:95]
	v_mfma_f32_16x16x32_bf16 v[84:87], v[204:207], v[188:191], v[84:87]
	v_mfma_f32_16x16x32_bf16 v[76:79], v[212:215], v[188:191], v[76:79]
	v_mfma_f32_16x16x32_bf16 v[68:71], v[204:207], v[196:199], v[68:71]
	v_mfma_f32_16x16x32_bf16 v[64:67], v[212:215], v[196:199], v[64:67]
	s_mov_b32 m0, s28
	s_add_u32 s100, s54, s6
	s_addc_u32 s101, s55, s7
	s_barrier
	ds_read_b128 v[168:171], v146 offset:16384
	ds_read_b128 v[172:175], v146 offset:17408
	ds_read_b128 v[176:179], v146 offset:18432
	ds_read_b128 v[180:183], v146 offset:19456
	ds_read_b128 v[184:187], v146 offset:20480
	ds_read_b128 v[188:191], v146 offset:21504
	ds_read_b128 v[192:195], v146 offset:22528
	ds_read_b128 v[196:199], v146 offset:23552
	global_load_lds_dwordx4 v134, s[54:55]
	s_mov_b32 m0, s29
	s_nop 0
	global_load_lds_dwordx4 v130, s[54:55]
	s_add_u32 s70, s52, 0x80000
	s_addc_u32 s71, s53, 0
	s_add_i32 s72, s59, s23
	s_mov_b32 m0, s72
	s_nop 0
	global_load_lds_dwordx4 v132, s[70:71]
	s_add_i32 m0, s72, 0x2000
	s_nop 0
	global_load_lds_dwordx4 v128, s[70:71]
	s_waitcnt vmcnt(6)
	s_barrier
	s_waitcnt lgkmcnt(0)
	v_mfma_f32_16x16x32_bf16 v[60:63], v[148:151], v[168:171], v[60:63]
	v_mfma_f32_16x16x32_bf16 v[56:59], v[160:163], v[168:171], v[56:59]
	v_mfma_f32_16x16x32_bf16 v[52:55], v[148:151], v[176:179], v[52:55]
	v_mfma_f32_16x16x32_bf16 v[44:47], v[160:163], v[176:179], v[44:47]
	v_mfma_f32_16x16x32_bf16 v[36:39], v[148:151], v[184:187], v[36:39]
	v_mfma_f32_16x16x32_bf16 v[28:31], v[160:163], v[184:187], v[28:31]
	v_mfma_f32_16x16x32_bf16 v[20:23], v[148:151], v[192:195], v[20:23]
	v_mfma_f32_16x16x32_bf16 v[12:15], v[160:163], v[192:195], v[12:15]
	v_mfma_f32_16x16x32_bf16 v[60:63], v[152:155], v[172:175], v[60:63]
	v_mfma_f32_16x16x32_bf16 v[56:59], v[164:167], v[172:175], v[56:59]
	v_mfma_f32_16x16x32_bf16 v[52:55], v[152:155], v[180:183], v[52:55]
	v_mfma_f32_16x16x32_bf16 v[44:47], v[164:167], v[180:183], v[44:47]
	v_mfma_f32_16x16x32_bf16 v[36:39], v[152:155], v[188:191], v[36:39]
	v_mfma_f32_16x16x32_bf16 v[28:31], v[164:167], v[188:191], v[28:31]
	v_mfma_f32_16x16x32_bf16 v[20:23], v[152:155], v[196:199], v[20:23]
	v_mfma_f32_16x16x32_bf16 v[12:15], v[164:167], v[196:199], v[12:15]
	v_mfma_f32_16x16x32_bf16 v[48:51], v[200:203], v[168:171], v[48:51]
	v_mfma_f32_16x16x32_bf16 v[40:43], v[208:211], v[168:171], v[40:43]
	v_mfma_f32_16x16x32_bf16 v[32:35], v[200:203], v[176:179], v[32:35]
	v_mfma_f32_16x16x32_bf16 v[24:27], v[208:211], v[176:179], v[24:27]
	v_mfma_f32_16x16x32_bf16 v[16:19], v[200:203], v[184:187], v[16:19]
	v_mfma_f32_16x16x32_bf16 v[8:11], v[208:211], v[184:187], v[8:11]
	v_mfma_f32_16x16x32_bf16 v[4:7], v[200:203], v[192:195], v[4:7]
	v_mfma_f32_16x16x32_bf16 v[0:3], v[208:211], v[192:195], v[0:3]
	v_mfma_f32_16x16x32_bf16 v[48:51], v[204:207], v[172:175], v[48:51]
	v_mfma_f32_16x16x32_bf16 v[40:43], v[212:215], v[172:175], v[40:43]
	v_mfma_f32_16x16x32_bf16 v[32:35], v[204:207], v[180:183], v[32:35]
	v_mfma_f32_16x16x32_bf16 v[24:27], v[212:215], v[180:183], v[24:27]
	v_mfma_f32_16x16x32_bf16 v[16:19], v[204:207], v[188:191], v[16:19]
	v_mfma_f32_16x16x32_bf16 v[8:11], v[212:215], v[188:191], v[8:11]
	v_mfma_f32_16x16x32_bf16 v[4:7], v[204:207], v[196:199], v[4:7]
	v_mfma_f32_16x16x32_bf16 v[0:3], v[212:215], v[196:199], v[0:3]
	s_add_i32 s70, 0, 0x18000
	v_add_u32_e32 v164, s70, v143
	s_barrier
; #define PG8_STAGE(bufoff, gbase, voff) do { _Pragma("unroll") for (int _i = 0; _i < 2; ++_i) \
;         __builtin_amdgcn_global_load_lds((const unsigned*)((const char*)(gbase) + (voff)[_i]), (LAS unsigned*)(lds + (bufoff) + ldsw + _i * 8192), 16, 0, 0); } while (0)
; #define PG8_LDA(dst, b, h) do { _Pragma("unroll") for (int m = 0; m < 4; ++m) _Pragma("unroll") for (int k = 0; k < 2; ++k) dst[m][k] = *(const LAS bf16x8*)(lds + PG8_SA(b, h) + aoff + m * 2048 + k * 1024); } while (0)
; #define PG8_LDB(dst, b, h) do { _Pragma("unroll") for (int n = 0; n < 2; ++n) _Pragma("unroll") for (int k = 0; k < 2; ++k) dst[n][k] = *(const LAS bf16x8*)(lds + PG8_SB(b, h) + boff + n * 2048 + k * 1024); } while (0)
; #define PG8_MMA(ai, bj, At, Bt) do { __builtin_amdgcn_s_setprio(1); _Pragma("unroll") for (int m = 0; m < 4; ++m) _Pragma("unroll") for (int n = 0; n < 2; ++n) _Pragma("unroll") for (int k = 0; k < 2; ++k) \
;         acc[ai][bj][m][n] = __builtin_amdgcn_mfma_f32_16x16x32_bf16(Bt[n][k], At[m][k], acc[ai][bj][m][n], 0, 0, 0); __builtin_amdgcn_s_setprio(0); } while (0)
; #define PG8_WAIT_V(n) asm volatile("s_waitcnt vmcnt(" #n ")" ::: "memory")
; #define PG8_WAIT_L(n) asm volatile("s_waitcnt lgkmcnt(" #n ")" ::: "memory")
; #define PG8_BAR __builtin_amdgcn_s_barrier()
; #define PG8_SCHED __builtin_amdgcn_sched_barrier(0)
; template <class Epi>
; __device__ __forceinline__ void gemm_phase(LAS unsigned char* lds, const Gemm g, const StaticOrder& S, const Epi& E) {
;     ...
;             PG8_LDB(B0, 1, 0); PG8_SCHED; PG8_LDA(At, 1, 0); PG8_STAGE(PG8_SA(0, 1), a2 + hstep, voffA);
;             PG8_WAIT_L(8); PG8_BAR; PG8_WAIT_L(0); PG8_MMA(0, 0, At, B0); PG8_BAR; PG8_SCHED;
;             PG8_LDB(B1, 1, 1); PG8_STAGE(PG8_SB(1, 0), b3, voffB);
;             PG8_BAR; PG8_WAIT_L(0); PG8_MMA(0, 1, At, B1); PG8_BAR;
;             PG8_LDA(At, 1, 1); PG8_STAGE(PG8_SA(1, 0), a3, voffA);
;             PG8_BAR; PG8_WAIT_L(0); PG8_MMA(1, 0, At, B0); PG8_BAR; PG8_SCHED;
;             PG8_STAGE(PG8_SB(1, 1), b3 + hstep, voffB);
;             PG8_WAIT_V(6); PG8_BAR; PG8_MMA(1, 1, At, B1); PG8_BAR;
;         }
	ds_read_b128 v[148:151], v164
	ds_read_b128 v[152:155], v164 offset:1024
	ds_read_b128 v[160:163], v164 offset:2048
	ds_read_b128 v[164:167], v164 offset:3072
	s_add_u32 s54, s54, 0x80000
	s_addc_u32 s55, s55, 0
	s_mov_b32 m0, s33
	ds_read_b128 v[168:171], v146 offset:32768
	ds_read_b128 v[172:175], v146 offset:33792
	ds_read_b128 v[176:179], v146 offset:34816
	ds_read_b128 v[180:183], v146 offset:35840
	ds_read_b128 v[184:187], v146 offset:36864
	ds_read_b128 v[188:191], v146 offset:37888
	ds_read_b128 v[192:195], v146 offset:38912
	ds_read_b128 v[196:199], v146 offset:39936
	global_load_lds_dwordx4 v134, s[54:55]
	s_mov_b32 m0, s36
	s_nop 0
	global_load_lds_dwordx4 v130, s[54:55]
	s_waitcnt lgkmcnt(8)
	s_barrier
	s_waitcnt lgkmcnt(0)
	v_mfma_f32_16x16x32_bf16 v[124:127], v[148:151], v[168:171], v[124:127]
	v_mfma_f32_16x16x32_bf16 v[120:123], v[160:163], v[168:171], v[120:123]
	v_mfma_f32_16x16x32_bf16 v[112:115], v[148:151], v[176:179], v[112:115]
	v_mfma_f32_16x16x32_bf16 v[104:107], v[160:163], v[176:179], v[104:107]
	v_mfma_f32_16x16x32_bf16 v[96:99], v[148:151], v[184:187], v[96:99]
	v_mfma_f32_16x16x32_bf16 v[88:91], v[160:163], v[184:187], v[88:91]
	v_mfma_f32_16x16x32_bf16 v[80:83], v[148:151], v[192:195], v[80:83]
	v_mfma_f32_16x16x32_bf16 v[72:75], v[160:163], v[192:195], v[72:75]
	v_mfma_f32_16x16x32_bf16 v[124:127], v[152:155], v[172:175], v[124:127]
	v_mfma_f32_16x16x32_bf16 v[120:123], v[164:167], v[172:175], v[120:123]
	v_mfma_f32_16x16x32_bf16 v[112:115], v[152:155], v[180:183], v[112:115]
	v_mfma_f32_16x16x32_bf16 v[104:107], v[164:167], v[180:183], v[104:107]
	v_mfma_f32_16x16x32_bf16 v[96:99], v[152:155], v[188:191], v[96:99]
	v_mfma_f32_16x16x32_bf16 v[88:91], v[164:167], v[188:191], v[88:91]
	v_mfma_f32_16x16x32_bf16 v[80:83], v[152:155], v[196:199], v[80:83]
	v_mfma_f32_16x16x32_bf16 v[72:75], v[164:167], v[196:199], v[72:75]
	s_barrier
	s_add_i32 s54, 0, 0x1c000
	s_add_i32 s55, s70, s23
	v_add_u32_e32 v212, s54, v143
	s_mov_b32 m0, s55
	ds_read_b128 v[200:203], v212
	ds_read_b128 v[204:207], v212 offset:1024
	ds_read_b128 v[208:211], v212 offset:2048
	ds_read_b128 v[212:215], v212 offset:3072
	global_load_lds_dwordx4 v132, s[98:99]
	s_add_i32 m0, s55, 0x2000
	s_nop 0
	global_load_lds_dwordx4 v128, s[98:99]
	s_waitcnt lgkmcnt(0)
	s_barrier
	s_waitcnt lgkmcnt(0)
	v_mfma_f32_16x16x32_bf16 v[116:119], v[200:203], v[168:171], v[116:119]
	v_mfma_f32_16x16x32_bf16 v[108:111], v[208:211], v[168:171], v[108:111]
	v_mfma_f32_16x16x32_bf16 v[100:103], v[200:203], v[176:179], v[100:103]
	v_mfma_f32_16x16x32_bf16 v[92:95], v[208:211], v[176:179], v[92:95]
	v_mfma_f32_16x16x32_bf16 v[84:87], v[200:203], v[184:187], v[84:87]
	v_mfma_f32_16x16x32_bf16 v[76:79], v[208:211], v[184:187], v[76:79]
	v_mfma_f32_16x16x32_bf16 v[68:71], v[200:203], v[192:195], v[68:71]
	v_mfma_f32_16x16x32_bf16 v[64:67], v[208:211], v[192:195], v[64:67]
	v_mfma_f32_16x16x32_bf16 v[116:119], v[204:207], v[172:175], v[116:119]
	v_mfma_f32_16x16x32_bf16 v[108:111], v[212:215], v[172:175], v[108:111]
	v_mfma_f32_16x16x32_bf16 v[100:103], v[204:207], v[180:183], v[100:103]
	v_mfma_f32_16x16x32_bf16 v[92:95], v[212:215], v[180:183], v[92:95]
	v_mfma_f32_16x16x32_bf16 v[84:87], v[204:207], v[188:191], v[84:87]
	v_mfma_f32_16x16x32_bf16 v[76:79], v[212:215], v[188:191], v[76:79]
	v_mfma_f32_16x16x32_bf16 v[68:71], v[204:207], v[196:199], v[68:71]
	v_mfma_f32_16x16x32_bf16 v[64:67], v[212:215], v[196:199], v[64:67]
	s_mov_b32 m0, s49
	s_barrier
	ds_read_b128 v[168:171], v146 offset:49152
	ds_read_b128 v[172:175], v146 offset:50176
	ds_read_b128 v[176:179], v146 offset:51200
	ds_read_b128 v[180:183], v146 offset:52224
	ds_read_b128 v[184:187], v146 offset:53248
	ds_read_b128 v[188:191], v146 offset:54272
	ds_read_b128 v[192:195], v146 offset:55296
	ds_read_b128 v[196:199], v146 offset:56320
	global_load_lds_dwordx4 v134, s[100:101]
	s_mov_b32 m0, s56
	s_nop 0
	global_load_lds_dwordx4 v130, s[100:101]
	s_add_u32 s52, s52, 0x80080
	s_addc_u32 s53, s53, 0
	s_add_i32 s54, s54, s23
	s_mov_b32 m0, s54
	s_nop 0
	global_load_lds_dwordx4 v132, s[52:53]
	s_add_i32 m0, s54, 0x2000
	s_nop 0
	global_load_lds_dwordx4 v128, s[52:53]
	s_waitcnt vmcnt(6)
	s_barrier
	s_waitcnt lgkmcnt(0)
	v_mfma_f32_16x16x32_bf16 v[60:63], v[148:151], v[168:171], v[60:63]
	v_mfma_f32_16x16x32_bf16 v[56:59], v[160:163], v[168:171], v[56:59]
	v_mfma_f32_16x16x32_bf16 v[52:55], v[148:151], v[176:179], v[52:55]
	v_mfma_f32_16x16x32_bf16 v[44:47], v[160:163], v[176:179], v[44:47]
	v_mfma_f32_16x16x32_bf16 v[36:39], v[148:151], v[184:187], v[36:39]
	v_mfma_f32_16x16x32_bf16 v[28:31], v[160:163], v[184:187], v[28:31]
	v_mfma_f32_16x16x32_bf16 v[20:23], v[148:151], v[192:195], v[20:23]
	v_mfma_f32_16x16x32_bf16 v[12:15], v[160:163], v[192:195], v[12:15]
	v_mfma_f32_16x16x32_bf16 v[60:63], v[152:155], v[172:175], v[60:63]
	v_mfma_f32_16x16x32_bf16 v[56:59], v[164:167], v[172:175], v[56:59]
	v_mfma_f32_16x16x32_bf16 v[52:55], v[152:155], v[180:183], v[52:55]
	v_mfma_f32_16x16x32_bf16 v[44:47], v[164:167], v[180:183], v[44:47]
	v_mfma_f32_16x16x32_bf16 v[36:39], v[152:155], v[188:191], v[36:39]
	v_mfma_f32_16x16x32_bf16 v[28:31], v[164:167], v[188:191], v[28:31]
	v_mfma_f32_16x16x32_bf16 v[20:23], v[152:155], v[196:199], v[20:23]
	v_mfma_f32_16x16x32_bf16 v[12:15], v[164:167], v[196:199], v[12:15]
	v_mfma_f32_16x16x32_bf16 v[48:51], v[200:203], v[168:171], v[48:51]
	v_mfma_f32_16x16x32_bf16 v[40:43], v[208:211], v[168:171], v[40:43]
	v_mfma_f32_16x16x32_bf16 v[32:35], v[200:203], v[176:179], v[32:35]
	v_mfma_f32_16x16x32_bf16 v[24:27], v[208:211], v[176:179], v[24:27]
	v_mfma_f32_16x16x32_bf16 v[16:19], v[200:203], v[184:187], v[16:19]
	v_mfma_f32_16x16x32_bf16 v[8:11], v[208:211], v[184:187], v[8:11]
	v_mfma_f32_16x16x32_bf16 v[4:7], v[200:203], v[192:195], v[4:7]
	v_mfma_f32_16x16x32_bf16 v[0:3], v[208:211], v[192:195], v[0:3]
	v_mfma_f32_16x16x32_bf16 v[48:51], v[204:207], v[172:175], v[48:51]
	v_mfma_f32_16x16x32_bf16 v[40:43], v[212:215], v[172:175], v[40:43]
	v_mfma_f32_16x16x32_bf16 v[32:35], v[204:207], v[180:183], v[32:35]
	v_mfma_f32_16x16x32_bf16 v[24:27], v[212:215], v[180:183], v[24:27]
	v_mfma_f32_16x16x32_bf16 v[16:19], v[204:207], v[188:191], v[16:19]
	v_mfma_f32_16x16x32_bf16 v[8:11], v[212:215], v[188:191], v[8:11]
	v_mfma_f32_16x16x32_bf16 v[4:7], v[204:207], v[196:199], v[4:7]
	v_mfma_f32_16x16x32_bf16 v[0:3], v[212:215], v[196:199], v[0:3]
	s_add_i32 s69, s69, 2
	s_add_u32 s50, s50, 0x100
	s_addc_u32 s51, s51, 0
	s_add_u32 s67, s67, 0x100
	s_addc_u32 s68, s68, 0
	s_cmp_gt_u32 s69, 29
	s_barrier
; #define PG8_WAIT_V(n) asm volatile("s_waitcnt vmcnt(" #n ")" ::: "memory")
; #define PG8_BAR __builtin_amdgcn_s_barrier()
; __device__ __forceinline__ u32x4 pack8(f32x4 v0, f32x4 v1) { u32x4 w; w.x = cvt_pk_bf16(v0[0], v0[1]); w.y = cvt_pk_bf16(v0[2], v0[3]); w.z = cvt_pk_bf16(v1[0], v1[1]); w.w = cvt_pk_bf16(v1[2], v1[3]); return w; }
; template <class Epi>
; __device__ __forceinline__ void gemm_phase(LAS unsigned char* lds, const Gemm g, const StaticOrder& S, const Epi& E) {
;     ...
;         E(acc, cur, wr, wc, fr, fq);
;         if (!has_next) break;
; #pragma unroll
;         for (int a = 0; a < 2; ++a)
; #pragma unroll
;             for (int b = 0; b < 2; ++b)
; #pragma unroll
;                 for (int m = 0; m < 4; ++m)
; #pragma unroll
;                     for (int n = 0; n < 2; ++n) acc[a][b][m][n] = (f32x4){0.f, 0.f, 0.f, 0.f};
;         cur = nxt; cA = nA; cB = nB; ++ui;
;     }
;     PG8_WAIT_V(0);
;     if (wr == 0) PG8_BAR;
;     PG8_BAR;
;     __device__ __forceinline__ void operator()(const f32x4 (&acc)[2][2][4][2], const Unit& u, int wr, int wc, int fr, int fq) const {
;         const int row0 = u.pm * BM + wr * 64 + fr, col0 = u.pn * BM + wc * 32 + 8 * fq;
; #pragma unroll
;         for (int ai = 0; ai < 2; ++ai)
; #pragma unroll
;             for (int m = 0; m < 4; ++m) { bf16_t* rowp = O + (size_t)(row0 + ai * HALF + m * 16) * ldc + col0;
; #pragma unroll
;                 for (int bj = 0; bj < 2; ++bj) *(u32x4*)(rowp + bj * HALF) = pack8(acc[ai][bj][m][0], acc[ai][bj][m][1]); }
;     }
	s_cbranch_scc0 .LBB0_673
	v_lshl_add_u32 v148, s48, 8, v142
	v_lshl_or_b32 v140, s64, 8, v144
	v_ashrrev_i32_e32 v149, 31, v148
	v_ashrrev_i32_e32 v141, 31, v140
	v_lshlrev_b64 v[150:151], 12, v[148:149]
	v_lshl_add_u64 v[150:151], s[24:25], 0, v[150:151]
	v_lshlrev_b64 v[152:153], 1, v[140:141]
	v_lshl_add_u64 v[140:141], v[150:151], 0, v[152:153]
	v_cvt_pk_bf16_f32 v124, v124, v125
	v_cvt_pk_bf16_f32 v125, v126, v127
	v_cvt_pk_bf16_f32 v126, v120, v121
	v_cvt_pk_bf16_f32 v127, v122, v123
	global_store_dwordx4 v[140:141], v[124:127], off
	v_cvt_pk_bf16_f32 v116, v116, v117
	v_cvt_pk_bf16_f32 v117, v118, v119
	v_cvt_pk_bf16_f32 v118, v108, v109
	v_or_b32_e32 v108, 16, v148
	v_ashrrev_i32_e32 v109, 31, v108
	v_lshlrev_b64 v[108:109], 12, v[108:109]
	v_lshl_add_u64 v[108:109], s[24:25], 0, v[108:109]
	v_cvt_pk_bf16_f32 v119, v110, v111
	global_store_dwordx4 v[140:141], v[116:119], off offset:256
	s_mov_b32 s64, s40
	s_mov_b32 s48, s42
	v_lshl_add_u64 v[116:117], v[108:109], 0, v[152:153]
	v_cvt_pk_bf16_f32 v108, v112, v113
	v_cvt_pk_bf16_f32 v109, v114, v115
	v_cvt_pk_bf16_f32 v110, v104, v105
	v_cvt_pk_bf16_f32 v111, v106, v107
	global_store_dwordx4 v[116:117], v[108:111], off
	v_cvt_pk_bf16_f32 v100, v100, v101
	v_cvt_pk_bf16_f32 v101, v102, v103
	v_cvt_pk_bf16_f32 v102, v92, v93
	v_or_b32_e32 v92, 32, v148
	v_ashrrev_i32_e32 v93, 31, v92
	v_lshlrev_b64 v[92:93], 12, v[92:93]
	v_lshl_add_u64 v[92:93], s[24:25], 0, v[92:93]
	v_cvt_pk_bf16_f32 v103, v94, v95
	global_store_dwordx4 v[116:117], v[100:103], off offset:256
	s_mov_b64 s[52:53], s[46:47]
	s_mov_b64 s[50:51], s[44:45]
	v_lshl_add_u64 v[100:101], v[92:93], 0, v[152:153]
	v_cvt_pk_bf16_f32 v92, v96, v97
	v_cvt_pk_bf16_f32 v93, v98, v99
	v_cvt_pk_bf16_f32 v94, v88, v89
	v_cvt_pk_bf16_f32 v95, v90, v91
	global_store_dwordx4 v[100:101], v[92:95], off
	v_cvt_pk_bf16_f32 v84, v84, v85
	v_cvt_pk_bf16_f32 v85, v86, v87
	v_cvt_pk_bf16_f32 v86, v76, v77
	v_or_b32_e32 v76, 48, v148
	v_ashrrev_i32_e32 v77, 31, v76
	v_lshlrev_b64 v[76:77], 12, v[76:77]
	v_lshl_add_u64 v[76:77], s[24:25], 0, v[76:77]
	v_cvt_pk_bf16_f32 v87, v78, v79
	global_store_dwordx4 v[100:101], v[84:87], off offset:256
	s_nop 1
	v_lshl_add_u64 v[84:85], v[76:77], 0, v[152:153]
	v_cvt_pk_bf16_f32 v76, v80, v81
	v_cvt_pk_bf16_f32 v77, v82, v83
	v_cvt_pk_bf16_f32 v78, v72, v73
	v_cvt_pk_bf16_f32 v79, v74, v75
	global_store_dwordx4 v[84:85], v[76:79], off
	v_cvt_pk_bf16_f32 v68, v68, v69
	v_cvt_pk_bf16_f32 v69, v70, v71
	v_cvt_pk_bf16_f32 v70, v64, v65
	v_cvt_pk_bf16_f32 v71, v66, v67
	global_store_dwordx4 v[84:85], v[68:71], off offset:256
	v_cvt_pk_bf16_f32 v60, v60, v61
	v_cvt_pk_bf16_f32 v61, v62, v63
	v_cvt_pk_bf16_f32 v62, v56, v57
	v_add_co_u32_e32 v56, vcc, s60, v140
	v_lshl_add_u64 v[64:65], v[140:141], 0, s[2:3]
	s_nop 0
	v_addc_co_u32_e32 v57, vcc, 0, v141, vcc
	v_cvt_pk_bf16_f32 v63, v58, v59
	global_store_dwordx4 v[56:57], v[60:63], off
	v_cvt_pk_bf16_f32 v48, v48, v49
	v_cvt_pk_bf16_f32 v49, v50, v51
	v_cvt_pk_bf16_f32 v50, v40, v41
	v_cvt_pk_bf16_f32 v51, v42, v43
	global_store_dwordx4 v[64:65], v[48:51], off offset:256
	v_cvt_pk_bf16_f32 v40, v52, v53
	v_cvt_pk_bf16_f32 v41, v54, v55
	v_cvt_pk_bf16_f32 v42, v44, v45
	v_add_co_u32_e32 v44, vcc, s61, v140
	s_nop 0
	v_lshl_add_u64 v[48:49], v[140:141], 0, s[8:9]
	v_addc_co_u32_e32 v45, vcc, 0, v141, vcc
	v_cvt_pk_bf16_f32 v43, v46, v47
	global_store_dwordx4 v[44:45], v[40:43], off
	v_cvt_pk_bf16_f32 v32, v32, v33
	v_cvt_pk_bf16_f32 v33, v34, v35
	v_cvt_pk_bf16_f32 v34, v24, v25
	v_cvt_pk_bf16_f32 v35, v26, v27
	global_store_dwordx4 v[48:49], v[32:35], off offset:256
	v_cvt_pk_bf16_f32 v24, v36, v37
	v_cvt_pk_bf16_f32 v25, v38, v39
	v_cvt_pk_bf16_f32 v26, v28, v29
	v_add_co_u32_e32 v28, vcc, s62, v140
	s_nop 0
	v_lshl_add_u64 v[32:33], v[140:141], 0, s[30:31]
	v_addc_co_u32_e32 v29, vcc, 0, v141, vcc
	v_cvt_pk_bf16_f32 v27, v30, v31
	global_store_dwordx4 v[28:29], v[24:27], off
	v_cvt_pk_bf16_f32 v16, v16, v17
	v_cvt_pk_bf16_f32 v17, v18, v19
	v_cvt_pk_bf16_f32 v18, v8, v9
	v_cvt_pk_bf16_f32 v19, v10, v11
	global_store_dwordx4 v[32:33], v[16:19], off offset:256
	v_cvt_pk_bf16_f32 v8, v20, v21
	v_cvt_pk_bf16_f32 v9, v22, v23
	v_cvt_pk_bf16_f32 v10, v12, v13
	v_add_co_u32_e32 v12, vcc, s63, v140
	s_nop 0
	v_lshl_add_u64 v[16:17], v[140:141], 0, s[34:35]
	v_addc_co_u32_e32 v13, vcc, 0, v141, vcc
	s_and_b64 vcc, exec, s[38:39]
	v_cvt_pk_bf16_f32 v11, v14, v15
	global_store_dwordx4 v[12:13], v[8:11], off
	v_cvt_pk_bf16_f32 v4, v4, v5
	v_cvt_pk_bf16_f32 v5, v6, v7
	v_cvt_pk_bf16_f32 v6, v0, v1
	v_cvt_pk_bf16_f32 v7, v2, v3
	global_store_dwordx4 v[16:17], v[4:7], off offset:256
	s_cbranch_vccz .LBB0_670
	s_waitcnt vmcnt(0)
	s_cmpk_gt_u32 s10, 0xff
	v_readlane_b32 s62, v232, 20
	v_readlane_b32 s61, v232, 21
	s_cbranch_scc1 .LBB0_677
	s_barrier

; #define PG8_STAGE(bufoff, gbase, voff) do { _Pragma("unroll") for (int _i = 0; _i < 2; ++_i) \
;         __builtin_amdgcn_global_load_lds((const unsigned*)((const char*)(gbase) + (voff)[_i]), (LAS unsigned*)(lds + (bufoff) + ldsw + _i * 8192), 16, 0, 0); } while (0)
; #define PG8_LDA(dst, b, h) do { _Pragma("unroll") for (int m = 0; m < 4; ++m) _Pragma("unroll") for (int k = 0; k < 2; ++k) dst[m][k] = *(const LAS bf16x8*)(lds + PG8_SA(b, h) + aoff + m * 2048 + k * 1024); } while (0)
; #define PG8_LDB(dst, b, h) do { _Pragma("unroll") for (int n = 0; n < 2; ++n) _Pragma("unroll") for (int k = 0; k < 2; ++k) dst[n][k] = *(const LAS bf16x8*)(lds + PG8_SB(b, h) + boff + n * 2048 + k * 1024); } while (0)
; #define PG8_MMA(ai, bj, At, Bt) do { __builtin_amdgcn_s_setprio(1); _Pragma("unroll") for (int m = 0; m < 4; ++m) _Pragma("unroll") for (int n = 0; n < 2; ++n) _Pragma("unroll") for (int k = 0; k < 2; ++k) \
;         acc[ai][bj][m][n] = __builtin_amdgcn_mfma_f32_16x16x32_bf16(Bt[n][k], At[m][k], acc[ai][bj][m][n], 0, 0, 0); __builtin_amdgcn_s_setprio(0); } while (0)
; #define PG8_WAIT_V(n) asm volatile("s_waitcnt vmcnt(" #n ")" ::: "memory")
; #define PG8_WAIT_L(n) asm volatile("s_waitcnt lgkmcnt(" #n ")" ::: "memory")
; #define PG8_BAR __builtin_amdgcn_s_barrier()
; #define PG8_SCHED __builtin_amdgcn_sched_barrier(0)
; template <class Epi>
; __device__ __forceinline__ void gemm_phase(LAS unsigned char* lds, const Gemm g, const StaticOrder& S, const Epi& E) {
;     ...
;             const char* a1 = cA + (size_t)(t + 1) * kstep;
;             const char* a2 = last ? nA : cA + (size_t)(t + 2) * kstep; const char* b2 = last ? nB : cB + (size_t)(t + 2) * kstep;
;             const char* a3 = a2 + kstep; const char* b3 = b2 + kstep;
;             PG8_LDB(B0, 0, 0); PG8_SCHED; PG8_LDA(At, 0, 0); PG8_STAGE(PG8_SA(1, 1), a1 + hstep, voffA);
;             PG8_WAIT_L(8); PG8_BAR; PG8_WAIT_L(0); PG8_MMA(0, 0, At, B0); PG8_BAR; PG8_SCHED;
;             PG8_LDB(B1, 0, 1); PG8_STAGE(PG8_SB(0, 0), b2, voffB);
;             PG8_BAR; PG8_WAIT_L(0); PG8_MMA(0, 1, At, B1); PG8_BAR;
;             PG8_LDA(At, 0, 1); PG8_STAGE(PG8_SA(0, 0), a2, voffA);
;             PG8_BAR; PG8_WAIT_L(0); PG8_MMA(1, 0, At, B0); PG8_BAR; PG8_SCHED;
;             PG8_STAGE(PG8_SB(0, 1), b2 + hstep, voffB);
;             PG8_WAIT_V(6); PG8_BAR; PG8_MMA(1, 1, At, B1); PG8_BAR;
.LBB0_796:
	ds_read_b128 v[144:147], v155
	ds_read_b128 v[148:151], v155 offset:1024
	ds_read_b128 v[160:163], v155 offset:2048
	ds_read_b128 v[164:167], v155 offset:3072
	s_add_u32 s42, s40, 0xfff80080
	s_addc_u32 s43, s41, -1
	s_cmp_eq_u32 s58, 28
	s_cselect_b32 s45, s31, s43
	s_cselect_b32 s44, s54, s42
	s_cselect_b32 s43, s9, s57
	s_cselect_b32 s42, s55, s56
	s_add_i32 m0, s27, 0xc000
	ds_read_b128 v[168:171], v156
	ds_read_b128 v[172:175], v156 offset:1024
	ds_read_b128 v[176:179], v156 offset:2048
	ds_read_b128 v[180:183], v156 offset:3072
	ds_read_b128 v[184:187], v156 offset:4096
	ds_read_b128 v[188:191], v156 offset:5120
	ds_read_b128 v[192:195], v156 offset:6144
	ds_read_b128 v[196:199], v156 offset:7168
	global_load_lds_dwordx4 v136, s[40:41]
	s_add_i32 m0, s27, 0xe000
	s_nop 0
	global_load_lds_dwordx4 v138, s[40:41]
	s_waitcnt lgkmcnt(8)
	s_barrier
	s_waitcnt lgkmcnt(0)
	v_mfma_f32_16x16x32_bf16 v[124:127], v[144:147], v[168:171], v[124:127]
	v_mfma_f32_16x16x32_bf16 v[120:123], v[160:163], v[168:171], v[120:123]
	v_mfma_f32_16x16x32_bf16 v[108:111], v[144:147], v[176:179], v[108:111]
	v_mfma_f32_16x16x32_bf16 v[104:107], v[160:163], v[176:179], v[104:107]
	v_mfma_f32_16x16x32_bf16 v[92:95], v[144:147], v[184:187], v[92:95]
	v_mfma_f32_16x16x32_bf16 v[88:91], v[160:163], v[184:187], v[88:91]
	v_mfma_f32_16x16x32_bf16 v[76:79], v[144:147], v[192:195], v[76:79]
	v_mfma_f32_16x16x32_bf16 v[72:75], v[160:163], v[192:195], v[72:75]
	v_mfma_f32_16x16x32_bf16 v[124:127], v[148:151], v[172:175], v[124:127]
	v_mfma_f32_16x16x32_bf16 v[120:123], v[164:167], v[172:175], v[120:123]
	v_mfma_f32_16x16x32_bf16 v[108:111], v[148:151], v[180:183], v[108:111]
	v_mfma_f32_16x16x32_bf16 v[104:107], v[164:167], v[180:183], v[104:107]
	v_mfma_f32_16x16x32_bf16 v[92:95], v[148:151], v[188:191], v[92:95]
	v_mfma_f32_16x16x32_bf16 v[88:91], v[164:167], v[188:191], v[88:91]
	v_mfma_f32_16x16x32_bf16 v[76:79], v[148:151], v[196:199], v[76:79]
	v_mfma_f32_16x16x32_bf16 v[72:75], v[164:167], v[196:199], v[72:75]
	s_barrier
	s_add_i32 s59, s50, s23
	s_add_u32 s98, s42, s2
	s_addc_u32 s99, s43, s3
	s_mov_b32 m0, s59
	ds_read_b128 v[200:203], v157
	ds_read_b128 v[204:207], v157 offset:1024
	ds_read_b128 v[208:211], v157 offset:2048
	ds_read_b128 v[212:215], v157 offset:3072
	global_load_lds_dwordx4 v132, s[42:43]
	s_add_i32 m0, s59, 0x2000
	s_nop 0
	global_load_lds_dwordx4 v128, s[42:43]
	s_waitcnt lgkmcnt(0)
	s_barrier
	s_waitcnt lgkmcnt(0)
	v_mfma_f32_16x16x32_bf16 v[116:119], v[200:203], v[168:171], v[116:119]
	v_mfma_f32_16x16x32_bf16 v[112:115], v[208:211], v[168:171], v[112:115]
	v_mfma_f32_16x16x32_bf16 v[100:103], v[200:203], v[176:179], v[100:103]
	v_mfma_f32_16x16x32_bf16 v[96:99], v[208:211], v[176:179], v[96:99]
	v_mfma_f32_16x16x32_bf16 v[84:87], v[200:203], v[184:187], v[84:87]
	v_mfma_f32_16x16x32_bf16 v[80:83], v[208:211], v[184:187], v[80:83]
	v_mfma_f32_16x16x32_bf16 v[68:71], v[200:203], v[192:195], v[68:71]
	v_mfma_f32_16x16x32_bf16 v[64:67], v[208:211], v[192:195], v[64:67]
	v_mfma_f32_16x16x32_bf16 v[116:119], v[204:207], v[172:175], v[116:119]
	v_mfma_f32_16x16x32_bf16 v[112:115], v[212:215], v[172:175], v[112:115]
	v_mfma_f32_16x16x32_bf16 v[100:103], v[204:207], v[180:183], v[100:103]
	v_mfma_f32_16x16x32_bf16 v[96:99], v[212:215], v[180:183], v[96:99]
	v_mfma_f32_16x16x32_bf16 v[84:87], v[204:207], v[188:191], v[84:87]
	v_mfma_f32_16x16x32_bf16 v[80:83], v[212:215], v[188:191], v[80:83]
	v_mfma_f32_16x16x32_bf16 v[68:71], v[204:207], v[196:199], v[68:71]
	v_mfma_f32_16x16x32_bf16 v[64:67], v[212:215], v[196:199], v[64:67]
	s_mov_b32 m0, s27
	s_add_u32 s100, s44, s2
	s_addc_u32 s101, s45, s3
	s_barrier
	ds_read_b128 v[168:171], v156 offset:16384
	ds_read_b128 v[172:175], v156 offset:17408
	ds_read_b128 v[176:179], v156 offset:18432
	ds_read_b128 v[180:183], v156 offset:19456
	ds_read_b128 v[184:187], v156 offset:20480
	ds_read_b128 v[188:191], v156 offset:21504
	ds_read_b128 v[192:195], v156 offset:22528
	ds_read_b128 v[196:199], v156 offset:23552
	global_load_lds_dwordx4 v134, s[44:45]
	s_mov_b32 m0, s28
	s_nop 0
	global_load_lds_dwordx4 v130, s[44:45]
	s_add_u32 s60, s42, 0x80000
	s_addc_u32 s61, s43, 0
	s_add_i32 s59, s51, s23
	s_mov_b32 m0, s59
	s_nop 0
	global_load_lds_dwordx4 v132, s[60:61]
	s_add_i32 m0, s59, 0x2000
	s_nop 0
	global_load_lds_dwordx4 v128, s[60:61]
	s_waitcnt vmcnt(6)
	s_barrier
	s_waitcnt lgkmcnt(0)
	v_mfma_f32_16x16x32_bf16 v[60:63], v[144:147], v[168:171], v[60:63]
	v_mfma_f32_16x16x32_bf16 v[56:59], v[160:163], v[168:171], v[56:59]
	v_mfma_f32_16x16x32_bf16 v[44:47], v[144:147], v[176:179], v[44:47]
	v_mfma_f32_16x16x32_bf16 v[40:43], v[160:163], v[176:179], v[40:43]
	v_mfma_f32_16x16x32_bf16 v[28:31], v[144:147], v[184:187], v[28:31]
	v_mfma_f32_16x16x32_bf16 v[24:27], v[160:163], v[184:187], v[24:27]
	v_mfma_f32_16x16x32_bf16 v[12:15], v[144:147], v[192:195], v[12:15]
	v_mfma_f32_16x16x32_bf16 v[8:11], v[160:163], v[192:195], v[8:11]
	v_mfma_f32_16x16x32_bf16 v[60:63], v[148:151], v[172:175], v[60:63]
	v_mfma_f32_16x16x32_bf16 v[56:59], v[164:167], v[172:175], v[56:59]
	v_mfma_f32_16x16x32_bf16 v[44:47], v[148:151], v[180:183], v[44:47]
	v_mfma_f32_16x16x32_bf16 v[40:43], v[164:167], v[180:183], v[40:43]
	v_mfma_f32_16x16x32_bf16 v[28:31], v[148:151], v[188:191], v[28:31]
	v_mfma_f32_16x16x32_bf16 v[24:27], v[164:167], v[188:191], v[24:27]
	v_mfma_f32_16x16x32_bf16 v[12:15], v[148:151], v[196:199], v[12:15]
	v_mfma_f32_16x16x32_bf16 v[8:11], v[164:167], v[196:199], v[8:11]
	v_mfma_f32_16x16x32_bf16 v[52:55], v[200:203], v[168:171], v[52:55]
	v_mfma_f32_16x16x32_bf16 v[48:51], v[208:211], v[168:171], v[48:51]
	v_mfma_f32_16x16x32_bf16 v[36:39], v[200:203], v[176:179], v[36:39]
	v_mfma_f32_16x16x32_bf16 v[32:35], v[208:211], v[176:179], v[32:35]
	v_mfma_f32_16x16x32_bf16 v[20:23], v[200:203], v[184:187], v[20:23]
	v_mfma_f32_16x16x32_bf16 v[16:19], v[208:211], v[184:187], v[16:19]
	v_mfma_f32_16x16x32_bf16 v[4:7], v[200:203], v[192:195], v[4:7]
	v_mfma_f32_16x16x32_bf16 v[0:3], v[208:211], v[192:195], v[0:3]
	v_mfma_f32_16x16x32_bf16 v[52:55], v[204:207], v[172:175], v[52:55]
	v_mfma_f32_16x16x32_bf16 v[48:51], v[212:215], v[172:175], v[48:51]
	v_mfma_f32_16x16x32_bf16 v[36:39], v[204:207], v[180:183], v[36:39]
	v_mfma_f32_16x16x32_bf16 v[32:35], v[212:215], v[180:183], v[32:35]
	v_mfma_f32_16x16x32_bf16 v[20:23], v[204:207], v[188:191], v[20:23]
	v_mfma_f32_16x16x32_bf16 v[16:19], v[212:215], v[188:191], v[16:19]
	v_mfma_f32_16x16x32_bf16 v[4:7], v[204:207], v[196:199], v[4:7]
	v_mfma_f32_16x16x32_bf16 v[0:3], v[212:215], v[196:199], v[0:3]
	s_add_i32 s59, 0, 0x18000
	v_add_u32_e32 v164, s59, v153
	s_barrier
; #define PG8_STAGE(bufoff, gbase, voff) do { _Pragma("unroll") for (int _i = 0; _i < 2; ++_i) \
;         __builtin_amdgcn_global_load_lds((const unsigned*)((const char*)(gbase) + (voff)[_i]), (LAS unsigned*)(lds + (bufoff) + ldsw + _i * 8192), 16, 0, 0); } while (0)
; #define PG8_LDA(dst, b, h) do { _Pragma("unroll") for (int m = 0; m < 4; ++m) _Pragma("unroll") for (int k = 0; k < 2; ++k) dst[m][k] = *(const LAS bf16x8*)(lds + PG8_SA(b, h) + aoff + m * 2048 + k * 1024); } while (0)
; #define PG8_LDB(dst, b, h) do { _Pragma("unroll") for (int n = 0; n < 2; ++n) _Pragma("unroll") for (int k = 0; k < 2; ++k) dst[n][k] = *(const LAS bf16x8*)(lds + PG8_SB(b, h) + boff + n * 2048 + k * 1024); } while (0)
; #define PG8_MMA(ai, bj, At, Bt) do { __builtin_amdgcn_s_setprio(1); _Pragma("unroll") for (int m = 0; m < 4; ++m) _Pragma("unroll") for (int n = 0; n < 2; ++n) _Pragma("unroll") for (int k = 0; k < 2; ++k) \
;         acc[ai][bj][m][n] = __builtin_amdgcn_mfma_f32_16x16x32_bf16(Bt[n][k], At[m][k], acc[ai][bj][m][n], 0, 0, 0); __builtin_amdgcn_s_setprio(0); } while (0)
; #define PG8_WAIT_V(n) asm volatile("s_waitcnt vmcnt(" #n ")" ::: "memory")
; #define PG8_WAIT_L(n) asm volatile("s_waitcnt lgkmcnt(" #n ")" ::: "memory")
; #define PG8_BAR __builtin_amdgcn_s_barrier()
; #define PG8_SCHED __builtin_amdgcn_sched_barrier(0)
; template <class Epi>
; __device__ __forceinline__ void gemm_phase(LAS unsigned char* lds, const Gemm g, const StaticOrder& S, const Epi& E) {
;     ...
;             PG8_LDB(B0, 1, 0); PG8_SCHED; PG8_LDA(At, 1, 0); PG8_STAGE(PG8_SA(0, 1), a2 + hstep, voffA);
;             PG8_WAIT_L(8); PG8_BAR; PG8_WAIT_L(0); PG8_MMA(0, 0, At, B0); PG8_BAR; PG8_SCHED;
;             PG8_LDB(B1, 1, 1); PG8_STAGE(PG8_SB(1, 0), b3, voffB);
;             PG8_BAR; PG8_WAIT_L(0); PG8_MMA(0, 1, At, B1); PG8_BAR;
;             PG8_LDA(At, 1, 1); PG8_STAGE(PG8_SA(1, 0), a3, voffA);
;             PG8_BAR; PG8_WAIT_L(0); PG8_MMA(1, 0, At, B0); PG8_BAR; PG8_SCHED;
;             PG8_STAGE(PG8_SB(1, 1), b3 + hstep, voffB);
;             PG8_WAIT_V(6); PG8_BAR; PG8_MMA(1, 1, At, B1); PG8_BAR;
;         }
	ds_read_b128 v[144:147], v164
	ds_read_b128 v[148:151], v164 offset:1024
	ds_read_b128 v[160:163], v164 offset:2048
	ds_read_b128 v[164:167], v164 offset:3072
	s_add_u32 s44, s44, 0x80000
	s_addc_u32 s45, s45, 0
	s_mov_b32 m0, s29
	ds_read_b128 v[168:171], v156 offset:32768
	ds_read_b128 v[172:175], v156 offset:33792
	ds_read_b128 v[176:179], v156 offset:34816
	ds_read_b128 v[180:183], v156 offset:35840
	ds_read_b128 v[184:187], v156 offset:36864
	ds_read_b128 v[188:191], v156 offset:37888
	ds_read_b128 v[192:195], v156 offset:38912
	ds_read_b128 v[196:199], v156 offset:39936
	global_load_lds_dwordx4 v134, s[44:45]
	s_mov_b32 m0, s33
	s_nop 0
	global_load_lds_dwordx4 v130, s[44:45]
	s_waitcnt lgkmcnt(8)
	s_barrier
	s_waitcnt lgkmcnt(0)
	v_mfma_f32_16x16x32_bf16 v[124:127], v[144:147], v[168:171], v[124:127]
	v_mfma_f32_16x16x32_bf16 v[120:123], v[160:163], v[168:171], v[120:123]
	v_mfma_f32_16x16x32_bf16 v[108:111], v[144:147], v[176:179], v[108:111]
	v_mfma_f32_16x16x32_bf16 v[104:107], v[160:163], v[176:179], v[104:107]
	v_mfma_f32_16x16x32_bf16 v[92:95], v[144:147], v[184:187], v[92:95]
	v_mfma_f32_16x16x32_bf16 v[88:91], v[160:163], v[184:187], v[88:91]
	v_mfma_f32_16x16x32_bf16 v[76:79], v[144:147], v[192:195], v[76:79]
	v_mfma_f32_16x16x32_bf16 v[72:75], v[160:163], v[192:195], v[72:75]
	v_mfma_f32_16x16x32_bf16 v[124:127], v[148:151], v[172:175], v[124:127]
	v_mfma_f32_16x16x32_bf16 v[120:123], v[164:167], v[172:175], v[120:123]
	v_mfma_f32_16x16x32_bf16 v[108:111], v[148:151], v[180:183], v[108:111]
	v_mfma_f32_16x16x32_bf16 v[104:107], v[164:167], v[180:183], v[104:107]
	v_mfma_f32_16x16x32_bf16 v[92:95], v[148:151], v[188:191], v[92:95]
	v_mfma_f32_16x16x32_bf16 v[88:91], v[164:167], v[188:191], v[88:91]
	v_mfma_f32_16x16x32_bf16 v[76:79], v[148:151], v[196:199], v[76:79]
	v_mfma_f32_16x16x32_bf16 v[72:75], v[164:167], v[196:199], v[72:75]
	s_barrier
	s_add_i32 s44, 0, 0x1c000
	s_add_i32 s45, s59, s23
	v_add_u32_e32 v212, s44, v153
	s_mov_b32 m0, s45
	ds_read_b128 v[200:203], v212
	ds_read_b128 v[204:207], v212 offset:1024
	ds_read_b128 v[208:211], v212 offset:2048
	ds_read_b128 v[212:215], v212 offset:3072
	global_load_lds_dwordx4 v132, s[98:99]
	s_add_i32 m0, s45, 0x2000
	s_nop 0
	global_load_lds_dwordx4 v128, s[98:99]
	s_waitcnt lgkmcnt(0)
	s_barrier
	s_waitcnt lgkmcnt(0)
	v_mfma_f32_16x16x32_bf16 v[116:119], v[200:203], v[168:171], v[116:119]
	v_mfma_f32_16x16x32_bf16 v[112:115], v[208:211], v[168:171], v[112:115]
	v_mfma_f32_16x16x32_bf16 v[100:103], v[200:203], v[176:179], v[100:103]
	v_mfma_f32_16x16x32_bf16 v[96:99], v[208:211], v[176:179], v[96:99]
	v_mfma_f32_16x16x32_bf16 v[84:87], v[200:203], v[184:187], v[84:87]
	v_mfma_f32_16x16x32_bf16 v[80:83], v[208:211], v[184:187], v[80:83]
	v_mfma_f32_16x16x32_bf16 v[68:71], v[200:203], v[192:195], v[68:71]
	v_mfma_f32_16x16x32_bf16 v[64:67], v[208:211], v[192:195], v[64:67]
	v_mfma_f32_16x16x32_bf16 v[116:119], v[204:207], v[172:175], v[116:119]
	v_mfma_f32_16x16x32_bf16 v[112:115], v[212:215], v[172:175], v[112:115]
	v_mfma_f32_16x16x32_bf16 v[100:103], v[204:207], v[180:183], v[100:103]
	v_mfma_f32_16x16x32_bf16 v[96:99], v[212:215], v[180:183], v[96:99]
	v_mfma_f32_16x16x32_bf16 v[84:87], v[204:207], v[188:191], v[84:87]
	v_mfma_f32_16x16x32_bf16 v[80:83], v[212:215], v[188:191], v[80:83]
	v_mfma_f32_16x16x32_bf16 v[68:71], v[204:207], v[196:199], v[68:71]
	v_mfma_f32_16x16x32_bf16 v[64:67], v[212:215], v[196:199], v[64:67]
	s_mov_b32 m0, s46
	s_barrier
	ds_read_b128 v[168:171], v156 offset:49152
	ds_read_b128 v[172:175], v156 offset:50176
	ds_read_b128 v[176:179], v156 offset:51200
	ds_read_b128 v[180:183], v156 offset:52224
	ds_read_b128 v[184:187], v156 offset:53248
	ds_read_b128 v[188:191], v156 offset:54272
	ds_read_b128 v[192:195], v156 offset:55296
	ds_read_b128 v[196:199], v156 offset:56320
	global_load_lds_dwordx4 v134, s[100:101]
	s_mov_b32 m0, s47
	s_nop 0
	global_load_lds_dwordx4 v130, s[100:101]
	s_add_u32 s42, s42, 0x80080
	s_addc_u32 s43, s43, 0
	s_add_i32 s44, s44, s23
	s_mov_b32 m0, s44
	s_nop 0
	global_load_lds_dwordx4 v132, s[42:43]
	s_add_i32 m0, s44, 0x2000
	s_nop 0
	global_load_lds_dwordx4 v128, s[42:43]
	s_waitcnt vmcnt(6)
	s_barrier
	s_waitcnt lgkmcnt(0)
	v_mfma_f32_16x16x32_bf16 v[60:63], v[144:147], v[168:171], v[60:63]
	v_mfma_f32_16x16x32_bf16 v[56:59], v[160:163], v[168:171], v[56:59]
	v_mfma_f32_16x16x32_bf16 v[44:47], v[144:147], v[176:179], v[44:47]
	v_mfma_f32_16x16x32_bf16 v[40:43], v[160:163], v[176:179], v[40:43]
	v_mfma_f32_16x16x32_bf16 v[28:31], v[144:147], v[184:187], v[28:31]
	v_mfma_f32_16x16x32_bf16 v[24:27], v[160:163], v[184:187], v[24:27]
	v_mfma_f32_16x16x32_bf16 v[12:15], v[144:147], v[192:195], v[12:15]
	v_mfma_f32_16x16x32_bf16 v[8:11], v[160:163], v[192:195], v[8:11]
	v_mfma_f32_16x16x32_bf16 v[60:63], v[148:151], v[172:175], v[60:63]
	v_mfma_f32_16x16x32_bf16 v[56:59], v[164:167], v[172:175], v[56:59]
	v_mfma_f32_16x16x32_bf16 v[44:47], v[148:151], v[180:183], v[44:47]
	v_mfma_f32_16x16x32_bf16 v[40:43], v[164:167], v[180:183], v[40:43]
	v_mfma_f32_16x16x32_bf16 v[28:31], v[148:151], v[188:191], v[28:31]
	v_mfma_f32_16x16x32_bf16 v[24:27], v[164:167], v[188:191], v[24:27]
	v_mfma_f32_16x16x32_bf16 v[12:15], v[148:151], v[196:199], v[12:15]
	v_mfma_f32_16x16x32_bf16 v[8:11], v[164:167], v[196:199], v[8:11]
	v_mfma_f32_16x16x32_bf16 v[52:55], v[200:203], v[168:171], v[52:55]
	v_mfma_f32_16x16x32_bf16 v[48:51], v[208:211], v[168:171], v[48:51]
	v_mfma_f32_16x16x32_bf16 v[36:39], v[200:203], v[176:179], v[36:39]
	v_mfma_f32_16x16x32_bf16 v[32:35], v[208:211], v[176:179], v[32:35]
	v_mfma_f32_16x16x32_bf16 v[20:23], v[200:203], v[184:187], v[20:23]
	v_mfma_f32_16x16x32_bf16 v[16:19], v[208:211], v[184:187], v[16:19]
	v_mfma_f32_16x16x32_bf16 v[4:7], v[200:203], v[192:195], v[4:7]
	v_mfma_f32_16x16x32_bf16 v[0:3], v[208:211], v[192:195], v[0:3]
	v_mfma_f32_16x16x32_bf16 v[52:55], v[204:207], v[172:175], v[52:55]
	v_mfma_f32_16x16x32_bf16 v[48:51], v[212:215], v[172:175], v[48:51]
	v_mfma_f32_16x16x32_bf16 v[36:39], v[204:207], v[180:183], v[36:39]
	v_mfma_f32_16x16x32_bf16 v[32:35], v[212:215], v[180:183], v[32:35]
	v_mfma_f32_16x16x32_bf16 v[20:23], v[204:207], v[188:191], v[20:23]
	v_mfma_f32_16x16x32_bf16 v[16:19], v[212:215], v[188:191], v[16:19]
	v_mfma_f32_16x16x32_bf16 v[4:7], v[204:207], v[196:199], v[4:7]
	v_mfma_f32_16x16x32_bf16 v[0:3], v[212:215], v[196:199], v[0:3]
	s_add_i32 s58, s58, 2
	s_add_u32 s40, s40, 0x100
	s_addc_u32 s41, s41, 0
	s_add_u32 s56, s56, 0x100
	s_addc_u32 s57, s57, 0
	s_cmp_gt_u32 s58, 29
	s_barrier
; __device__ __forceinline__ float fast_rcp(float x) { return __builtin_amdgcn_rcpf(x); }
; __device__ __forceinline__ float fast_exp2(float x) { return __builtin_amdgcn_exp2f(x); }
; __device__ __forceinline__ u32x4 pack8(f32x4 v0, f32x4 v1) { u32x4 w; w.x = cvt_pk_bf16(v0[0], v0[1]); w.y = cvt_pk_bf16(v0[2], v0[3]); w.z = cvt_pk_bf16(v1[0], v1[1]); w.w = cvt_pk_bf16(v1[2], v1[3]); return w; }
;     __device__ __forceinline__ void operator()(const f32x4 (&acc)[2][2][4][2], const Unit& u, int wr, int wc, int fr, int fq) const {
;         const int row0 = u.pm * BM + wr * 64 + fr, col0 = u.pn * HALF + wc * 32 + 8 * fq;
; #pragma unroll
;         for (int ai = 0; ai < 2; ++ai)
; #pragma unroll
;             for (int m = 0; m < 4; ++m) { bf16_t* rowp = O + (size_t)(row0 + ai * HALF + m * 16) * DFF + col0;
;                 const float r = rs[row0 + ai * HALF + m * 16], r2 = r * r;
;                 f32x4 h0, h1;
; #pragma unroll
;                 for (int j = 0; j < 4; ++j) {
;                     const float g0 = acc[ai][0][m][0][j], g1 = acc[ai][0][m][1][j];
;                     h0[j] = g0 * r2 * fast_rcp(1.0f + fast_exp2(g0 * (-LOG2E * r))) * acc[ai][1][m][0][j];
;                     h1[j] = g1 * r2 * fast_rcp(1.0f + fast_exp2(g1 * (-LOG2E * r))) * acc[ai][1][m][1][j]; }
;                 *(u32x4*)rowp = pack8(h0, h1); }
;     }
	s_cbranch_scc0 .LBB0_796
	v_lshl_add_u32 v144, s38, 8, v152
	v_ashrrev_i32_e32 v145, 31, v144
	v_lshl_add_u64 v[150:151], v[144:145], 2, s[14:15]
	v_mov_b32_e32 v145, v224
	v_mov_b32_e32 v204, v225
	v_mov_b32_e32 v205, v226
	v_mov_b32_e32 v206, v227
	v_mov_b32_e32 v207, v228
	v_mov_b32_e32 v208, v229
	v_mov_b32_e32 v209, v230
	v_mov_b32_e32 v210, v231
	v_lshl_or_b32 v148, s53, 7, v154
	v_mov_b64_e32 v[146:147], s[20:21]
	v_ashrrev_i32_e32 v149, 31, v148
	v_mad_i64_i32 v[160:161], s[40:41], v144, s52, v[146:147]
	v_lshlrev_b64 v[148:149], 1, v[148:149]
	v_lshl_add_u64 v[160:161], v[160:161], 0, v[148:149]
	s_and_b64 vcc, exec, s[6:7]
	s_mov_b32 s53, s8
	s_mov_b32 s38, s30
	s_mov_b64 s[42:43], s[36:37]
	v_mul_f32_e32 v162, v145, v145
	v_mul_f32_e32 v145, 0xbfb8aa3b, v145
	v_mul_f32_e32 v163, v124, v162
	v_mul_f32_e32 v164, v120, v162
	v_mul_f32_e32 v120, v120, v145
	v_mul_f32_e32 v165, v125, v162
	v_mul_f32_e32 v125, v125, v145
	v_mul_f32_e32 v166, v121, v162
	v_mul_f32_e32 v121, v121, v145
	v_mul_f32_e32 v167, v126, v162
	v_mul_f32_e32 v126, v126, v145
	v_mul_f32_e32 v168, v122, v162
	v_mul_f32_e32 v122, v122, v145
	v_mul_f32_e32 v169, v127, v162
	v_mul_f32_e32 v127, v127, v145
	v_mul_f32_e32 v162, v123, v162
	v_mul_f32_e32 v123, v123, v145
	v_mul_f32_e32 v124, v124, v145
	v_exp_f32_e32 v120, v120
	v_exp_f32_e32 v125, v125
	v_exp_f32_e32 v121, v121
	v_exp_f32_e32 v126, v126
	v_exp_f32_e32 v122, v122
	v_exp_f32_e32 v127, v127
	v_exp_f32_e32 v123, v123
	v_exp_f32_e32 v124, v124
	v_add_f32_e32 v120, 1.0, v120
	v_add_f32_e32 v125, 1.0, v125
	v_add_f32_e32 v121, 1.0, v121
	v_add_f32_e32 v126, 1.0, v126
	v_add_f32_e32 v122, 1.0, v122
	v_add_f32_e32 v127, 1.0, v127
	v_add_f32_e32 v123, 1.0, v123
	v_add_f32_e32 v124, 1.0, v124
	v_rcp_f32_e32 v120, v120
	v_rcp_f32_e32 v125, v125
	v_rcp_f32_e32 v121, v121
	v_rcp_f32_e32 v126, v126
	v_rcp_f32_e32 v122, v122
	v_rcp_f32_e32 v127, v127
	v_rcp_f32_e32 v123, v123
	v_rcp_f32_e32 v124, v124
	v_mul_f32_e32 v120, v164, v120
	v_mul_f32_e32 v125, v165, v125
	v_mul_f32_e32 v121, v166, v121
	v_mul_f32_e32 v126, v167, v126
	v_mul_f32_e32 v122, v168, v122
	v_mul_f32_e32 v127, v169, v127
	v_mul_f32_e32 v123, v162, v123
	v_mul_f32_e32 v124, v163, v124
	v_mul_f32_e32 v120, v112, v120
	v_mul_f32_e32 v112, v117, v125
	v_mul_f32_e32 v117, v113, v121
	v_mul_f32_e32 v113, v118, v126
	v_mul_f32_e32 v118, v114, v122
	v_mul_f32_e32 v114, v119, v127
	v_mul_f32_e32 v115, v115, v123
	v_mul_f32_e32 v116, v116, v124
	v_cvt_pk_bf16_f32 v112, v116, v112
	v_cvt_pk_bf16_f32 v113, v113, v114
	v_cvt_pk_bf16_f32 v114, v120, v117
	v_cvt_pk_bf16_f32 v115, v118, v115
	global_store_dwordx4 v[160:161], v[112:115], off
	s_nop 1
	v_mov_b32_e32 v114, v204
	s_nop 0
	v_or_b32_e32 v112, 16, v144
	v_mad_i64_i32 v[112:113], s[40:41], v112, s52, v[146:147]
	v_lshl_add_u64 v[112:113], v[112:113], 0, v[148:149]
	v_mul_f32_e32 v115, v114, v114
	v_mul_f32_e32 v114, 0xbfb8aa3b, v114
	v_mul_f32_e32 v116, v108, v115
	v_mul_f32_e32 v117, v104, v115
	v_mul_f32_e32 v104, v104, v114
	v_mul_f32_e32 v118, v109, v115
	v_mul_f32_e32 v109, v109, v114
	v_mul_f32_e32 v119, v105, v115
	v_mul_f32_e32 v105, v105, v114
	v_mul_f32_e32 v120, v110, v115
	v_mul_f32_e32 v110, v110, v114
	v_mul_f32_e32 v121, v106, v115
	v_mul_f32_e32 v106, v106, v114
	v_mul_f32_e32 v122, v111, v115
	v_mul_f32_e32 v111, v111, v114
	v_mul_f32_e32 v115, v107, v115
	v_mul_f32_e32 v107, v107, v114
	v_mul_f32_e32 v108, v108, v114
	v_exp_f32_e32 v104, v104
	v_exp_f32_e32 v109, v109
	v_exp_f32_e32 v105, v105
	v_exp_f32_e32 v110, v110
	v_exp_f32_e32 v106, v106
	v_exp_f32_e32 v111, v111
	v_exp_f32_e32 v107, v107
	v_exp_f32_e32 v108, v108
	v_add_f32_e32 v104, 1.0, v104
	v_add_f32_e32 v109, 1.0, v109
	v_add_f32_e32 v105, 1.0, v105
	v_add_f32_e32 v110, 1.0, v110
	v_add_f32_e32 v106, 1.0, v106
	v_add_f32_e32 v111, 1.0, v111
	v_add_f32_e32 v107, 1.0, v107
	v_add_f32_e32 v108, 1.0, v108
	v_rcp_f32_e32 v104, v104
	v_rcp_f32_e32 v109, v109
	v_rcp_f32_e32 v105, v105
	v_rcp_f32_e32 v110, v110
	v_rcp_f32_e32 v106, v106
	v_rcp_f32_e32 v111, v111
	v_rcp_f32_e32 v107, v107
	v_rcp_f32_e32 v108, v108
	v_mul_f32_e32 v104, v117, v104
	v_mul_f32_e32 v109, v118, v109
	v_mul_f32_e32 v105, v119, v105
	v_mul_f32_e32 v110, v120, v110
	v_mul_f32_e32 v106, v121, v106
	v_mul_f32_e32 v111, v122, v111
	v_mul_f32_e32 v107, v115, v107
	v_mul_f32_e32 v108, v116, v108
	v_mul_f32_e32 v104, v96, v104
	v_mul_f32_e32 v96, v101, v109
	v_mul_f32_e32 v101, v97, v105
	v_mul_f32_e32 v97, v102, v110
	v_mul_f32_e32 v102, v98, v106
	v_mul_f32_e32 v98, v103, v111
	v_mul_f32_e32 v99, v99, v107
	v_mul_f32_e32 v100, v100, v108
	v_cvt_pk_bf16_f32 v96, v100, v96
	v_cvt_pk_bf16_f32 v97, v97, v98
	v_cvt_pk_bf16_f32 v98, v104, v101
	v_cvt_pk_bf16_f32 v99, v102, v99
	global_store_dwordx4 v[112:113], v[96:99], off
	s_nop 1
	v_mov_b32_e32 v98, v205
	s_nop 0
	v_or_b32_e32 v96, 32, v144
	v_mad_i64_i32 v[96:97], s[40:41], v96, s52, v[146:147]
	v_lshl_add_u64 v[96:97], v[96:97], 0, v[148:149]
	v_mul_f32_e32 v99, v98, v98
	v_mul_f32_e32 v98, 0xbfb8aa3b, v98
	v_mul_f32_e32 v100, v92, v99
	v_mul_f32_e32 v101, v88, v99
	v_mul_f32_e32 v88, v88, v98
	v_mul_f32_e32 v102, v93, v99
	v_mul_f32_e32 v93, v93, v98
	v_mul_f32_e32 v103, v89, v99
	v_mul_f32_e32 v89, v89, v98
	v_mul_f32_e32 v104, v94, v99
	v_mul_f32_e32 v94, v94, v98
	v_mul_f32_e32 v105, v90, v99
	v_mul_f32_e32 v90, v90, v98
	v_mul_f32_e32 v106, v95, v99
	v_mul_f32_e32 v95, v95, v98
	v_mul_f32_e32 v99, v91, v99
	v_mul_f32_e32 v91, v91, v98
	v_mul_f32_e32 v92, v92, v98
	v_exp_f32_e32 v88, v88
	v_exp_f32_e32 v93, v93
	v_exp_f32_e32 v89, v89
	v_exp_f32_e32 v94, v94
	v_exp_f32_e32 v90, v90
	v_exp_f32_e32 v95, v95
; __device__ __forceinline__ float fast_rcp(float x) { return __builtin_amdgcn_rcpf(x); }
; __device__ __forceinline__ float fast_exp2(float x) { return __builtin_amdgcn_exp2f(x); }
; __device__ __forceinline__ u32x4 pack8(f32x4 v0, f32x4 v1) { u32x4 w; w.x = cvt_pk_bf16(v0[0], v0[1]); w.y = cvt_pk_bf16(v0[2], v0[3]); w.z = cvt_pk_bf16(v1[0], v1[1]); w.w = cvt_pk_bf16(v1[2], v1[3]); return w; }
;     __device__ __forceinline__ void operator()(const f32x4 (&acc)[2][2][4][2], const Unit& u, int wr, int wc, int fr, int fq) const {
;         const int row0 = u.pm * BM + wr * 64 + fr, col0 = u.pn * HALF + wc * 32 + 8 * fq;
; #pragma unroll
;         for (int ai = 0; ai < 2; ++ai)
; #pragma unroll
;             for (int m = 0; m < 4; ++m) { bf16_t* rowp = O + (size_t)(row0 + ai * HALF + m * 16) * DFF + col0;
;                 const float r = rs[row0 + ai * HALF + m * 16], r2 = r * r;
;                 f32x4 h0, h1;
; #pragma unroll
;                 for (int j = 0; j < 4; ++j) {
;                     const float g0 = acc[ai][0][m][0][j], g1 = acc[ai][0][m][1][j];
;                     h0[j] = g0 * r2 * fast_rcp(1.0f + fast_exp2(g0 * (-LOG2E * r))) * acc[ai][1][m][0][j];
;                     h1[j] = g1 * r2 * fast_rcp(1.0f + fast_exp2(g1 * (-LOG2E * r))) * acc[ai][1][m][1][j]; }
;                 *(u32x4*)rowp = pack8(h0, h1); }
;     }
	v_exp_f32_e32 v91, v91
	v_exp_f32_e32 v92, v92
	v_add_f32_e32 v88, 1.0, v88
	v_add_f32_e32 v93, 1.0, v93
	v_add_f32_e32 v89, 1.0, v89
	v_add_f32_e32 v94, 1.0, v94
	v_add_f32_e32 v90, 1.0, v90
	v_add_f32_e32 v95, 1.0, v95
	v_add_f32_e32 v91, 1.0, v91
	v_add_f32_e32 v92, 1.0, v92
	v_rcp_f32_e32 v88, v88
	v_rcp_f32_e32 v93, v93
	v_rcp_f32_e32 v89, v89
	v_rcp_f32_e32 v94, v94
	v_rcp_f32_e32 v90, v90
	v_rcp_f32_e32 v95, v95
	v_rcp_f32_e32 v91, v91
	v_rcp_f32_e32 v92, v92
	v_mul_f32_e32 v88, v101, v88
	v_mul_f32_e32 v93, v102, v93
	v_mul_f32_e32 v89, v103, v89
	v_mul_f32_e32 v94, v104, v94
	v_mul_f32_e32 v90, v105, v90
	v_mul_f32_e32 v95, v106, v95
	v_mul_f32_e32 v91, v99, v91
	v_mul_f32_e32 v92, v100, v92
	v_mul_f32_e32 v88, v80, v88
	v_mul_f32_e32 v80, v85, v93
	v_mul_f32_e32 v85, v81, v89
	v_mul_f32_e32 v81, v86, v94
	v_mul_f32_e32 v86, v82, v90
	v_mul_f32_e32 v82, v87, v95
	v_mul_f32_e32 v83, v83, v91
	v_mul_f32_e32 v84, v84, v92
	v_cvt_pk_bf16_f32 v80, v84, v80
	v_cvt_pk_bf16_f32 v81, v81, v82
	v_cvt_pk_bf16_f32 v82, v88, v85
	v_cvt_pk_bf16_f32 v83, v86, v83
	global_store_dwordx4 v[96:97], v[80:83], off
	s_nop 1
	v_mov_b32_e32 v82, v206
	s_nop 0
	v_or_b32_e32 v80, 48, v144
	v_mad_i64_i32 v[80:81], s[40:41], v80, s52, v[146:147]
	v_lshl_add_u64 v[80:81], v[80:81], 0, v[148:149]
	v_mul_f32_e32 v83, v82, v82
	v_mul_f32_e32 v82, 0xbfb8aa3b, v82
	v_mul_f32_e32 v84, v76, v83
	v_mul_f32_e32 v85, v72, v83
	v_mul_f32_e32 v72, v72, v82
	v_mul_f32_e32 v86, v77, v83
	v_mul_f32_e32 v77, v77, v82
	v_mul_f32_e32 v87, v73, v83
	v_mul_f32_e32 v73, v73, v82
	v_mul_f32_e32 v88, v78, v83
	v_mul_f32_e32 v78, v78, v82
	v_mul_f32_e32 v89, v74, v83
	v_mul_f32_e32 v74, v74, v82
	v_mul_f32_e32 v90, v79, v83
	v_mul_f32_e32 v79, v79, v82
	v_mul_f32_e32 v83, v75, v83
	v_mul_f32_e32 v75, v75, v82
	v_mul_f32_e32 v76, v76, v82
	v_exp_f32_e32 v72, v72
	v_exp_f32_e32 v77, v77
	v_exp_f32_e32 v73, v73
	v_exp_f32_e32 v78, v78
	v_exp_f32_e32 v74, v74
	v_exp_f32_e32 v79, v79
	v_exp_f32_e32 v75, v75
	v_exp_f32_e32 v76, v76
	v_add_f32_e32 v72, 1.0, v72
	v_add_f32_e32 v77, 1.0, v77
	v_add_f32_e32 v73, 1.0, v73
	v_add_f32_e32 v78, 1.0, v78
	v_add_f32_e32 v74, 1.0, v74
	v_add_f32_e32 v79, 1.0, v79
	v_add_f32_e32 v75, 1.0, v75
	v_add_f32_e32 v76, 1.0, v76
	v_rcp_f32_e32 v72, v72
	v_rcp_f32_e32 v77, v77
	v_rcp_f32_e32 v73, v73
	v_rcp_f32_e32 v78, v78
	v_rcp_f32_e32 v74, v74
	v_rcp_f32_e32 v79, v79
	v_rcp_f32_e32 v75, v75
	v_rcp_f32_e32 v76, v76
	v_mul_f32_e32 v72, v85, v72
	v_mul_f32_e32 v77, v86, v77
	v_mul_f32_e32 v73, v87, v73
	v_mul_f32_e32 v78, v88, v78
	v_mul_f32_e32 v74, v89, v74
	v_mul_f32_e32 v79, v90, v79
	v_mul_f32_e32 v75, v83, v75
	v_mul_f32_e32 v76, v84, v76
	v_mul_f32_e32 v72, v64, v72
	v_mul_f32_e32 v64, v69, v77
	v_mul_f32_e32 v69, v65, v73
	v_mul_f32_e32 v65, v70, v78
	v_mul_f32_e32 v70, v66, v74
	v_mul_f32_e32 v66, v71, v79
	v_mul_f32_e32 v67, v67, v75
	v_mul_f32_e32 v68, v68, v76
	v_cvt_pk_bf16_f32 v64, v68, v64
	v_cvt_pk_bf16_f32 v65, v65, v66
	v_cvt_pk_bf16_f32 v66, v72, v69
	v_cvt_pk_bf16_f32 v67, v70, v67
	global_store_dwordx4 v[80:81], v[64:67], off
	s_nop 1
	v_mov_b32_e32 v66, v207
	s_nop 0
	v_add_u32_e32 v64, 0x80, v144
	v_mad_i64_i32 v[64:65], s[40:41], v64, s52, v[146:147]
	v_lshl_add_u64 v[64:65], v[64:65], 0, v[148:149]
	v_mul_f32_e32 v67, v66, v66
	v_mul_f32_e32 v66, 0xbfb8aa3b, v66
	v_mul_f32_e32 v68, v60, v67
	v_mul_f32_e32 v69, v56, v67
	v_mul_f32_e32 v56, v56, v66
	v_mul_f32_e32 v70, v61, v67
	v_mul_f32_e32 v61, v61, v66
	v_mul_f32_e32 v71, v57, v67
	v_mul_f32_e32 v57, v57, v66
	v_mul_f32_e32 v72, v62, v67
	v_mul_f32_e32 v62, v62, v66
	v_mul_f32_e32 v73, v58, v67
	v_mul_f32_e32 v58, v58, v66
	v_mul_f32_e32 v74, v63, v67
	v_mul_f32_e32 v63, v63, v66
	v_mul_f32_e32 v67, v59, v67
	v_mul_f32_e32 v59, v59, v66
	v_mul_f32_e32 v60, v60, v66
	v_exp_f32_e32 v56, v56
	v_exp_f32_e32 v61, v61
	v_exp_f32_e32 v57, v57
	v_exp_f32_e32 v62, v62
	v_exp_f32_e32 v58, v58
	v_exp_f32_e32 v63, v63
	v_exp_f32_e32 v59, v59
	v_exp_f32_e32 v60, v60
	v_add_f32_e32 v56, 1.0, v56
	v_add_f32_e32 v61, 1.0, v61
	v_add_f32_e32 v57, 1.0, v57
	v_add_f32_e32 v62, 1.0, v62
	v_add_f32_e32 v58, 1.0, v58
	v_add_f32_e32 v63, 1.0, v63
	v_add_f32_e32 v59, 1.0, v59
	v_add_f32_e32 v60, 1.0, v60
	v_rcp_f32_e32 v56, v56
	v_rcp_f32_e32 v61, v61
	v_rcp_f32_e32 v57, v57
	v_rcp_f32_e32 v62, v62
	v_rcp_f32_e32 v58, v58
	v_rcp_f32_e32 v63, v63
	v_rcp_f32_e32 v59, v59
	v_rcp_f32_e32 v60, v60
	v_mul_f32_e32 v56, v69, v56
	v_mul_f32_e32 v61, v70, v61
	v_mul_f32_e32 v57, v71, v57
	v_mul_f32_e32 v62, v72, v62
	v_mul_f32_e32 v58, v73, v58
	v_mul_f32_e32 v63, v74, v63
	v_mul_f32_e32 v59, v67, v59
	v_mul_f32_e32 v60, v68, v60
	v_mul_f32_e32 v56, v48, v56
	v_mul_f32_e32 v48, v53, v61
	v_mul_f32_e32 v53, v49, v57
	v_mul_f32_e32 v49, v54, v62
	v_mul_f32_e32 v54, v50, v58
	v_mul_f32_e32 v50, v55, v63
	v_mul_f32_e32 v51, v51, v59
	v_mul_f32_e32 v52, v52, v60
	v_cvt_pk_bf16_f32 v48, v52, v48
	v_cvt_pk_bf16_f32 v49, v49, v50
	v_cvt_pk_bf16_f32 v50, v56, v53
	v_cvt_pk_bf16_f32 v51, v54, v51
	global_store_dwordx4 v[64:65], v[48:51], off
	s_nop 1
	v_mov_b32_e32 v50, v208
	s_nop 0
	v_add_u32_e32 v48, 0x90, v144
	v_mad_i64_i32 v[48:49], s[40:41], v48, s52, v[146:147]
	v_lshl_add_u64 v[48:49], v[48:49], 0, v[148:149]
	v_mul_f32_e32 v51, v50, v50
	v_mul_f32_e32 v50, 0xbfb8aa3b, v50
	v_mul_f32_e32 v52, v44, v51
	v_mul_f32_e32 v53, v40, v51
	v_mul_f32_e32 v40, v40, v50
	v_mul_f32_e32 v54, v45, v51
	v_mul_f32_e32 v45, v45, v50
	v_mul_f32_e32 v55, v41, v51
	v_mul_f32_e32 v41, v41, v50
	v_mul_f32_e32 v56, v46, v51
; __device__ __forceinline__ float fast_rcp(float x) { return __builtin_amdgcn_rcpf(x); }
; __device__ __forceinline__ float fast_exp2(float x) { return __builtin_amdgcn_exp2f(x); }
; __device__ __forceinline__ u32x4 pack8(f32x4 v0, f32x4 v1) { u32x4 w; w.x = cvt_pk_bf16(v0[0], v0[1]); w.y = cvt_pk_bf16(v0[2], v0[3]); w.z = cvt_pk_bf16(v1[0], v1[1]); w.w = cvt_pk_bf16(v1[2], v1[3]); return w; }
; template <class Epi>
; __device__ __forceinline__ void gemm_phase(LAS unsigned char* lds, const Gemm g, const StaticOrder& S, const Epi& E) {
;     ...
;         E(acc, cur, wr, wc, fr, fq);
;         if (!has_next) break;
;     __device__ __forceinline__ void operator()(const f32x4 (&acc)[2][2][4][2], const Unit& u, int wr, int wc, int fr, int fq) const {
;         const int row0 = u.pm * BM + wr * 64 + fr, col0 = u.pn * HALF + wc * 32 + 8 * fq;
; #pragma unroll
;         for (int ai = 0; ai < 2; ++ai)
; #pragma unroll
;             for (int m = 0; m < 4; ++m) { bf16_t* rowp = O + (size_t)(row0 + ai * HALF + m * 16) * DFF + col0;
;                 const float r = rs[row0 + ai * HALF + m * 16], r2 = r * r;
;                 f32x4 h0, h1;
; #pragma unroll
;                 for (int j = 0; j < 4; ++j) {
;                     const float g0 = acc[ai][0][m][0][j], g1 = acc[ai][0][m][1][j];
;                     h0[j] = g0 * r2 * fast_rcp(1.0f + fast_exp2(g0 * (-LOG2E * r))) * acc[ai][1][m][0][j];
;                     h1[j] = g1 * r2 * fast_rcp(1.0f + fast_exp2(g1 * (-LOG2E * r))) * acc[ai][1][m][1][j]; }
;                 *(u32x4*)rowp = pack8(h0, h1); }
;     }
	v_mul_f32_e32 v46, v46, v50
	v_mul_f32_e32 v57, v42, v51
	v_mul_f32_e32 v42, v42, v50
	v_mul_f32_e32 v58, v47, v51
	v_mul_f32_e32 v47, v47, v50
	v_mul_f32_e32 v51, v43, v51
	v_mul_f32_e32 v43, v43, v50
	v_mul_f32_e32 v44, v44, v50
	v_exp_f32_e32 v40, v40
	v_exp_f32_e32 v45, v45
	v_exp_f32_e32 v41, v41
	v_exp_f32_e32 v46, v46
	v_exp_f32_e32 v42, v42
	v_exp_f32_e32 v47, v47
	v_exp_f32_e32 v43, v43
	v_exp_f32_e32 v44, v44
	v_add_f32_e32 v40, 1.0, v40
	v_add_f32_e32 v45, 1.0, v45
	v_add_f32_e32 v41, 1.0, v41
	v_add_f32_e32 v46, 1.0, v46
	v_add_f32_e32 v42, 1.0, v42
	v_add_f32_e32 v47, 1.0, v47
	v_add_f32_e32 v43, 1.0, v43
	v_add_f32_e32 v44, 1.0, v44
	v_rcp_f32_e32 v40, v40
	v_rcp_f32_e32 v45, v45
	v_rcp_f32_e32 v41, v41
	v_rcp_f32_e32 v46, v46
	v_rcp_f32_e32 v42, v42
	v_rcp_f32_e32 v47, v47
	v_rcp_f32_e32 v43, v43
	v_rcp_f32_e32 v44, v44
	v_mul_f32_e32 v40, v53, v40
	v_mul_f32_e32 v45, v54, v45
	v_mul_f32_e32 v41, v55, v41
	v_mul_f32_e32 v46, v56, v46
	v_mul_f32_e32 v42, v57, v42
	v_mul_f32_e32 v47, v58, v47
	v_mul_f32_e32 v43, v51, v43
	v_mul_f32_e32 v44, v52, v44
	v_mul_f32_e32 v40, v32, v40
	v_mul_f32_e32 v32, v37, v45
	v_mul_f32_e32 v37, v33, v41
	v_mul_f32_e32 v33, v38, v46
	v_mul_f32_e32 v38, v34, v42
	v_mul_f32_e32 v34, v39, v47
	v_mul_f32_e32 v35, v35, v43
	v_mul_f32_e32 v36, v36, v44
	v_cvt_pk_bf16_f32 v32, v36, v32
	v_cvt_pk_bf16_f32 v33, v33, v34
	v_cvt_pk_bf16_f32 v34, v40, v37
	v_cvt_pk_bf16_f32 v35, v38, v35
	global_store_dwordx4 v[48:49], v[32:35], off
	s_nop 1
	v_mov_b32_e32 v34, v209
	s_nop 0
	v_add_u32_e32 v32, 0xa0, v144
	v_mad_i64_i32 v[32:33], s[40:41], v32, s52, v[146:147]
	v_lshl_add_u64 v[32:33], v[32:33], 0, v[148:149]
	s_mov_b64 s[40:41], s[34:35]
	v_mul_f32_e32 v35, v34, v34
	v_mul_f32_e32 v34, 0xbfb8aa3b, v34
	v_mul_f32_e32 v36, v28, v35
	v_mul_f32_e32 v37, v24, v35
	v_mul_f32_e32 v24, v24, v34
	v_mul_f32_e32 v38, v29, v35
	v_mul_f32_e32 v29, v29, v34
	v_mul_f32_e32 v39, v25, v35
	v_mul_f32_e32 v25, v25, v34
	v_mul_f32_e32 v40, v30, v35
	v_mul_f32_e32 v30, v30, v34
	v_mul_f32_e32 v41, v26, v35
	v_mul_f32_e32 v26, v26, v34
	v_mul_f32_e32 v42, v31, v35
	v_mul_f32_e32 v31, v31, v34
	v_mul_f32_e32 v35, v27, v35
	v_mul_f32_e32 v27, v27, v34
	v_mul_f32_e32 v28, v28, v34
	v_exp_f32_e32 v24, v24
	v_exp_f32_e32 v29, v29
	v_exp_f32_e32 v25, v25
	v_exp_f32_e32 v30, v30
	v_exp_f32_e32 v26, v26
	v_exp_f32_e32 v31, v31
	v_exp_f32_e32 v27, v27
	v_exp_f32_e32 v28, v28
	v_add_f32_e32 v24, 1.0, v24
	v_add_f32_e32 v29, 1.0, v29
	v_add_f32_e32 v25, 1.0, v25
	v_add_f32_e32 v30, 1.0, v30
	v_add_f32_e32 v26, 1.0, v26
	v_add_f32_e32 v31, 1.0, v31
	v_add_f32_e32 v27, 1.0, v27
	v_add_f32_e32 v28, 1.0, v28
	v_rcp_f32_e32 v24, v24
	v_rcp_f32_e32 v29, v29
	v_rcp_f32_e32 v25, v25
	v_rcp_f32_e32 v30, v30
	v_rcp_f32_e32 v26, v26
	v_rcp_f32_e32 v31, v31
	v_rcp_f32_e32 v27, v27
	v_rcp_f32_e32 v28, v28
	v_mul_f32_e32 v24, v37, v24
	v_mul_f32_e32 v29, v38, v29
	v_mul_f32_e32 v25, v39, v25
	v_mul_f32_e32 v30, v40, v30
	v_mul_f32_e32 v26, v41, v26
	v_mul_f32_e32 v31, v42, v31
	v_mul_f32_e32 v27, v35, v27
	v_mul_f32_e32 v28, v36, v28
	v_mul_f32_e32 v24, v16, v24
	v_mul_f32_e32 v16, v21, v29
	v_mul_f32_e32 v21, v17, v25
	v_mul_f32_e32 v17, v22, v30
	v_mul_f32_e32 v22, v18, v26
	v_mul_f32_e32 v18, v23, v31
	v_mul_f32_e32 v19, v19, v27
	v_mul_f32_e32 v20, v20, v28
	v_cvt_pk_bf16_f32 v16, v20, v16
	v_cvt_pk_bf16_f32 v17, v17, v18
	v_cvt_pk_bf16_f32 v18, v24, v21
	v_cvt_pk_bf16_f32 v19, v22, v19
	global_store_dwordx4 v[32:33], v[16:19], off
	s_nop 1
	v_mov_b32_e32 v18, v210
	s_nop 0
	v_add_u32_e32 v16, 0xb0, v144
	v_mad_i64_i32 v[16:17], s[6:7], v16, s52, v[146:147]
	v_lshl_add_u64 v[16:17], v[16:17], 0, v[148:149]
	v_mul_f32_e32 v19, v18, v18
	v_mul_f32_e32 v18, 0xbfb8aa3b, v18
	v_mul_f32_e32 v20, v12, v19
	v_mul_f32_e32 v21, v8, v19
	v_mul_f32_e32 v8, v8, v18
	v_mul_f32_e32 v22, v13, v19
	v_mul_f32_e32 v13, v13, v18
	v_mul_f32_e32 v23, v9, v19
	v_mul_f32_e32 v9, v9, v18
	v_mul_f32_e32 v24, v14, v19
	v_mul_f32_e32 v14, v14, v18
	v_mul_f32_e32 v25, v10, v19
	v_mul_f32_e32 v10, v10, v18
	v_mul_f32_e32 v26, v15, v19
	v_mul_f32_e32 v15, v15, v18
	v_mul_f32_e32 v19, v11, v19
	v_mul_f32_e32 v11, v11, v18
	v_mul_f32_e32 v12, v12, v18
	v_exp_f32_e32 v8, v8
	v_exp_f32_e32 v13, v13
	v_exp_f32_e32 v9, v9
	v_exp_f32_e32 v14, v14
	v_exp_f32_e32 v10, v10
	v_exp_f32_e32 v15, v15
	v_exp_f32_e32 v11, v11
	v_exp_f32_e32 v12, v12
	v_add_f32_e32 v8, 1.0, v8
	v_add_f32_e32 v13, 1.0, v13
	v_add_f32_e32 v9, 1.0, v9
	v_add_f32_e32 v14, 1.0, v14
	v_add_f32_e32 v10, 1.0, v10
	v_add_f32_e32 v15, 1.0, v15
	v_add_f32_e32 v11, 1.0, v11
	v_add_f32_e32 v12, 1.0, v12
	v_rcp_f32_e32 v8, v8
	v_rcp_f32_e32 v13, v13
	v_rcp_f32_e32 v9, v9
	v_rcp_f32_e32 v14, v14
	v_rcp_f32_e32 v10, v10
	v_rcp_f32_e32 v15, v15
	v_rcp_f32_e32 v11, v11
	v_rcp_f32_e32 v12, v12
	v_mul_f32_e32 v8, v21, v8
	v_mul_f32_e32 v13, v22, v13
	v_mul_f32_e32 v9, v23, v9
	v_mul_f32_e32 v14, v24, v14
	v_mul_f32_e32 v10, v25, v10
	v_mul_f32_e32 v15, v26, v15
	v_mul_f32_e32 v11, v19, v11
	v_mul_f32_e32 v12, v20, v12
	v_mul_f32_e32 v8, v0, v8
	v_mul_f32_e32 v0, v5, v13
	v_mul_f32_e32 v5, v1, v9
	v_mul_f32_e32 v1, v6, v14
	v_mul_f32_e32 v6, v2, v10
	v_mul_f32_e32 v2, v7, v15
	v_mul_f32_e32 v3, v3, v11
	v_mul_f32_e32 v4, v4, v12
	v_cvt_pk_bf16_f32 v0, v4, v0
	v_cvt_pk_bf16_f32 v1, v1, v2
	v_cvt_pk_bf16_f32 v2, v8, v5
	v_cvt_pk_bf16_f32 v3, v6, v3
	global_store_dwordx4 v[16:17], v[0:3], off
	s_cbranch_vccz .LBB0_793
	s_waitcnt vmcnt(0)
	s_cmpk_gt_u32 s10, 0xff
	s_cbranch_scc1 .LBB0_800
	s_barrier

; #define PG8_STAGE(bufoff, gbase, voff) do { _Pragma("unroll") for (int _i = 0; _i < 2; ++_i) \
;         __builtin_amdgcn_global_load_lds((const unsigned*)((const char*)(gbase) + (voff)[_i]), (LAS unsigned*)(lds + (bufoff) + ldsw + _i * 8192), 16, 0, 0); } while (0)
; #define PG8_LDA(dst, b, h) do { _Pragma("unroll") for (int m = 0; m < 4; ++m) _Pragma("unroll") for (int k = 0; k < 2; ++k) dst[m][k] = *(const LAS bf16x8*)(lds + PG8_SA(b, h) + aoff + m * 2048 + k * 1024); } while (0)
; #define PG8_LDB(dst, b, h) do { _Pragma("unroll") for (int n = 0; n < 2; ++n) _Pragma("unroll") for (int k = 0; k < 2; ++k) dst[n][k] = *(const LAS bf16x8*)(lds + PG8_SB(b, h) + boff + n * 2048 + k * 1024); } while (0)
; #define PG8_MMA(ai, bj, At, Bt) do { __builtin_amdgcn_s_setprio(1); _Pragma("unroll") for (int m = 0; m < 4; ++m) _Pragma("unroll") for (int n = 0; n < 2; ++n) _Pragma("unroll") for (int k = 0; k < 2; ++k) \
;         acc[ai][bj][m][n] = __builtin_amdgcn_mfma_f32_16x16x32_bf16(Bt[n][k], At[m][k], acc[ai][bj][m][n], 0, 0, 0); __builtin_amdgcn_s_setprio(0); } while (0)
; #define PG8_WAIT_V(n) asm volatile("s_waitcnt vmcnt(" #n ")" ::: "memory")
; #define PG8_WAIT_L(n) asm volatile("s_waitcnt lgkmcnt(" #n ")" ::: "memory")
; #define PG8_BAR __builtin_amdgcn_s_barrier()
; #define PG8_SCHED __builtin_amdgcn_sched_barrier(0)
; template <class Epi>
; __device__ __forceinline__ void gemm_phase(LAS unsigned char* lds, const Gemm g, const StaticOrder& S, const Epi& E) {
;     ...
;             const char* a1 = cA + (size_t)(t + 1) * kstep;
;             const char* a2 = last ? nA : cA + (size_t)(t + 2) * kstep; const char* b2 = last ? nB : cB + (size_t)(t + 2) * kstep;
;             const char* a3 = a2 + kstep; const char* b3 = b2 + kstep;
;             PG8_LDB(B0, 0, 0); PG8_SCHED; PG8_LDA(At, 0, 0); PG8_STAGE(PG8_SA(1, 1), a1 + hstep, voffA);
;             PG8_WAIT_L(8); PG8_BAR; PG8_WAIT_L(0); PG8_MMA(0, 0, At, B0); PG8_BAR; PG8_SCHED;
;             PG8_LDB(B1, 0, 1); PG8_STAGE(PG8_SB(0, 0), b2, voffB);
;             PG8_BAR; PG8_WAIT_L(0); PG8_MMA(0, 1, At, B1); PG8_BAR;
;             PG8_LDA(At, 0, 1); PG8_STAGE(PG8_SA(0, 0), a2, voffA);
;             PG8_BAR; PG8_WAIT_L(0); PG8_MMA(1, 0, At, B0); PG8_BAR; PG8_SCHED;
;             PG8_STAGE(PG8_SB(0, 1), b2 + hstep, voffB);
;             PG8_WAIT_V(6); PG8_BAR; PG8_MMA(1, 1, At, B1); PG8_BAR;
.LBB0_864:
	ds_read_b128 v[148:151], v145
	ds_read_b128 v[152:155], v145 offset:1024
	ds_read_b128 v[160:163], v145 offset:2048
	ds_read_b128 v[164:167], v145 offset:3072
	s_add_u32 s44, s42, 0x100
	s_addc_u32 s45, s43, 0
	s_cmpk_eq_i32 s67, 0x54
	s_cselect_b32 s49, s41, s45
	s_cselect_b32 s48, s40, s44
	s_cselect_b32 s47, s7, s66
	s_cselect_b32 s46, s6, s65
	s_add_i32 m0, s28, 0xc000
	ds_read_b128 v[168:171], v146
	ds_read_b128 v[172:175], v146 offset:1024
	ds_read_b128 v[176:179], v146 offset:2048
	ds_read_b128 v[180:183], v146 offset:3072
	ds_read_b128 v[184:187], v146 offset:4096
	ds_read_b128 v[188:191], v146 offset:5120
	ds_read_b128 v[192:195], v146 offset:6144
	ds_read_b128 v[196:199], v146 offset:7168
	global_load_lds_dwordx4 v136, s[42:43]
	s_add_i32 m0, s28, 0xe000
	s_nop 0
	global_load_lds_dwordx4 v138, s[42:43]
	s_waitcnt lgkmcnt(8)
	s_barrier
	s_waitcnt lgkmcnt(0)
	v_mfma_f32_16x16x32_bf16 v[124:127], v[148:151], v[168:171], v[124:127]
	v_mfma_f32_16x16x32_bf16 v[120:123], v[160:163], v[168:171], v[120:123]
	v_mfma_f32_16x16x32_bf16 v[112:115], v[148:151], v[176:179], v[112:115]
	v_mfma_f32_16x16x32_bf16 v[104:107], v[160:163], v[176:179], v[104:107]
	v_mfma_f32_16x16x32_bf16 v[96:99], v[148:151], v[184:187], v[96:99]
	v_mfma_f32_16x16x32_bf16 v[88:91], v[160:163], v[184:187], v[88:91]
	v_mfma_f32_16x16x32_bf16 v[80:83], v[148:151], v[192:195], v[80:83]
	v_mfma_f32_16x16x32_bf16 v[72:75], v[160:163], v[192:195], v[72:75]
	v_mfma_f32_16x16x32_bf16 v[124:127], v[152:155], v[172:175], v[124:127]
	v_mfma_f32_16x16x32_bf16 v[120:123], v[164:167], v[172:175], v[120:123]
	v_mfma_f32_16x16x32_bf16 v[112:115], v[152:155], v[180:183], v[112:115]
	v_mfma_f32_16x16x32_bf16 v[104:107], v[164:167], v[180:183], v[104:107]
	v_mfma_f32_16x16x32_bf16 v[96:99], v[152:155], v[188:191], v[96:99]
	v_mfma_f32_16x16x32_bf16 v[88:91], v[164:167], v[188:191], v[88:91]
	v_mfma_f32_16x16x32_bf16 v[80:83], v[152:155], v[196:199], v[80:83]
	v_mfma_f32_16x16x32_bf16 v[72:75], v[164:167], v[196:199], v[72:75]
	s_barrier
	s_add_i32 s42, s55, s23
	s_add_u32 s98, s46, s2
	s_addc_u32 s99, s47, s3
	s_mov_b32 m0, s42
	ds_read_b128 v[200:203], v147
	ds_read_b128 v[204:207], v147 offset:1024
	ds_read_b128 v[208:211], v147 offset:2048
	ds_read_b128 v[212:215], v147 offset:3072
	global_load_lds_dwordx4 v132, s[46:47]
	s_add_i32 m0, s42, 0x2000
	s_nop 0
	global_load_lds_dwordx4 v128, s[46:47]
	s_waitcnt lgkmcnt(0)
	s_barrier
	s_waitcnt lgkmcnt(0)
	v_mfma_f32_16x16x32_bf16 v[116:119], v[200:203], v[168:171], v[116:119]
	v_mfma_f32_16x16x32_bf16 v[108:111], v[208:211], v[168:171], v[108:111]
	v_mfma_f32_16x16x32_bf16 v[100:103], v[200:203], v[176:179], v[100:103]
	v_mfma_f32_16x16x32_bf16 v[92:95], v[208:211], v[176:179], v[92:95]
	v_mfma_f32_16x16x32_bf16 v[84:87], v[200:203], v[184:187], v[84:87]
	v_mfma_f32_16x16x32_bf16 v[76:79], v[208:211], v[184:187], v[76:79]
	v_mfma_f32_16x16x32_bf16 v[68:71], v[200:203], v[192:195], v[68:71]
	v_mfma_f32_16x16x32_bf16 v[64:67], v[208:211], v[192:195], v[64:67]
	v_mfma_f32_16x16x32_bf16 v[116:119], v[204:207], v[172:175], v[116:119]
	v_mfma_f32_16x16x32_bf16 v[108:111], v[212:215], v[172:175], v[108:111]
	v_mfma_f32_16x16x32_bf16 v[100:103], v[204:207], v[180:183], v[100:103]
	v_mfma_f32_16x16x32_bf16 v[92:95], v[212:215], v[180:183], v[92:95]
	v_mfma_f32_16x16x32_bf16 v[84:87], v[204:207], v[188:191], v[84:87]
	v_mfma_f32_16x16x32_bf16 v[76:79], v[212:215], v[188:191], v[76:79]
	v_mfma_f32_16x16x32_bf16 v[68:71], v[204:207], v[196:199], v[68:71]
	v_mfma_f32_16x16x32_bf16 v[64:67], v[212:215], v[196:199], v[64:67]
	s_mov_b32 m0, s28
	s_add_u32 s100, s48, s2
	s_addc_u32 s101, s49, s3
	s_barrier
	ds_read_b128 v[168:171], v146 offset:16384
	ds_read_b128 v[172:175], v146 offset:17408
	ds_read_b128 v[176:179], v146 offset:18432
	ds_read_b128 v[180:183], v146 offset:19456
	ds_read_b128 v[184:187], v146 offset:20480
	ds_read_b128 v[188:191], v146 offset:21504
	ds_read_b128 v[192:195], v146 offset:22528
	ds_read_b128 v[196:199], v146 offset:23552
	global_load_lds_dwordx4 v134, s[48:49]
	s_mov_b32 m0, s29
	s_nop 0
	global_load_lds_dwordx4 v130, s[48:49]
	s_add_u32 s42, s46, 0x160000
	s_addc_u32 s43, s47, 0
	s_add_i32 s68, s56, s23
	s_mov_b32 m0, s68
	s_nop 0
	global_load_lds_dwordx4 v132, s[42:43]
	s_add_i32 m0, s68, 0x2000
	s_nop 0
	global_load_lds_dwordx4 v128, s[42:43]
	s_waitcnt vmcnt(6)
	s_barrier
	s_waitcnt lgkmcnt(0)
	v_mfma_f32_16x16x32_bf16 v[60:63], v[148:151], v[168:171], v[60:63]
	v_mfma_f32_16x16x32_bf16 v[56:59], v[160:163], v[168:171], v[56:59]
	v_mfma_f32_16x16x32_bf16 v[52:55], v[148:151], v[176:179], v[52:55]
	v_mfma_f32_16x16x32_bf16 v[44:47], v[160:163], v[176:179], v[44:47]
	v_mfma_f32_16x16x32_bf16 v[36:39], v[148:151], v[184:187], v[36:39]
	v_mfma_f32_16x16x32_bf16 v[28:31], v[160:163], v[184:187], v[28:31]
	v_mfma_f32_16x16x32_bf16 v[20:23], v[148:151], v[192:195], v[20:23]
	v_mfma_f32_16x16x32_bf16 v[12:15], v[160:163], v[192:195], v[12:15]
	v_mfma_f32_16x16x32_bf16 v[60:63], v[152:155], v[172:175], v[60:63]
	v_mfma_f32_16x16x32_bf16 v[56:59], v[164:167], v[172:175], v[56:59]
	v_mfma_f32_16x16x32_bf16 v[52:55], v[152:155], v[180:183], v[52:55]
	v_mfma_f32_16x16x32_bf16 v[44:47], v[164:167], v[180:183], v[44:47]
	v_mfma_f32_16x16x32_bf16 v[36:39], v[152:155], v[188:191], v[36:39]
	v_mfma_f32_16x16x32_bf16 v[28:31], v[164:167], v[188:191], v[28:31]
	v_mfma_f32_16x16x32_bf16 v[20:23], v[152:155], v[196:199], v[20:23]
	v_mfma_f32_16x16x32_bf16 v[12:15], v[164:167], v[196:199], v[12:15]
	v_mfma_f32_16x16x32_bf16 v[48:51], v[200:203], v[168:171], v[48:51]
	v_mfma_f32_16x16x32_bf16 v[40:43], v[208:211], v[168:171], v[40:43]
	v_mfma_f32_16x16x32_bf16 v[32:35], v[200:203], v[176:179], v[32:35]
	v_mfma_f32_16x16x32_bf16 v[24:27], v[208:211], v[176:179], v[24:27]
	v_mfma_f32_16x16x32_bf16 v[16:19], v[200:203], v[184:187], v[16:19]
	v_mfma_f32_16x16x32_bf16 v[8:11], v[208:211], v[184:187], v[8:11]
	v_mfma_f32_16x16x32_bf16 v[4:7], v[200:203], v[192:195], v[4:7]
	v_mfma_f32_16x16x32_bf16 v[0:3], v[208:211], v[192:195], v[0:3]
	v_mfma_f32_16x16x32_bf16 v[48:51], v[204:207], v[172:175], v[48:51]
	v_mfma_f32_16x16x32_bf16 v[40:43], v[212:215], v[172:175], v[40:43]
	v_mfma_f32_16x16x32_bf16 v[32:35], v[204:207], v[180:183], v[32:35]
	v_mfma_f32_16x16x32_bf16 v[24:27], v[212:215], v[180:183], v[24:27]
	v_mfma_f32_16x16x32_bf16 v[16:19], v[204:207], v[188:191], v[16:19]
	v_mfma_f32_16x16x32_bf16 v[8:11], v[212:215], v[188:191], v[8:11]
	v_mfma_f32_16x16x32_bf16 v[4:7], v[204:207], v[196:199], v[4:7]
	v_mfma_f32_16x16x32_bf16 v[0:3], v[212:215], v[196:199], v[0:3]
	s_add_i32 s68, 0, 0x18000
	v_add_u32_e32 v164, s68, v143
	s_barrier
; #define PG8_STAGE(bufoff, gbase, voff) do { _Pragma("unroll") for (int _i = 0; _i < 2; ++_i) \
;         __builtin_amdgcn_global_load_lds((const unsigned*)((const char*)(gbase) + (voff)[_i]), (LAS unsigned*)(lds + (bufoff) + ldsw + _i * 8192), 16, 0, 0); } while (0)
; #define PG8_LDA(dst, b, h) do { _Pragma("unroll") for (int m = 0; m < 4; ++m) _Pragma("unroll") for (int k = 0; k < 2; ++k) dst[m][k] = *(const LAS bf16x8*)(lds + PG8_SA(b, h) + aoff + m * 2048 + k * 1024); } while (0)
; #define PG8_LDB(dst, b, h) do { _Pragma("unroll") for (int n = 0; n < 2; ++n) _Pragma("unroll") for (int k = 0; k < 2; ++k) dst[n][k] = *(const LAS bf16x8*)(lds + PG8_SB(b, h) + boff + n * 2048 + k * 1024); } while (0)
; #define PG8_MMA(ai, bj, At, Bt) do { __builtin_amdgcn_s_setprio(1); _Pragma("unroll") for (int m = 0; m < 4; ++m) _Pragma("unroll") for (int n = 0; n < 2; ++n) _Pragma("unroll") for (int k = 0; k < 2; ++k) \
;         acc[ai][bj][m][n] = __builtin_amdgcn_mfma_f32_16x16x32_bf16(Bt[n][k], At[m][k], acc[ai][bj][m][n], 0, 0, 0); __builtin_amdgcn_s_setprio(0); } while (0)
; #define PG8_WAIT_V(n) asm volatile("s_waitcnt vmcnt(" #n ")" ::: "memory")
; #define PG8_WAIT_L(n) asm volatile("s_waitcnt lgkmcnt(" #n ")" ::: "memory")
; #define PG8_BAR __builtin_amdgcn_s_barrier()
; #define PG8_SCHED __builtin_amdgcn_sched_barrier(0)
; template <class Epi>
; __device__ __forceinline__ void gemm_phase(LAS unsigned char* lds, const Gemm g, const StaticOrder& S, const Epi& E) {
;     ...
;             PG8_LDB(B0, 1, 0); PG8_SCHED; PG8_LDA(At, 1, 0); PG8_STAGE(PG8_SA(0, 1), a2 + hstep, voffA);
;             PG8_WAIT_L(8); PG8_BAR; PG8_WAIT_L(0); PG8_MMA(0, 0, At, B0); PG8_BAR; PG8_SCHED;
;             PG8_LDB(B1, 1, 1); PG8_STAGE(PG8_SB(1, 0), b3, voffB);
;             PG8_BAR; PG8_WAIT_L(0); PG8_MMA(0, 1, At, B1); PG8_BAR;
;             PG8_LDA(At, 1, 1); PG8_STAGE(PG8_SA(1, 0), a3, voffA);
;             PG8_BAR; PG8_WAIT_L(0); PG8_MMA(1, 0, At, B0); PG8_BAR; PG8_SCHED;
;             PG8_STAGE(PG8_SB(1, 1), b3 + hstep, voffB);
;             PG8_WAIT_V(6); PG8_BAR; PG8_MMA(1, 1, At, B1); PG8_BAR;
;         }
	ds_read_b128 v[148:151], v164
	ds_read_b128 v[152:155], v164 offset:1024
	ds_read_b128 v[160:163], v164 offset:2048
	ds_read_b128 v[164:167], v164 offset:3072
	s_add_u32 s42, s48, 0x160000
	s_addc_u32 s43, s49, 0
	s_mov_b32 m0, s33
	ds_read_b128 v[168:171], v146 offset:32768
	ds_read_b128 v[172:175], v146 offset:33792
	ds_read_b128 v[176:179], v146 offset:34816
	ds_read_b128 v[180:183], v146 offset:35840
	ds_read_b128 v[184:187], v146 offset:36864
	ds_read_b128 v[188:191], v146 offset:37888
	ds_read_b128 v[192:195], v146 offset:38912
	ds_read_b128 v[196:199], v146 offset:39936
	global_load_lds_dwordx4 v134, s[42:43]
	s_mov_b32 m0, s50
	s_nop 0
	global_load_lds_dwordx4 v130, s[42:43]
	s_waitcnt lgkmcnt(8)
	s_barrier
	s_waitcnt lgkmcnt(0)
	v_mfma_f32_16x16x32_bf16 v[124:127], v[148:151], v[168:171], v[124:127]
	v_mfma_f32_16x16x32_bf16 v[120:123], v[160:163], v[168:171], v[120:123]
	v_mfma_f32_16x16x32_bf16 v[112:115], v[148:151], v[176:179], v[112:115]
	v_mfma_f32_16x16x32_bf16 v[104:107], v[160:163], v[176:179], v[104:107]
	v_mfma_f32_16x16x32_bf16 v[96:99], v[148:151], v[184:187], v[96:99]
	v_mfma_f32_16x16x32_bf16 v[88:91], v[160:163], v[184:187], v[88:91]
	v_mfma_f32_16x16x32_bf16 v[80:83], v[148:151], v[192:195], v[80:83]
	v_mfma_f32_16x16x32_bf16 v[72:75], v[160:163], v[192:195], v[72:75]
	v_mfma_f32_16x16x32_bf16 v[124:127], v[152:155], v[172:175], v[124:127]
	v_mfma_f32_16x16x32_bf16 v[120:123], v[164:167], v[172:175], v[120:123]
	v_mfma_f32_16x16x32_bf16 v[112:115], v[152:155], v[180:183], v[112:115]
	v_mfma_f32_16x16x32_bf16 v[104:107], v[164:167], v[180:183], v[104:107]
	v_mfma_f32_16x16x32_bf16 v[96:99], v[152:155], v[188:191], v[96:99]
	v_mfma_f32_16x16x32_bf16 v[88:91], v[164:167], v[188:191], v[88:91]
	v_mfma_f32_16x16x32_bf16 v[80:83], v[152:155], v[196:199], v[80:83]
	v_mfma_f32_16x16x32_bf16 v[72:75], v[164:167], v[196:199], v[72:75]
	s_barrier
	s_add_i32 s48, 0, 0x1c000
	s_add_i32 s42, s68, s23
	v_add_u32_e32 v212, s48, v143
	s_mov_b32 m0, s42
	ds_read_b128 v[200:203], v212
	ds_read_b128 v[204:207], v212 offset:1024
	ds_read_b128 v[208:211], v212 offset:2048
	ds_read_b128 v[212:215], v212 offset:3072
	global_load_lds_dwordx4 v132, s[98:99]
	s_add_i32 m0, s42, 0x2000
	s_nop 0
	global_load_lds_dwordx4 v128, s[98:99]
	s_waitcnt lgkmcnt(0)
	s_barrier
	s_waitcnt lgkmcnt(0)
	v_mfma_f32_16x16x32_bf16 v[116:119], v[200:203], v[168:171], v[116:119]
	v_mfma_f32_16x16x32_bf16 v[108:111], v[208:211], v[168:171], v[108:111]
	v_mfma_f32_16x16x32_bf16 v[100:103], v[200:203], v[176:179], v[100:103]
	v_mfma_f32_16x16x32_bf16 v[92:95], v[208:211], v[176:179], v[92:95]
	v_mfma_f32_16x16x32_bf16 v[84:87], v[200:203], v[184:187], v[84:87]
	v_mfma_f32_16x16x32_bf16 v[76:79], v[208:211], v[184:187], v[76:79]
	v_mfma_f32_16x16x32_bf16 v[68:71], v[200:203], v[192:195], v[68:71]
	v_mfma_f32_16x16x32_bf16 v[64:67], v[208:211], v[192:195], v[64:67]
	v_mfma_f32_16x16x32_bf16 v[116:119], v[204:207], v[172:175], v[116:119]
	v_mfma_f32_16x16x32_bf16 v[108:111], v[212:215], v[172:175], v[108:111]
	v_mfma_f32_16x16x32_bf16 v[100:103], v[204:207], v[180:183], v[100:103]
	v_mfma_f32_16x16x32_bf16 v[92:95], v[212:215], v[180:183], v[92:95]
	v_mfma_f32_16x16x32_bf16 v[84:87], v[204:207], v[188:191], v[84:87]
	v_mfma_f32_16x16x32_bf16 v[76:79], v[212:215], v[188:191], v[76:79]
	v_mfma_f32_16x16x32_bf16 v[68:71], v[204:207], v[196:199], v[68:71]
	v_mfma_f32_16x16x32_bf16 v[64:67], v[212:215], v[196:199], v[64:67]
	s_mov_b32 m0, s52
	s_barrier
	ds_read_b128 v[168:171], v146 offset:49152
	ds_read_b128 v[172:175], v146 offset:50176
	ds_read_b128 v[176:179], v146 offset:51200
	ds_read_b128 v[180:183], v146 offset:52224
	ds_read_b128 v[184:187], v146 offset:53248
	ds_read_b128 v[188:191], v146 offset:54272
	ds_read_b128 v[192:195], v146 offset:55296
	ds_read_b128 v[196:199], v146 offset:56320
	global_load_lds_dwordx4 v134, s[100:101]
	s_mov_b32 m0, s53
	s_nop 0
	global_load_lds_dwordx4 v130, s[100:101]
	s_add_u32 s42, s46, 0x160080
	s_addc_u32 s43, s47, 0
	s_add_i32 s46, s48, s23
	s_mov_b32 m0, s46
	s_nop 0
	global_load_lds_dwordx4 v132, s[42:43]
	s_add_i32 m0, s46, 0x2000
	s_nop 0
	global_load_lds_dwordx4 v128, s[42:43]
	s_waitcnt vmcnt(6)
	s_barrier
	s_waitcnt lgkmcnt(0)
	v_mfma_f32_16x16x32_bf16 v[60:63], v[148:151], v[168:171], v[60:63]
	v_mfma_f32_16x16x32_bf16 v[56:59], v[160:163], v[168:171], v[56:59]
	v_mfma_f32_16x16x32_bf16 v[52:55], v[148:151], v[176:179], v[52:55]
	v_mfma_f32_16x16x32_bf16 v[44:47], v[160:163], v[176:179], v[44:47]
	v_mfma_f32_16x16x32_bf16 v[36:39], v[148:151], v[184:187], v[36:39]
	v_mfma_f32_16x16x32_bf16 v[28:31], v[160:163], v[184:187], v[28:31]
	v_mfma_f32_16x16x32_bf16 v[20:23], v[148:151], v[192:195], v[20:23]
	v_mfma_f32_16x16x32_bf16 v[12:15], v[160:163], v[192:195], v[12:15]
	v_mfma_f32_16x16x32_bf16 v[60:63], v[152:155], v[172:175], v[60:63]
	v_mfma_f32_16x16x32_bf16 v[56:59], v[164:167], v[172:175], v[56:59]
	v_mfma_f32_16x16x32_bf16 v[52:55], v[152:155], v[180:183], v[52:55]
	v_mfma_f32_16x16x32_bf16 v[44:47], v[164:167], v[180:183], v[44:47]
	v_mfma_f32_16x16x32_bf16 v[36:39], v[152:155], v[188:191], v[36:39]
	v_mfma_f32_16x16x32_bf16 v[28:31], v[164:167], v[188:191], v[28:31]
	v_mfma_f32_16x16x32_bf16 v[20:23], v[152:155], v[196:199], v[20:23]
	v_mfma_f32_16x16x32_bf16 v[12:15], v[164:167], v[196:199], v[12:15]
	v_mfma_f32_16x16x32_bf16 v[48:51], v[200:203], v[168:171], v[48:51]
	v_mfma_f32_16x16x32_bf16 v[40:43], v[208:211], v[168:171], v[40:43]
	v_mfma_f32_16x16x32_bf16 v[32:35], v[200:203], v[176:179], v[32:35]
	v_mfma_f32_16x16x32_bf16 v[24:27], v[208:211], v[176:179], v[24:27]
	v_mfma_f32_16x16x32_bf16 v[16:19], v[200:203], v[184:187], v[16:19]
	v_mfma_f32_16x16x32_bf16 v[8:11], v[208:211], v[184:187], v[8:11]
	v_mfma_f32_16x16x32_bf16 v[4:7], v[200:203], v[192:195], v[4:7]
	v_mfma_f32_16x16x32_bf16 v[0:3], v[208:211], v[192:195], v[0:3]
	v_mfma_f32_16x16x32_bf16 v[48:51], v[204:207], v[172:175], v[48:51]
	v_mfma_f32_16x16x32_bf16 v[40:43], v[212:215], v[172:175], v[40:43]
	v_mfma_f32_16x16x32_bf16 v[32:35], v[204:207], v[180:183], v[32:35]
	v_mfma_f32_16x16x32_bf16 v[24:27], v[212:215], v[180:183], v[24:27]
	v_mfma_f32_16x16x32_bf16 v[16:19], v[204:207], v[188:191], v[16:19]
	v_mfma_f32_16x16x32_bf16 v[8:11], v[212:215], v[188:191], v[8:11]
	v_mfma_f32_16x16x32_bf16 v[4:7], v[204:207], v[196:199], v[4:7]
	v_mfma_f32_16x16x32_bf16 v[0:3], v[212:215], v[196:199], v[0:3]
	s_add_i32 s67, s67, 2
	s_add_u32 s65, s65, 0x100
	s_addc_u32 s66, s66, 0
	s_cmpk_gt_u32 s67, 0x55
	s_mov_b64 s[42:43], s[44:45]
	s_barrier
; #define PG8_WAIT_V(n) asm volatile("s_waitcnt vmcnt(" #n ")" ::: "memory")
; #define PG8_BAR __builtin_amdgcn_s_barrier()
; __device__ __forceinline__ u32x4 pack8(f32x4 v0, f32x4 v1) { u32x4 w; w.x = cvt_pk_bf16(v0[0], v0[1]); w.y = cvt_pk_bf16(v0[2], v0[3]); w.z = cvt_pk_bf16(v1[0], v1[1]); w.w = cvt_pk_bf16(v1[2], v1[3]); return w; }
; template <class Epi>
; __device__ __forceinline__ void gemm_phase(LAS unsigned char* lds, const Gemm g, const StaticOrder& S, const Epi& E) {
;     ...
;         E(acc, cur, wr, wc, fr, fq);
;         if (!has_next) break;
; #pragma unroll
;         for (int a = 0; a < 2; ++a)
; #pragma unroll
;             for (int b = 0; b < 2; ++b)
; #pragma unroll
;                 for (int m = 0; m < 4; ++m)
; #pragma unroll
;                     for (int n = 0; n < 2; ++n) acc[a][b][m][n] = (f32x4){0.f, 0.f, 0.f, 0.f};
;         cur = nxt; cA = nA; cB = nB; ++ui;
;     }
;     PG8_WAIT_V(0);
;     if (wr == 0) PG8_BAR;
;     PG8_BAR;
;     __device__ __forceinline__ void operator()(const f32x4 (&acc)[2][2][4][2], const Unit& u, int wr, int wc, int fr, int fq) const {
;         const int row0 = u.pm * BM + wr * 64 + fr, col0 = u.pn * BM + wc * 32 + 8 * fq;
; #pragma unroll
;         for (int ai = 0; ai < 2; ++ai)
; #pragma unroll
;             for (int m = 0; m < 4; ++m) { bf16_t* rowp = O + (size_t)(row0 + ai * HALF + m * 16) * ldc + col0;
; #pragma unroll
;                 for (int bj = 0; bj < 2; ++bj) *(u32x4*)(rowp + bj * HALF) = pack8(acc[ai][bj][m][0], acc[ai][bj][m][1]); }
;     }
	s_cbranch_scc0 .LBB0_864
	v_lshl_add_u32 v148, s63, 8, v142
	v_lshl_or_b32 v140, s64, 8, v144
	v_ashrrev_i32_e32 v149, 31, v148
	v_ashrrev_i32_e32 v141, 31, v140
	v_lshlrev_b64 v[150:151], 12, v[148:149]
	v_lshl_add_u64 v[150:151], s[24:25], 0, v[150:151]
	v_lshlrev_b64 v[152:153], 1, v[140:141]
	v_lshl_add_u64 v[140:141], v[150:151], 0, v[152:153]
	v_cvt_pk_bf16_f32 v124, v124, v125
	v_cvt_pk_bf16_f32 v125, v126, v127
	v_cvt_pk_bf16_f32 v126, v120, v121
	v_cvt_pk_bf16_f32 v127, v122, v123
	global_store_dwordx4 v[140:141], v[124:127], off
	v_cvt_pk_bf16_f32 v116, v116, v117
	v_cvt_pk_bf16_f32 v117, v118, v119
	v_cvt_pk_bf16_f32 v118, v108, v109
	v_or_b32_e32 v108, 16, v148
	v_ashrrev_i32_e32 v109, 31, v108
	v_lshlrev_b64 v[108:109], 12, v[108:109]
	v_lshl_add_u64 v[108:109], s[24:25], 0, v[108:109]
	v_cvt_pk_bf16_f32 v119, v110, v111
	global_store_dwordx4 v[140:141], v[116:119], off offset:256
	s_mov_b32 s64, s61
	s_mov_b32 s63, s62
	v_lshl_add_u64 v[116:117], v[108:109], 0, v[152:153]
	v_cvt_pk_bf16_f32 v108, v112, v113
	v_cvt_pk_bf16_f32 v109, v114, v115
	v_cvt_pk_bf16_f32 v110, v104, v105
	v_cvt_pk_bf16_f32 v111, v106, v107
	global_store_dwordx4 v[116:117], v[108:111], off
	v_cvt_pk_bf16_f32 v100, v100, v101
	v_cvt_pk_bf16_f32 v101, v102, v103
	v_cvt_pk_bf16_f32 v102, v92, v93
	v_or_b32_e32 v92, 32, v148
	v_ashrrev_i32_e32 v93, 31, v92
	v_lshlrev_b64 v[92:93], 12, v[92:93]
	v_lshl_add_u64 v[92:93], s[24:25], 0, v[92:93]
	v_cvt_pk_bf16_f32 v103, v94, v95
	global_store_dwordx4 v[116:117], v[100:103], off offset:256
	s_mov_b64 s[44:45], s[6:7]
	s_mov_b64 s[42:43], s[40:41]
	v_lshl_add_u64 v[100:101], v[92:93], 0, v[152:153]
	v_cvt_pk_bf16_f32 v92, v96, v97
	v_cvt_pk_bf16_f32 v93, v98, v99
	v_cvt_pk_bf16_f32 v94, v88, v89
	v_cvt_pk_bf16_f32 v95, v90, v91
	global_store_dwordx4 v[100:101], v[92:95], off
	v_cvt_pk_bf16_f32 v84, v84, v85
	v_cvt_pk_bf16_f32 v85, v86, v87
	v_cvt_pk_bf16_f32 v86, v76, v77
	v_or_b32_e32 v76, 48, v148
	v_ashrrev_i32_e32 v77, 31, v76
	v_lshlrev_b64 v[76:77], 12, v[76:77]
	v_lshl_add_u64 v[76:77], s[24:25], 0, v[76:77]
	v_cvt_pk_bf16_f32 v87, v78, v79
	global_store_dwordx4 v[100:101], v[84:87], off offset:256
	s_nop 1
	v_lshl_add_u64 v[84:85], v[76:77], 0, v[152:153]
	v_cvt_pk_bf16_f32 v76, v80, v81
	v_cvt_pk_bf16_f32 v77, v82, v83
	v_cvt_pk_bf16_f32 v78, v72, v73
	v_cvt_pk_bf16_f32 v79, v74, v75
	global_store_dwordx4 v[84:85], v[76:79], off
	v_cvt_pk_bf16_f32 v68, v68, v69
	v_cvt_pk_bf16_f32 v69, v70, v71
	v_cvt_pk_bf16_f32 v70, v64, v65
	v_cvt_pk_bf16_f32 v71, v66, v67
	global_store_dwordx4 v[84:85], v[68:71], off offset:256
	v_cvt_pk_bf16_f32 v60, v60, v61
	v_cvt_pk_bf16_f32 v61, v62, v63
	v_cvt_pk_bf16_f32 v62, v56, v57
	v_add_co_u32_e32 v56, vcc, s57, v140
	v_lshl_add_u64 v[64:65], v[140:141], 0, s[8:9]
	s_nop 0
	v_addc_co_u32_e32 v57, vcc, 0, v141, vcc
	v_cvt_pk_bf16_f32 v63, v58, v59
	global_store_dwordx4 v[56:57], v[60:63], off
	v_cvt_pk_bf16_f32 v48, v48, v49
	v_cvt_pk_bf16_f32 v49, v50, v51
	v_cvt_pk_bf16_f32 v50, v40, v41
	v_cvt_pk_bf16_f32 v51, v42, v43
	global_store_dwordx4 v[64:65], v[48:51], off offset:256
	v_cvt_pk_bf16_f32 v40, v52, v53
	v_cvt_pk_bf16_f32 v41, v54, v55
	v_cvt_pk_bf16_f32 v42, v44, v45
	v_add_co_u32_e32 v44, vcc, s58, v140
	s_nop 0
	v_lshl_add_u64 v[48:49], v[140:141], 0, s[30:31]
	v_addc_co_u32_e32 v45, vcc, 0, v141, vcc
	v_cvt_pk_bf16_f32 v43, v46, v47
	global_store_dwordx4 v[44:45], v[40:43], off
	v_cvt_pk_bf16_f32 v32, v32, v33
	v_cvt_pk_bf16_f32 v33, v34, v35
	v_cvt_pk_bf16_f32 v34, v24, v25
	v_cvt_pk_bf16_f32 v35, v26, v27
	global_store_dwordx4 v[48:49], v[32:35], off offset:256
	v_cvt_pk_bf16_f32 v24, v36, v37
	v_cvt_pk_bf16_f32 v25, v38, v39
	v_cvt_pk_bf16_f32 v26, v28, v29
	v_add_co_u32_e32 v28, vcc, s59, v140
	s_nop 0
	v_lshl_add_u64 v[32:33], v[140:141], 0, s[34:35]
	v_addc_co_u32_e32 v29, vcc, 0, v141, vcc
	v_cvt_pk_bf16_f32 v27, v30, v31
	global_store_dwordx4 v[28:29], v[24:27], off
	v_cvt_pk_bf16_f32 v16, v16, v17
	v_cvt_pk_bf16_f32 v17, v18, v19
	v_cvt_pk_bf16_f32 v18, v8, v9
	v_cvt_pk_bf16_f32 v19, v10, v11
	global_store_dwordx4 v[32:33], v[16:19], off offset:256
	v_cvt_pk_bf16_f32 v8, v20, v21
	v_cvt_pk_bf16_f32 v9, v22, v23
	v_cvt_pk_bf16_f32 v10, v12, v13
	v_add_co_u32_e32 v12, vcc, s60, v140
	s_nop 0
	v_lshl_add_u64 v[16:17], v[140:141], 0, s[36:37]
	v_addc_co_u32_e32 v13, vcc, 0, v141, vcc
	s_and_b64 vcc, exec, s[38:39]
	v_cvt_pk_bf16_f32 v11, v14, v15
	global_store_dwordx4 v[12:13], v[8:11], off
	v_cvt_pk_bf16_f32 v4, v4, v5
	v_cvt_pk_bf16_f32 v5, v6, v7
	v_cvt_pk_bf16_f32 v6, v0, v1
	v_cvt_pk_bf16_f32 v7, v2, v3
	global_store_dwordx4 v[16:17], v[4:7], off offset:256
	s_cbranch_vccz .LBB0_857
	s_waitcnt vmcnt(0)
	s_cmpk_gt_u32 s10, 0xff
	v_readlane_b32 s62, v232, 20
	v_readlane_b32 s61, v232, 21
	s_cbranch_scc1 .LBB0_868
	s_barrier

; #define PG8_STAGE(bufoff, gbase, voff) do { _Pragma("unroll") for (int _i = 0; _i < 2; ++_i) \
;         __builtin_amdgcn_global_load_lds((const unsigned*)((const char*)(gbase) + (voff)[_i]), (LAS unsigned*)(lds + (bufoff) + ldsw + _i * 8192), 16, 0, 0); } while (0)
; #define PG8_LDA(dst, b, h) do { _Pragma("unroll") for (int m = 0; m < 4; ++m) _Pragma("unroll") for (int k = 0; k < 2; ++k) dst[m][k] = *(const LAS bf16x8*)(lds + PG8_SA(b, h) + aoff + m * 2048 + k * 1024); } while (0)
; #define PG8_LDB(dst, b, h) do { _Pragma("unroll") for (int n = 0; n < 2; ++n) _Pragma("unroll") for (int k = 0; k < 2; ++k) dst[n][k] = *(const LAS bf16x8*)(lds + PG8_SB(b, h) + boff + n * 2048 + k * 1024); } while (0)
; #define PG8_MMA(ai, bj, At, Bt) do { __builtin_amdgcn_s_setprio(1); _Pragma("unroll") for (int m = 0; m < 4; ++m) _Pragma("unroll") for (int n = 0; n < 2; ++n) _Pragma("unroll") for (int k = 0; k < 2; ++k) \
;         acc[ai][bj][m][n] = __builtin_amdgcn_mfma_f32_16x16x32_bf16(Bt[n][k], At[m][k], acc[ai][bj][m][n], 0, 0, 0); __builtin_amdgcn_s_setprio(0); } while (0)
; #define PG8_WAIT_V(n) asm volatile("s_waitcnt vmcnt(" #n ")" ::: "memory")
; #define PG8_WAIT_L(n) asm volatile("s_waitcnt lgkmcnt(" #n ")" ::: "memory")
; #define PG8_BAR __builtin_amdgcn_s_barrier()
; #define PG8_SCHED __builtin_amdgcn_sched_barrier(0)
; template <class Epi>
; __device__ __forceinline__ void gemm_phase(LAS unsigned char* lds, const Gemm g, const StaticOrder& S, const Epi& E) {
;     ...
;             const char* a1 = cA + (size_t)(t + 1) * kstep;
;             const char* a2 = last ? nA : cA + (size_t)(t + 2) * kstep; const char* b2 = last ? nB : cB + (size_t)(t + 2) * kstep;
;             const char* a3 = a2 + kstep; const char* b3 = b2 + kstep;
;             PG8_LDB(B0, 0, 0); PG8_SCHED; PG8_LDA(At, 0, 0); PG8_STAGE(PG8_SA(1, 1), a1 + hstep, voffA);
;             PG8_WAIT_L(8); PG8_BAR; PG8_WAIT_L(0); PG8_MMA(0, 0, At, B0); PG8_BAR; PG8_SCHED;
;             PG8_LDB(B1, 0, 1); PG8_STAGE(PG8_SB(0, 0), b2, voffB);
;             PG8_BAR; PG8_WAIT_L(0); PG8_MMA(0, 1, At, B1); PG8_BAR;
;             PG8_LDA(At, 0, 1); PG8_STAGE(PG8_SA(0, 0), a2, voffA);
;             PG8_BAR; PG8_WAIT_L(0); PG8_MMA(1, 0, At, B0); PG8_BAR; PG8_SCHED;
;             PG8_STAGE(PG8_SB(0, 1), b2 + hstep, voffB);
;             PG8_WAIT_V(6); PG8_BAR; PG8_MMA(1, 1, At, B1); PG8_BAR;
.LBB0_999:
	ds_read_b128 v[140:143], v151
	ds_read_b128 v[144:147], v151 offset:1024
	ds_read_b128 v[154:157], v151 offset:2048
	ds_read_b128 v[160:163], v151 offset:3072
	s_add_u32 s48, s46, 0xfff80080
	s_addc_u32 s49, s47, -1
	s_cmp_eq_u32 s63, 28
	s_cselect_b32 s51, s37, s49
	s_cselect_b32 s50, s59, s48
	s_cselect_b32 s49, s35, s62
	s_cselect_b32 s48, s60, s61
	s_add_i32 m0, s28, 0xc000
	ds_read_b128 v[164:167], v152
	ds_read_b128 v[168:171], v152 offset:1024
	ds_read_b128 v[172:175], v152 offset:2048
	ds_read_b128 v[176:179], v152 offset:3072
	ds_read_b128 v[180:183], v152 offset:4096
	ds_read_b128 v[184:187], v152 offset:5120
	ds_read_b128 v[188:191], v152 offset:6144
	ds_read_b128 v[192:195], v152 offset:7168
	global_load_lds_dwordx4 v136, s[46:47]
	s_add_i32 m0, s28, 0xe000
	s_nop 0
	global_load_lds_dwordx4 v138, s[46:47]
	s_waitcnt lgkmcnt(8)
	s_barrier
	s_waitcnt lgkmcnt(0)
	v_mfma_f32_16x16x32_bf16 v[124:127], v[140:143], v[164:167], v[124:127]
	v_mfma_f32_16x16x32_bf16 v[120:123], v[154:157], v[164:167], v[120:123]
	v_mfma_f32_16x16x32_bf16 v[108:111], v[140:143], v[172:175], v[108:111]
	v_mfma_f32_16x16x32_bf16 v[104:107], v[154:157], v[172:175], v[104:107]
	v_mfma_f32_16x16x32_bf16 v[92:95], v[140:143], v[180:183], v[92:95]
	v_mfma_f32_16x16x32_bf16 v[88:91], v[154:157], v[180:183], v[88:91]
	v_mfma_f32_16x16x32_bf16 v[76:79], v[140:143], v[188:191], v[76:79]
	v_mfma_f32_16x16x32_bf16 v[72:75], v[154:157], v[188:191], v[72:75]
	v_mfma_f32_16x16x32_bf16 v[124:127], v[144:147], v[168:171], v[124:127]
	v_mfma_f32_16x16x32_bf16 v[120:123], v[160:163], v[168:171], v[120:123]
	v_mfma_f32_16x16x32_bf16 v[108:111], v[144:147], v[176:179], v[108:111]
	v_mfma_f32_16x16x32_bf16 v[104:107], v[160:163], v[176:179], v[104:107]
	v_mfma_f32_16x16x32_bf16 v[92:95], v[144:147], v[184:187], v[92:95]
	v_mfma_f32_16x16x32_bf16 v[88:91], v[160:163], v[184:187], v[88:91]
	v_mfma_f32_16x16x32_bf16 v[76:79], v[144:147], v[192:195], v[76:79]
	v_mfma_f32_16x16x32_bf16 v[72:75], v[160:163], v[192:195], v[72:75]
	s_barrier
	s_add_i32 s64, s56, s23
	s_add_u32 s98, s48, s4
	s_addc_u32 s99, s49, s5
	s_mov_b32 m0, s64
	ds_read_b128 v[196:199], v153
	ds_read_b128 v[200:203], v153 offset:1024
	ds_read_b128 v[204:207], v153 offset:2048
	ds_read_b128 v[208:211], v153 offset:3072
	global_load_lds_dwordx4 v132, s[48:49]
	s_add_i32 m0, s64, 0x2000
	s_nop 0
	global_load_lds_dwordx4 v128, s[48:49]
	s_waitcnt lgkmcnt(0)
	s_barrier
	s_waitcnt lgkmcnt(0)
	v_mfma_f32_16x16x32_bf16 v[116:119], v[196:199], v[164:167], v[116:119]
	v_mfma_f32_16x16x32_bf16 v[112:115], v[204:207], v[164:167], v[112:115]
	v_mfma_f32_16x16x32_bf16 v[100:103], v[196:199], v[172:175], v[100:103]
	v_mfma_f32_16x16x32_bf16 v[96:99], v[204:207], v[172:175], v[96:99]
	v_mfma_f32_16x16x32_bf16 v[84:87], v[196:199], v[180:183], v[84:87]
	v_mfma_f32_16x16x32_bf16 v[80:83], v[204:207], v[180:183], v[80:83]
	v_mfma_f32_16x16x32_bf16 v[68:71], v[196:199], v[188:191], v[68:71]
	v_mfma_f32_16x16x32_bf16 v[64:67], v[204:207], v[188:191], v[64:67]
	v_mfma_f32_16x16x32_bf16 v[116:119], v[200:203], v[168:171], v[116:119]
	v_mfma_f32_16x16x32_bf16 v[112:115], v[208:211], v[168:171], v[112:115]
	v_mfma_f32_16x16x32_bf16 v[100:103], v[200:203], v[176:179], v[100:103]
	v_mfma_f32_16x16x32_bf16 v[96:99], v[208:211], v[176:179], v[96:99]
	v_mfma_f32_16x16x32_bf16 v[84:87], v[200:203], v[184:187], v[84:87]
	v_mfma_f32_16x16x32_bf16 v[80:83], v[208:211], v[184:187], v[80:83]
	v_mfma_f32_16x16x32_bf16 v[68:71], v[200:203], v[192:195], v[68:71]
	v_mfma_f32_16x16x32_bf16 v[64:67], v[208:211], v[192:195], v[64:67]
	s_mov_b32 m0, s28
	s_add_u32 s100, s50, s4
	s_addc_u32 s101, s51, s5
	s_barrier
	ds_read_b128 v[164:167], v152 offset:16384
	ds_read_b128 v[168:171], v152 offset:17408
	ds_read_b128 v[172:175], v152 offset:18432
	ds_read_b128 v[176:179], v152 offset:19456
	ds_read_b128 v[180:183], v152 offset:20480
	ds_read_b128 v[184:187], v152 offset:21504
	ds_read_b128 v[188:191], v152 offset:22528
	ds_read_b128 v[192:195], v152 offset:23552
	global_load_lds_dwordx4 v134, s[50:51]
	s_mov_b32 m0, s29
	s_nop 0
	global_load_lds_dwordx4 v130, s[50:51]
	s_add_u32 s64, s48, 0x80000
	s_addc_u32 s65, s49, 0
	s_add_i32 s66, s57, s23
	s_mov_b32 m0, s66
	s_nop 0
	global_load_lds_dwordx4 v132, s[64:65]
	s_add_i32 m0, s66, 0x2000
	s_nop 0
	global_load_lds_dwordx4 v128, s[64:65]
	s_waitcnt vmcnt(6)
	s_barrier
	s_waitcnt lgkmcnt(0)
	v_mfma_f32_16x16x32_bf16 v[60:63], v[140:143], v[164:167], v[60:63]
	v_mfma_f32_16x16x32_bf16 v[56:59], v[154:157], v[164:167], v[56:59]
	v_mfma_f32_16x16x32_bf16 v[44:47], v[140:143], v[172:175], v[44:47]
	v_mfma_f32_16x16x32_bf16 v[40:43], v[154:157], v[172:175], v[40:43]
	v_mfma_f32_16x16x32_bf16 v[28:31], v[140:143], v[180:183], v[28:31]
	v_mfma_f32_16x16x32_bf16 v[24:27], v[154:157], v[180:183], v[24:27]
	v_mfma_f32_16x16x32_bf16 v[12:15], v[140:143], v[188:191], v[12:15]
	v_mfma_f32_16x16x32_bf16 v[8:11], v[154:157], v[188:191], v[8:11]
	v_mfma_f32_16x16x32_bf16 v[60:63], v[144:147], v[168:171], v[60:63]
	v_mfma_f32_16x16x32_bf16 v[56:59], v[160:163], v[168:171], v[56:59]
	v_mfma_f32_16x16x32_bf16 v[44:47], v[144:147], v[176:179], v[44:47]
	v_mfma_f32_16x16x32_bf16 v[40:43], v[160:163], v[176:179], v[40:43]
	v_mfma_f32_16x16x32_bf16 v[28:31], v[144:147], v[184:187], v[28:31]
	v_mfma_f32_16x16x32_bf16 v[24:27], v[160:163], v[184:187], v[24:27]
	v_mfma_f32_16x16x32_bf16 v[12:15], v[144:147], v[192:195], v[12:15]
	v_mfma_f32_16x16x32_bf16 v[8:11], v[160:163], v[192:195], v[8:11]
	v_mfma_f32_16x16x32_bf16 v[52:55], v[196:199], v[164:167], v[52:55]
	v_mfma_f32_16x16x32_bf16 v[48:51], v[204:207], v[164:167], v[48:51]
	v_mfma_f32_16x16x32_bf16 v[36:39], v[196:199], v[172:175], v[36:39]
	v_mfma_f32_16x16x32_bf16 v[32:35], v[204:207], v[172:175], v[32:35]
	v_mfma_f32_16x16x32_bf16 v[20:23], v[196:199], v[180:183], v[20:23]
	v_mfma_f32_16x16x32_bf16 v[16:19], v[204:207], v[180:183], v[16:19]
	v_mfma_f32_16x16x32_bf16 v[4:7], v[196:199], v[188:191], v[4:7]
	v_mfma_f32_16x16x32_bf16 v[0:3], v[204:207], v[188:191], v[0:3]
	v_mfma_f32_16x16x32_bf16 v[52:55], v[200:203], v[168:171], v[52:55]
	v_mfma_f32_16x16x32_bf16 v[48:51], v[208:211], v[168:171], v[48:51]
	v_mfma_f32_16x16x32_bf16 v[36:39], v[200:203], v[176:179], v[36:39]
	v_mfma_f32_16x16x32_bf16 v[32:35], v[208:211], v[176:179], v[32:35]
	v_mfma_f32_16x16x32_bf16 v[20:23], v[200:203], v[184:187], v[20:23]
	v_mfma_f32_16x16x32_bf16 v[16:19], v[208:211], v[184:187], v[16:19]
	v_mfma_f32_16x16x32_bf16 v[4:7], v[200:203], v[192:195], v[4:7]
	v_mfma_f32_16x16x32_bf16 v[0:3], v[208:211], v[192:195], v[0:3]
	s_add_i32 s64, 0, 0x18000
	v_add_u32_e32 v160, s64, v149
	s_barrier
; #define PG8_STAGE(bufoff, gbase, voff) do { _Pragma("unroll") for (int _i = 0; _i < 2; ++_i) \
;         __builtin_amdgcn_global_load_lds((const unsigned*)((const char*)(gbase) + (voff)[_i]), (LAS unsigned*)(lds + (bufoff) + ldsw + _i * 8192), 16, 0, 0); } while (0)
; #define PG8_LDA(dst, b, h) do { _Pragma("unroll") for (int m = 0; m < 4; ++m) _Pragma("unroll") for (int k = 0; k < 2; ++k) dst[m][k] = *(const LAS bf16x8*)(lds + PG8_SA(b, h) + aoff + m * 2048 + k * 1024); } while (0)
; #define PG8_LDB(dst, b, h) do { _Pragma("unroll") for (int n = 0; n < 2; ++n) _Pragma("unroll") for (int k = 0; k < 2; ++k) dst[n][k] = *(const LAS bf16x8*)(lds + PG8_SB(b, h) + boff + n * 2048 + k * 1024); } while (0)
; #define PG8_MMA(ai, bj, At, Bt) do { __builtin_amdgcn_s_setprio(1); _Pragma("unroll") for (int m = 0; m < 4; ++m) _Pragma("unroll") for (int n = 0; n < 2; ++n) _Pragma("unroll") for (int k = 0; k < 2; ++k) \
;         acc[ai][bj][m][n] = __builtin_amdgcn_mfma_f32_16x16x32_bf16(Bt[n][k], At[m][k], acc[ai][bj][m][n], 0, 0, 0); __builtin_amdgcn_s_setprio(0); } while (0)
; #define PG8_WAIT_V(n) asm volatile("s_waitcnt vmcnt(" #n ")" ::: "memory")
; #define PG8_WAIT_L(n) asm volatile("s_waitcnt lgkmcnt(" #n ")" ::: "memory")
; #define PG8_BAR __builtin_amdgcn_s_barrier()
; #define PG8_SCHED __builtin_amdgcn_sched_barrier(0)
; template <class Epi>
; __device__ __forceinline__ void gemm_phase(LAS unsigned char* lds, const Gemm g, const StaticOrder& S, const Epi& E) {
;     ...
;         for (int t = 0; t < nt; t += 2) {
;     ...
;             PG8_LDB(B0, 1, 0); PG8_SCHED; PG8_LDA(At, 1, 0); PG8_STAGE(PG8_SA(0, 1), a2 + hstep, voffA);
;             PG8_WAIT_L(8); PG8_BAR; PG8_WAIT_L(0); PG8_MMA(0, 0, At, B0); PG8_BAR; PG8_SCHED;
;             PG8_LDB(B1, 1, 1); PG8_STAGE(PG8_SB(1, 0), b3, voffB);
;             PG8_BAR; PG8_WAIT_L(0); PG8_MMA(0, 1, At, B1); PG8_BAR;
;             PG8_LDA(At, 1, 1); PG8_STAGE(PG8_SA(1, 0), a3, voffA);
;             PG8_BAR; PG8_WAIT_L(0); PG8_MMA(1, 0, At, B0); PG8_BAR; PG8_SCHED;
;             PG8_STAGE(PG8_SB(1, 1), b3 + hstep, voffB);
;             PG8_WAIT_V(6); PG8_BAR; PG8_MMA(1, 1, At, B1); PG8_BAR;
	ds_read_b128 v[140:143], v160
	ds_read_b128 v[144:147], v160 offset:1024
	ds_read_b128 v[154:157], v160 offset:2048
	ds_read_b128 v[160:163], v160 offset:3072
	s_add_u32 s50, s50, 0x80000
	s_addc_u32 s51, s51, 0
	s_mov_b32 m0, s33
	ds_read_b128 v[164:167], v152 offset:32768
	ds_read_b128 v[168:171], v152 offset:33792
	ds_read_b128 v[172:175], v152 offset:34816
	ds_read_b128 v[176:179], v152 offset:35840
	ds_read_b128 v[180:183], v152 offset:36864
	ds_read_b128 v[184:187], v152 offset:37888
	ds_read_b128 v[188:191], v152 offset:38912
	ds_read_b128 v[192:195], v152 offset:39936
	global_load_lds_dwordx4 v134, s[50:51]
	s_mov_b32 m0, s45
	s_nop 0
	global_load_lds_dwordx4 v130, s[50:51]
	s_waitcnt lgkmcnt(8)
	s_barrier
	s_waitcnt lgkmcnt(0)
	v_mfma_f32_16x16x32_bf16 v[124:127], v[140:143], v[164:167], v[124:127]
	v_mfma_f32_16x16x32_bf16 v[120:123], v[154:157], v[164:167], v[120:123]
	v_mfma_f32_16x16x32_bf16 v[108:111], v[140:143], v[172:175], v[108:111]
	v_mfma_f32_16x16x32_bf16 v[104:107], v[154:157], v[172:175], v[104:107]
	v_mfma_f32_16x16x32_bf16 v[92:95], v[140:143], v[180:183], v[92:95]
	v_mfma_f32_16x16x32_bf16 v[88:91], v[154:157], v[180:183], v[88:91]
	v_mfma_f32_16x16x32_bf16 v[76:79], v[140:143], v[188:191], v[76:79]
	v_mfma_f32_16x16x32_bf16 v[72:75], v[154:157], v[188:191], v[72:75]
	v_mfma_f32_16x16x32_bf16 v[124:127], v[144:147], v[168:171], v[124:127]
	v_mfma_f32_16x16x32_bf16 v[120:123], v[160:163], v[168:171], v[120:123]
	v_mfma_f32_16x16x32_bf16 v[108:111], v[144:147], v[176:179], v[108:111]
	v_mfma_f32_16x16x32_bf16 v[104:107], v[160:163], v[176:179], v[104:107]
	v_mfma_f32_16x16x32_bf16 v[92:95], v[144:147], v[184:187], v[92:95]
	v_mfma_f32_16x16x32_bf16 v[88:91], v[160:163], v[184:187], v[88:91]
	v_mfma_f32_16x16x32_bf16 v[76:79], v[144:147], v[192:195], v[76:79]
	v_mfma_f32_16x16x32_bf16 v[72:75], v[160:163], v[192:195], v[72:75]
	s_barrier
	s_add_i32 s50, 0, 0x1c000
	s_add_i32 s51, s64, s23
	v_add_u32_e32 v208, s50, v149
	s_mov_b32 m0, s51
	ds_read_b128 v[196:199], v208
	ds_read_b128 v[200:203], v208 offset:1024
	ds_read_b128 v[204:207], v208 offset:2048
	ds_read_b128 v[208:211], v208 offset:3072
	global_load_lds_dwordx4 v132, s[98:99]
	s_add_i32 m0, s51, 0x2000
	s_nop 0
	global_load_lds_dwordx4 v128, s[98:99]
	s_waitcnt lgkmcnt(0)
	s_barrier
	s_waitcnt lgkmcnt(0)
	v_mfma_f32_16x16x32_bf16 v[116:119], v[196:199], v[164:167], v[116:119]
	v_mfma_f32_16x16x32_bf16 v[112:115], v[204:207], v[164:167], v[112:115]
	v_mfma_f32_16x16x32_bf16 v[100:103], v[196:199], v[172:175], v[100:103]
	v_mfma_f32_16x16x32_bf16 v[96:99], v[204:207], v[172:175], v[96:99]
	v_mfma_f32_16x16x32_bf16 v[84:87], v[196:199], v[180:183], v[84:87]
	v_mfma_f32_16x16x32_bf16 v[80:83], v[204:207], v[180:183], v[80:83]
	v_mfma_f32_16x16x32_bf16 v[68:71], v[196:199], v[188:191], v[68:71]
	v_mfma_f32_16x16x32_bf16 v[64:67], v[204:207], v[188:191], v[64:67]
	v_mfma_f32_16x16x32_bf16 v[116:119], v[200:203], v[168:171], v[116:119]
	v_mfma_f32_16x16x32_bf16 v[112:115], v[208:211], v[168:171], v[112:115]
	v_mfma_f32_16x16x32_bf16 v[100:103], v[200:203], v[176:179], v[100:103]
	v_mfma_f32_16x16x32_bf16 v[96:99], v[208:211], v[176:179], v[96:99]
	v_mfma_f32_16x16x32_bf16 v[84:87], v[200:203], v[184:187], v[84:87]
	v_mfma_f32_16x16x32_bf16 v[80:83], v[208:211], v[184:187], v[80:83]
	v_mfma_f32_16x16x32_bf16 v[68:71], v[200:203], v[192:195], v[68:71]
	v_mfma_f32_16x16x32_bf16 v[64:67], v[208:211], v[192:195], v[64:67]
	s_mov_b32 m0, s53
	s_barrier
	ds_read_b128 v[164:167], v152 offset:49152
	ds_read_b128 v[168:171], v152 offset:50176
	ds_read_b128 v[172:175], v152 offset:51200
	ds_read_b128 v[176:179], v152 offset:52224
	ds_read_b128 v[180:183], v152 offset:53248
	ds_read_b128 v[184:187], v152 offset:54272
	ds_read_b128 v[188:191], v152 offset:55296
	ds_read_b128 v[192:195], v152 offset:56320
	global_load_lds_dwordx4 v134, s[100:101]
	s_mov_b32 m0, s54
	s_nop 0
	global_load_lds_dwordx4 v130, s[100:101]
	s_add_u32 s48, s48, 0x80080
	s_addc_u32 s49, s49, 0
	s_add_i32 s50, s50, s23
	s_mov_b32 m0, s50
	s_nop 0
	global_load_lds_dwordx4 v132, s[48:49]
	s_add_i32 m0, s50, 0x2000
	s_nop 0
	global_load_lds_dwordx4 v128, s[48:49]
	s_waitcnt vmcnt(6)
	s_barrier
	s_waitcnt lgkmcnt(0)
	v_mfma_f32_16x16x32_bf16 v[60:63], v[140:143], v[164:167], v[60:63]
	v_mfma_f32_16x16x32_bf16 v[56:59], v[154:157], v[164:167], v[56:59]
	v_mfma_f32_16x16x32_bf16 v[44:47], v[140:143], v[172:175], v[44:47]
	v_mfma_f32_16x16x32_bf16 v[40:43], v[154:157], v[172:175], v[40:43]
	v_mfma_f32_16x16x32_bf16 v[28:31], v[140:143], v[180:183], v[28:31]
	v_mfma_f32_16x16x32_bf16 v[24:27], v[154:157], v[180:183], v[24:27]
	v_mfma_f32_16x16x32_bf16 v[12:15], v[140:143], v[188:191], v[12:15]
	v_mfma_f32_16x16x32_bf16 v[8:11], v[154:157], v[188:191], v[8:11]
	v_mfma_f32_16x16x32_bf16 v[60:63], v[144:147], v[168:171], v[60:63]
	v_mfma_f32_16x16x32_bf16 v[56:59], v[160:163], v[168:171], v[56:59]
	v_mfma_f32_16x16x32_bf16 v[44:47], v[144:147], v[176:179], v[44:47]
	v_mfma_f32_16x16x32_bf16 v[40:43], v[160:163], v[176:179], v[40:43]
	v_mfma_f32_16x16x32_bf16 v[28:31], v[144:147], v[184:187], v[28:31]
	v_mfma_f32_16x16x32_bf16 v[24:27], v[160:163], v[184:187], v[24:27]
	v_mfma_f32_16x16x32_bf16 v[12:15], v[144:147], v[192:195], v[12:15]
	v_mfma_f32_16x16x32_bf16 v[8:11], v[160:163], v[192:195], v[8:11]
	v_mfma_f32_16x16x32_bf16 v[52:55], v[196:199], v[164:167], v[52:55]
	v_mfma_f32_16x16x32_bf16 v[48:51], v[204:207], v[164:167], v[48:51]
	v_mfma_f32_16x16x32_bf16 v[36:39], v[196:199], v[172:175], v[36:39]
	v_mfma_f32_16x16x32_bf16 v[32:35], v[204:207], v[172:175], v[32:35]
	v_mfma_f32_16x16x32_bf16 v[20:23], v[196:199], v[180:183], v[20:23]
	v_mfma_f32_16x16x32_bf16 v[16:19], v[204:207], v[180:183], v[16:19]
	v_mfma_f32_16x16x32_bf16 v[4:7], v[196:199], v[188:191], v[4:7]
	v_mfma_f32_16x16x32_bf16 v[0:3], v[204:207], v[188:191], v[0:3]
	v_mfma_f32_16x16x32_bf16 v[52:55], v[200:203], v[168:171], v[52:55]
	v_mfma_f32_16x16x32_bf16 v[48:51], v[208:211], v[168:171], v[48:51]
	v_mfma_f32_16x16x32_bf16 v[36:39], v[200:203], v[176:179], v[36:39]
	v_mfma_f32_16x16x32_bf16 v[32:35], v[208:211], v[176:179], v[32:35]
	v_mfma_f32_16x16x32_bf16 v[20:23], v[200:203], v[184:187], v[20:23]
	v_mfma_f32_16x16x32_bf16 v[16:19], v[208:211], v[184:187], v[16:19]
	v_mfma_f32_16x16x32_bf16 v[4:7], v[200:203], v[192:195], v[4:7]
	v_mfma_f32_16x16x32_bf16 v[0:3], v[208:211], v[192:195], v[0:3]
	s_add_i32 s63, s63, 2
	s_add_u32 s46, s46, 0x100
	s_addc_u32 s47, s47, 0
	s_add_u32 s61, s61, 0x100
	s_addc_u32 s62, s62, 0
	s_cmp_gt_u32 s63, 29
	s_barrier
; __device__ __forceinline__ float bf_lo(unsigned w) { return __uint_as_float(w << 16); }
; __device__ __forceinline__ float bf_hi(unsigned w) { return __uint_as_float(w & 0xffff0000u); }
; __device__ __forceinline__ float fast_rcp(float x) { return __builtin_amdgcn_rcpf(x); }
; __device__ __forceinline__ float fast_exp2(float x) { return __builtin_amdgcn_exp2f(x); }
; __device__ __forceinline__ u32x4 pack8(f32x4 v0, f32x4 v1) { u32x4 w; w.x = cvt_pk_bf16(v0[0], v0[1]); w.y = cvt_pk_bf16(v0[2], v0[3]); w.z = cvt_pk_bf16(v1[0], v1[1]); w.w = cvt_pk_bf16(v1[2], v1[3]); return w; }
; template <class Epi>
; __device__ __forceinline__ void gemm_phase(LAS unsigned char* lds, const Gemm g, const StaticOrder& S, const Epi& E) {
;     ...
;         const bool has_next = S.next(ui + 1, nxt);
;     __device__ __forceinline__ void operator()(const f32x4 (&acc)[2][2][4][2], const Unit& u, int wr, int wc, int fr, int fq) const {
;         const int row0 = u.pm * BM + wr * 64 + fr, col0 = u.pn * BM + wc * 32 + 8 * fq;
; #pragma unroll
;         for (int ai = 0; ai < 2; ++ai)
; #pragma unroll
;             for (int m = 0; m < 4; ++m) { const size_t ro = (size_t)(row0 + ai * HALF + m * 16) * DM + col0; const float nr = -LOG2E * rs[row0 + ai * HALF + m * 16];
; #pragma unroll
;                 for (int bj = 0; bj < 2; ++bj) {
;                     const u32x4 pw = *(const u32x4*)(PP + ro + bj * HALF);
;                     const float pv[8] = {bf_lo(pw.x), bf_hi(pw.x), bf_lo(pw.y), bf_hi(pw.y), bf_lo(pw.z), bf_hi(pw.z), bf_lo(pw.w), bf_hi(pw.w)};
;                     f32x4 t0, t1;
; #pragma unroll
;                     for (int j = 0; j < 4; ++j) {
;                         t0[j] = fast_rcp(1.0f + fast_exp2(acc[ai][bj][m][0][j] * nr)) * pv[j];
;                         t1[j] = fast_rcp(1.0f + fast_exp2(acc[ai][bj][m][1][j] * nr)) * pv[4 + j]; }
;                     *(u32x4*)(O + ro + bj * HALF) = pack8(t0, t1); } }
	s_cbranch_scc0 .LBB0_999
	v_lshl_add_u32 v144, s44, 8, v148
	v_ashrrev_i32_e32 v145, 31, v144
	v_lshl_add_u64 v[140:141], v[144:145], 2, s[14:15]
	global_load_dword v164, v[140:141], off
	v_lshl_or_b32 v146, s58, 8, v150
	v_ashrrev_i32_e32 v147, 31, v146
	v_lshlrev_b64 v[142:143], 11, v[144:145]
	v_lshl_add_u64 v[142:143], v[142:143], 0, v[146:147]
	v_lshlrev_b64 v[142:143], 1, v[142:143]
	v_lshl_add_u64 v[160:161], s[20:21], 0, v[142:143]
	global_load_dwordx4 v[154:157], v[160:161], off
	global_load_dwordx4 v[220:223], v[160:161], off offset:256
	v_lshl_add_u64 v[162:163], s[24:25], 0, v[142:143]
	s_and_b64 vcc, exec, s[38:39]
	s_mov_b32 s58, s34
	s_mov_b32 s44, s36
	s_mov_b64 s[48:49], s[42:43]
	s_mov_b64 s[46:47], s[40:41]
	s_waitcnt vmcnt(0)
	v_mul_f32_e32 v145, 0xbfb8aa3b, v164
	v_mul_f32_e32 v124, v124, v145
	v_mul_f32_e32 v120, v120, v145
	v_mul_f32_e32 v125, v125, v145
	v_mul_f32_e32 v121, v121, v145
	v_mul_f32_e32 v126, v126, v145
	v_mul_f32_e32 v122, v122, v145
	v_mul_f32_e32 v127, v127, v145
	v_mul_f32_e32 v123, v123, v145
	v_exp_f32_e32 v124, v124
	v_exp_f32_e32 v120, v120
	v_exp_f32_e32 v125, v125
	v_exp_f32_e32 v121, v121
	v_exp_f32_e32 v126, v126
	v_exp_f32_e32 v122, v122
	v_exp_f32_e32 v127, v127
	v_exp_f32_e32 v123, v123
	v_add_f32_e32 v124, 1.0, v124
	v_add_f32_e32 v120, 1.0, v120
	v_add_f32_e32 v125, 1.0, v125
	v_add_f32_e32 v121, 1.0, v121
	v_add_f32_e32 v126, 1.0, v126
	v_add_f32_e32 v122, 1.0, v122
	v_add_f32_e32 v127, 1.0, v127
	v_add_f32_e32 v123, 1.0, v123
	v_rcp_f32_e32 v124, v124
	v_rcp_f32_e32 v120, v120
	v_rcp_f32_e32 v125, v125
	v_rcp_f32_e32 v121, v121
	v_rcp_f32_e32 v126, v126
	v_rcp_f32_e32 v122, v122
	v_rcp_f32_e32 v127, v127
	v_rcp_f32_e32 v123, v123
	v_lshlrev_b32_e32 v164, 16, v154
	v_and_b32_e32 v154, 0xffff0000, v154
	v_lshlrev_b32_e32 v165, 16, v155
	v_and_b32_e32 v155, 0xffff0000, v155
	v_lshlrev_b32_e32 v166, 16, v156
	v_and_b32_e32 v156, 0xffff0000, v156
	v_lshlrev_b32_e32 v167, 16, v157
	v_and_b32_e32 v157, 0xffff0000, v157
	v_mul_f32_e32 v124, v124, v164
	v_mul_f32_e32 v164, v120, v166
	v_mul_f32_e32 v120, v125, v154
	v_mul_f32_e32 v125, v121, v156
	v_mul_f32_e32 v121, v126, v165
	v_mul_f32_e32 v126, v122, v167
	v_mul_f32_e32 v122, v127, v155
	v_mul_f32_e32 v123, v123, v157
	v_cvt_pk_bf16_f32 v120, v124, v120
	v_cvt_pk_bf16_f32 v121, v121, v122
	v_cvt_pk_bf16_f32 v122, v164, v125
	v_cvt_pk_bf16_f32 v123, v126, v123
	global_store_dwordx4 v[162:163], v[120:123], off
	v_mul_f32_e32 v116, v116, v145
	v_mul_f32_e32 v112, v112, v145
	v_mul_f32_e32 v117, v117, v145
	v_mul_f32_e32 v113, v113, v145
	v_mul_f32_e32 v118, v118, v145
	v_mul_f32_e32 v114, v114, v145
	v_mul_f32_e32 v119, v119, v145
	v_mul_f32_e32 v115, v115, v145
	v_exp_f32_e32 v116, v116
	v_exp_f32_e32 v112, v112
	v_exp_f32_e32 v117, v117
	v_exp_f32_e32 v113, v113
	v_exp_f32_e32 v118, v118
	v_exp_f32_e32 v114, v114
	v_exp_f32_e32 v119, v119
	v_exp_f32_e32 v115, v115
	v_add_f32_e32 v116, 1.0, v116
	v_add_f32_e32 v112, 1.0, v112
	v_add_f32_e32 v117, 1.0, v117
	v_add_f32_e32 v113, 1.0, v113
	v_add_f32_e32 v118, 1.0, v118
	v_add_f32_e32 v114, 1.0, v114
	v_add_f32_e32 v119, 1.0, v119
	v_add_f32_e32 v115, 1.0, v115
	v_rcp_f32_e32 v116, v116
	v_rcp_f32_e32 v112, v112
	v_rcp_f32_e32 v117, v117
	v_rcp_f32_e32 v113, v113
	v_rcp_f32_e32 v118, v118
	v_rcp_f32_e32 v114, v114
	v_rcp_f32_e32 v119, v119
	v_rcp_f32_e32 v115, v115
	v_or_b32_e32 v124, 16, v144
	v_ashrrev_i32_e32 v125, 31, v124
	v_lshlrev_b64 v[124:125], 11, v[124:125]
	v_lshl_add_u64 v[124:125], v[124:125], 0, v[146:147]
	v_lshlrev_b64 v[124:125], 1, v[124:125]
	v_lshl_add_u64 v[126:127], s[20:21], 0, v[124:125]
	v_lshlrev_b32_e32 v145, 16, v220
	v_and_b32_e32 v120, 0xffff0000, v220
	v_lshlrev_b32_e32 v154, 16, v221
	v_and_b32_e32 v121, 0xffff0000, v221
	v_lshlrev_b32_e32 v155, 16, v222
	v_and_b32_e32 v122, 0xffff0000, v222
	v_lshlrev_b32_e32 v156, 16, v223
	v_and_b32_e32 v123, 0xffff0000, v223
	v_mul_f32_e32 v116, v116, v145
	v_mul_f32_e32 v145, v112, v155
	v_mul_f32_e32 v112, v117, v120
	v_mul_f32_e32 v117, v113, v122
	v_mul_f32_e32 v113, v118, v154
	v_mul_f32_e32 v118, v114, v156
	v_mul_f32_e32 v114, v119, v121
	v_mul_f32_e32 v115, v115, v123
	v_cvt_pk_bf16_f32 v112, v116, v112
	v_cvt_pk_bf16_f32 v113, v113, v114
	v_cvt_pk_bf16_f32 v114, v145, v117
	v_cvt_pk_bf16_f32 v115, v118, v115
	global_store_dwordx4 v[162:163], v[112:115], off offset:256
	global_load_dword v118, v[140:141], off offset:64
	s_nop 0
	global_load_dwordx4 v[112:115], v[126:127], off
	global_load_dwordx4 v[224:227], v[126:127], off offset:256
	v_lshl_add_u64 v[116:117], s[24:25], 0, v[124:125]
	s_waitcnt vmcnt(0)
; __device__ __forceinline__ float bf_lo(unsigned w) { return __uint_as_float(w << 16); }
; __device__ __forceinline__ float bf_hi(unsigned w) { return __uint_as_float(w & 0xffff0000u); }
; __device__ __forceinline__ float fast_rcp(float x) { return __builtin_amdgcn_rcpf(x); }
; __device__ __forceinline__ float fast_exp2(float x) { return __builtin_amdgcn_exp2f(x); }
; __device__ __forceinline__ u32x4 pack8(f32x4 v0, f32x4 v1) { u32x4 w; w.x = cvt_pk_bf16(v0[0], v0[1]); w.y = cvt_pk_bf16(v0[2], v0[3]); w.z = cvt_pk_bf16(v1[0], v1[1]); w.w = cvt_pk_bf16(v1[2], v1[3]); return w; }
;     __device__ __forceinline__ void operator()(const f32x4 (&acc)[2][2][4][2], const Unit& u, int wr, int wc, int fr, int fq) const {
;     ...
;             for (int m = 0; m < 4; ++m) { const size_t ro = (size_t)(row0 + ai * HALF + m * 16) * DM + col0; const float nr = -LOG2E * rs[row0 + ai * HALF + m * 16];
; #pragma unroll
;                 for (int bj = 0; bj < 2; ++bj) {
;                     const u32x4 pw = *(const u32x4*)(PP + ro + bj * HALF);
;                     const float pv[8] = {bf_lo(pw.x), bf_hi(pw.x), bf_lo(pw.y), bf_hi(pw.y), bf_lo(pw.z), bf_hi(pw.z), bf_lo(pw.w), bf_hi(pw.w)};
;                     f32x4 t0, t1;
; #pragma unroll
;                     for (int j = 0; j < 4; ++j) {
;                         t0[j] = fast_rcp(1.0f + fast_exp2(acc[ai][bj][m][0][j] * nr)) * pv[j];
;                         t1[j] = fast_rcp(1.0f + fast_exp2(acc[ai][bj][m][1][j] * nr)) * pv[4 + j]; }
;                     *(u32x4*)(O + ro + bj * HALF) = pack8(t0, t1); } }
	v_mul_f32_e32 v118, 0xbfb8aa3b, v118
	v_mul_f32_e32 v108, v108, v118
	v_mul_f32_e32 v104, v104, v118
	v_mul_f32_e32 v109, v109, v118
	v_mul_f32_e32 v105, v105, v118
	v_mul_f32_e32 v110, v110, v118
	v_mul_f32_e32 v106, v106, v118
	v_mul_f32_e32 v111, v111, v118
	v_mul_f32_e32 v107, v107, v118
	v_exp_f32_e32 v108, v108
	v_exp_f32_e32 v104, v104
	v_exp_f32_e32 v109, v109
	v_exp_f32_e32 v105, v105
	v_exp_f32_e32 v110, v110
	v_exp_f32_e32 v106, v106
	v_exp_f32_e32 v111, v111
	v_exp_f32_e32 v107, v107
	v_add_f32_e32 v108, 1.0, v108
	v_add_f32_e32 v104, 1.0, v104
	v_add_f32_e32 v109, 1.0, v109
	v_add_f32_e32 v105, 1.0, v105
	v_add_f32_e32 v110, 1.0, v110
	v_add_f32_e32 v106, 1.0, v106
	v_add_f32_e32 v111, 1.0, v111
	v_add_f32_e32 v107, 1.0, v107
	v_rcp_f32_e32 v108, v108
	v_rcp_f32_e32 v104, v104
	v_rcp_f32_e32 v109, v109
	v_rcp_f32_e32 v105, v105
	v_rcp_f32_e32 v110, v110
	v_rcp_f32_e32 v106, v106
	v_rcp_f32_e32 v111, v111
	v_rcp_f32_e32 v107, v107
	v_lshlrev_b32_e32 v119, 16, v112
	v_and_b32_e32 v112, 0xffff0000, v112
	v_lshlrev_b32_e32 v120, 16, v113
	v_and_b32_e32 v113, 0xffff0000, v113
	v_lshlrev_b32_e32 v121, 16, v114
	v_and_b32_e32 v114, 0xffff0000, v114
	v_lshlrev_b32_e32 v122, 16, v115
	v_and_b32_e32 v115, 0xffff0000, v115
	v_mul_f32_e32 v108, v108, v119
	v_mul_f32_e32 v119, v104, v121
	v_mul_f32_e32 v104, v109, v112
	v_mul_f32_e32 v109, v105, v114
	v_mul_f32_e32 v105, v110, v120
	v_mul_f32_e32 v110, v106, v122
	v_mul_f32_e32 v106, v111, v113
	v_mul_f32_e32 v107, v107, v115
	v_cvt_pk_bf16_f32 v104, v108, v104
	v_cvt_pk_bf16_f32 v105, v105, v106
	v_cvt_pk_bf16_f32 v106, v119, v109
	v_cvt_pk_bf16_f32 v107, v110, v107
	global_store_dwordx4 v[116:117], v[104:107], off
	v_mul_f32_e32 v100, v100, v118
	v_mul_f32_e32 v96, v96, v118
	v_mul_f32_e32 v101, v101, v118
	v_mul_f32_e32 v97, v97, v118
	v_mul_f32_e32 v102, v102, v118
	v_mul_f32_e32 v98, v98, v118
	v_mul_f32_e32 v103, v103, v118
	v_mul_f32_e32 v99, v99, v118
	v_exp_f32_e32 v100, v100
	v_exp_f32_e32 v96, v96
	v_exp_f32_e32 v101, v101
	v_exp_f32_e32 v97, v97
	v_exp_f32_e32 v102, v102
	v_exp_f32_e32 v98, v98
	v_exp_f32_e32 v103, v103
	v_exp_f32_e32 v99, v99
	v_add_f32_e32 v100, 1.0, v100
	v_add_f32_e32 v96, 1.0, v96
	v_add_f32_e32 v101, 1.0, v101
	v_add_f32_e32 v97, 1.0, v97
	v_add_f32_e32 v102, 1.0, v102
	v_add_f32_e32 v98, 1.0, v98
	v_add_f32_e32 v103, 1.0, v103
	v_add_f32_e32 v99, 1.0, v99
	v_rcp_f32_e32 v100, v100
	v_rcp_f32_e32 v96, v96
	v_rcp_f32_e32 v101, v101
	v_rcp_f32_e32 v97, v97
	v_rcp_f32_e32 v102, v102
	v_rcp_f32_e32 v98, v98
	v_rcp_f32_e32 v103, v103
	v_rcp_f32_e32 v99, v99
	v_or_b32_e32 v108, 32, v144
	v_ashrrev_i32_e32 v109, 31, v108
	v_lshlrev_b64 v[108:109], 11, v[108:109]
	v_lshl_add_u64 v[108:109], v[108:109], 0, v[146:147]
	v_lshlrev_b64 v[108:109], 1, v[108:109]
	v_lshl_add_u64 v[110:111], s[20:21], 0, v[108:109]
	v_lshlrev_b32_e32 v112, 16, v224
	v_and_b32_e32 v104, 0xffff0000, v224
	v_lshlrev_b32_e32 v113, 16, v225
	v_and_b32_e32 v105, 0xffff0000, v225
	v_lshlrev_b32_e32 v114, 16, v226
	v_and_b32_e32 v106, 0xffff0000, v226
	v_lshlrev_b32_e32 v115, 16, v227
	v_and_b32_e32 v107, 0xffff0000, v227
	v_mul_f32_e32 v100, v100, v112
	v_mul_f32_e32 v112, v96, v114
	v_mul_f32_e32 v96, v101, v104
	v_mul_f32_e32 v101, v97, v106
	v_mul_f32_e32 v97, v102, v113
	v_mul_f32_e32 v102, v98, v115
	v_mul_f32_e32 v98, v103, v105
	v_mul_f32_e32 v99, v99, v107
	v_cvt_pk_bf16_f32 v96, v100, v96
	v_cvt_pk_bf16_f32 v97, v97, v98
	v_cvt_pk_bf16_f32 v98, v112, v101
	v_cvt_pk_bf16_f32 v99, v102, v99
	global_store_dwordx4 v[116:117], v[96:99], off offset:256
	global_load_dword v102, v[140:141], off offset:128
	s_nop 0
	global_load_dwordx4 v[96:99], v[110:111], off
	global_load_dwordx4 v[220:223], v[110:111], off offset:256
	v_lshl_add_u64 v[100:101], s[24:25], 0, v[108:109]
	s_waitcnt vmcnt(0)
	v_mul_f32_e32 v102, 0xbfb8aa3b, v102
	v_mul_f32_e32 v92, v92, v102
	v_mul_f32_e32 v88, v88, v102
	v_mul_f32_e32 v93, v93, v102
	v_mul_f32_e32 v89, v89, v102
	v_mul_f32_e32 v94, v94, v102
	v_mul_f32_e32 v90, v90, v102
	v_mul_f32_e32 v95, v95, v102
	v_mul_f32_e32 v91, v91, v102
	v_exp_f32_e32 v92, v92
	v_exp_f32_e32 v88, v88
	v_exp_f32_e32 v93, v93
	v_exp_f32_e32 v89, v89
	v_exp_f32_e32 v94, v94
	v_exp_f32_e32 v90, v90
	v_exp_f32_e32 v95, v95
	v_exp_f32_e32 v91, v91
	v_add_f32_e32 v92, 1.0, v92
	v_add_f32_e32 v88, 1.0, v88
	v_add_f32_e32 v93, 1.0, v93
	v_add_f32_e32 v89, 1.0, v89
	v_add_f32_e32 v94, 1.0, v94
	v_add_f32_e32 v90, 1.0, v90
	v_add_f32_e32 v95, 1.0, v95
	v_add_f32_e32 v91, 1.0, v91
	v_rcp_f32_e32 v92, v92
	v_rcp_f32_e32 v88, v88
	v_rcp_f32_e32 v93, v93
	v_rcp_f32_e32 v89, v89
	v_rcp_f32_e32 v94, v94
	v_rcp_f32_e32 v90, v90
	v_rcp_f32_e32 v95, v95
	v_rcp_f32_e32 v91, v91
	v_lshlrev_b32_e32 v103, 16, v96
	v_and_b32_e32 v96, 0xffff0000, v96
	v_lshlrev_b32_e32 v104, 16, v97
	v_and_b32_e32 v97, 0xffff0000, v97
	v_lshlrev_b32_e32 v105, 16, v98
	v_and_b32_e32 v98, 0xffff0000, v98
	v_lshlrev_b32_e32 v106, 16, v99
	v_and_b32_e32 v99, 0xffff0000, v99
	v_mul_f32_e32 v92, v92, v103
	v_mul_f32_e32 v103, v88, v105
	v_mul_f32_e32 v88, v93, v96
	v_mul_f32_e32 v93, v89, v98
	v_mul_f32_e32 v89, v94, v104
	v_mul_f32_e32 v94, v90, v106
	v_mul_f32_e32 v90, v95, v97
	v_mul_f32_e32 v91, v91, v99
	v_cvt_pk_bf16_f32 v88, v92, v88
	v_cvt_pk_bf16_f32 v89, v89, v90
	v_cvt_pk_bf16_f32 v90, v103, v93
	v_cvt_pk_bf16_f32 v91, v94, v91
	global_store_dwordx4 v[100:101], v[88:91], off
	v_mul_f32_e32 v84, v84, v102
	v_mul_f32_e32 v80, v80, v102
	v_mul_f32_e32 v85, v85, v102
	v_mul_f32_e32 v81, v81, v102
	v_mul_f32_e32 v86, v86, v102
	v_mul_f32_e32 v82, v82, v102
	v_mul_f32_e32 v87, v87, v102
	v_mul_f32_e32 v83, v83, v102
; __device__ __forceinline__ float bf_lo(unsigned w) { return __uint_as_float(w << 16); }
; __device__ __forceinline__ float bf_hi(unsigned w) { return __uint_as_float(w & 0xffff0000u); }
; __device__ __forceinline__ float fast_rcp(float x) { return __builtin_amdgcn_rcpf(x); }
; __device__ __forceinline__ float fast_exp2(float x) { return __builtin_amdgcn_exp2f(x); }
; __device__ __forceinline__ u32x4 pack8(f32x4 v0, f32x4 v1) { u32x4 w; w.x = cvt_pk_bf16(v0[0], v0[1]); w.y = cvt_pk_bf16(v0[2], v0[3]); w.z = cvt_pk_bf16(v1[0], v1[1]); w.w = cvt_pk_bf16(v1[2], v1[3]); return w; }
;     __device__ __forceinline__ void operator()(const f32x4 (&acc)[2][2][4][2], const Unit& u, int wr, int wc, int fr, int fq) const {
;     ...
;             for (int m = 0; m < 4; ++m) { const size_t ro = (size_t)(row0 + ai * HALF + m * 16) * DM + col0; const float nr = -LOG2E * rs[row0 + ai * HALF + m * 16];
; #pragma unroll
;                 for (int bj = 0; bj < 2; ++bj) {
;                     const u32x4 pw = *(const u32x4*)(PP + ro + bj * HALF);
;                     const float pv[8] = {bf_lo(pw.x), bf_hi(pw.x), bf_lo(pw.y), bf_hi(pw.y), bf_lo(pw.z), bf_hi(pw.z), bf_lo(pw.w), bf_hi(pw.w)};
;                     f32x4 t0, t1;
; #pragma unroll
;                     for (int j = 0; j < 4; ++j) {
;                         t0[j] = fast_rcp(1.0f + fast_exp2(acc[ai][bj][m][0][j] * nr)) * pv[j];
;                         t1[j] = fast_rcp(1.0f + fast_exp2(acc[ai][bj][m][1][j] * nr)) * pv[4 + j]; }
;                     *(u32x4*)(O + ro + bj * HALF) = pack8(t0, t1); } }
	v_exp_f32_e32 v84, v84
	v_exp_f32_e32 v80, v80
	v_exp_f32_e32 v85, v85
	v_exp_f32_e32 v81, v81
	v_exp_f32_e32 v86, v86
	v_exp_f32_e32 v82, v82
	v_exp_f32_e32 v87, v87
	v_exp_f32_e32 v83, v83
	v_add_f32_e32 v84, 1.0, v84
	v_add_f32_e32 v80, 1.0, v80
	v_add_f32_e32 v85, 1.0, v85
	v_add_f32_e32 v81, 1.0, v81
	v_add_f32_e32 v86, 1.0, v86
	v_add_f32_e32 v82, 1.0, v82
	v_add_f32_e32 v87, 1.0, v87
	v_add_f32_e32 v83, 1.0, v83
	v_rcp_f32_e32 v84, v84
	v_rcp_f32_e32 v80, v80
	v_rcp_f32_e32 v85, v85
	v_rcp_f32_e32 v81, v81
	v_rcp_f32_e32 v86, v86
	v_rcp_f32_e32 v82, v82
	v_rcp_f32_e32 v87, v87
	v_rcp_f32_e32 v83, v83
	v_or_b32_e32 v92, 48, v144
	v_ashrrev_i32_e32 v93, 31, v92
	v_lshlrev_b64 v[92:93], 11, v[92:93]
	v_lshl_add_u64 v[92:93], v[92:93], 0, v[146:147]
	v_lshlrev_b64 v[92:93], 1, v[92:93]
	v_lshl_add_u64 v[94:95], s[20:21], 0, v[92:93]
	v_lshlrev_b32_e32 v96, 16, v220
	v_and_b32_e32 v88, 0xffff0000, v220
	v_lshlrev_b32_e32 v97, 16, v221
	v_and_b32_e32 v89, 0xffff0000, v221
	v_lshlrev_b32_e32 v98, 16, v222
	v_and_b32_e32 v90, 0xffff0000, v222
	v_lshlrev_b32_e32 v99, 16, v223
	v_and_b32_e32 v91, 0xffff0000, v223
	v_mul_f32_e32 v84, v84, v96
	v_mul_f32_e32 v96, v80, v98
	v_mul_f32_e32 v80, v85, v88
	v_mul_f32_e32 v85, v81, v90
	v_mul_f32_e32 v81, v86, v97
	v_mul_f32_e32 v86, v82, v99
	v_mul_f32_e32 v82, v87, v89
	v_mul_f32_e32 v83, v83, v91
	v_cvt_pk_bf16_f32 v80, v84, v80
	v_cvt_pk_bf16_f32 v81, v81, v82
	v_cvt_pk_bf16_f32 v82, v96, v85
	v_cvt_pk_bf16_f32 v83, v86, v83
	global_store_dwordx4 v[100:101], v[80:83], off offset:256
	global_load_dword v86, v[140:141], off offset:192
	s_nop 0
	global_load_dwordx4 v[80:83], v[94:95], off
	global_load_dwordx4 v[224:227], v[94:95], off offset:256
	v_lshl_add_u64 v[84:85], s[24:25], 0, v[92:93]
	s_waitcnt vmcnt(0)
	v_mul_f32_e32 v86, 0xbfb8aa3b, v86
	v_mul_f32_e32 v76, v76, v86
	v_mul_f32_e32 v72, v72, v86
	v_mul_f32_e32 v77, v77, v86
	v_mul_f32_e32 v73, v73, v86
	v_mul_f32_e32 v78, v78, v86
	v_mul_f32_e32 v74, v74, v86
	v_mul_f32_e32 v79, v79, v86
	v_mul_f32_e32 v75, v75, v86
	v_exp_f32_e32 v76, v76
	v_exp_f32_e32 v72, v72
	v_exp_f32_e32 v77, v77
	v_exp_f32_e32 v73, v73
	v_exp_f32_e32 v78, v78
	v_exp_f32_e32 v74, v74
	v_exp_f32_e32 v79, v79
	v_exp_f32_e32 v75, v75
	v_add_f32_e32 v76, 1.0, v76
	v_add_f32_e32 v72, 1.0, v72
	v_add_f32_e32 v77, 1.0, v77
	v_add_f32_e32 v73, 1.0, v73
	v_add_f32_e32 v78, 1.0, v78
	v_add_f32_e32 v74, 1.0, v74
	v_add_f32_e32 v79, 1.0, v79
	v_add_f32_e32 v75, 1.0, v75
	v_rcp_f32_e32 v76, v76
	v_rcp_f32_e32 v72, v72
	v_rcp_f32_e32 v77, v77
	v_rcp_f32_e32 v73, v73
	v_rcp_f32_e32 v78, v78
	v_rcp_f32_e32 v74, v74
	v_rcp_f32_e32 v79, v79
	v_rcp_f32_e32 v75, v75
	v_lshlrev_b32_e32 v87, 16, v80
	v_and_b32_e32 v80, 0xffff0000, v80
	v_lshlrev_b32_e32 v88, 16, v81
	v_and_b32_e32 v81, 0xffff0000, v81
	v_lshlrev_b32_e32 v89, 16, v82
	v_and_b32_e32 v82, 0xffff0000, v82
	v_lshlrev_b32_e32 v90, 16, v83
	v_and_b32_e32 v83, 0xffff0000, v83
	v_mul_f32_e32 v76, v76, v87
	v_mul_f32_e32 v87, v72, v89
	v_mul_f32_e32 v72, v77, v80
	v_mul_f32_e32 v77, v73, v82
	v_mul_f32_e32 v73, v78, v88
	v_mul_f32_e32 v78, v74, v90
	v_mul_f32_e32 v74, v79, v81
	v_mul_f32_e32 v75, v75, v83
	v_cvt_pk_bf16_f32 v72, v76, v72
	v_cvt_pk_bf16_f32 v73, v73, v74
	v_cvt_pk_bf16_f32 v74, v87, v77
	v_cvt_pk_bf16_f32 v75, v78, v75
	global_store_dwordx4 v[84:85], v[72:75], off
	v_mul_f32_e32 v68, v68, v86
	v_mul_f32_e32 v64, v64, v86
	v_mul_f32_e32 v69, v69, v86
	v_mul_f32_e32 v65, v65, v86
	v_mul_f32_e32 v70, v70, v86
	v_mul_f32_e32 v66, v66, v86
	v_mul_f32_e32 v71, v71, v86
	v_mul_f32_e32 v67, v67, v86
	v_exp_f32_e32 v68, v68
	v_exp_f32_e32 v64, v64
	v_exp_f32_e32 v69, v69
	v_exp_f32_e32 v65, v65
	v_exp_f32_e32 v70, v70
	v_exp_f32_e32 v66, v66
	v_exp_f32_e32 v71, v71
	v_exp_f32_e32 v67, v67
	v_add_f32_e32 v68, 1.0, v68
	v_add_f32_e32 v64, 1.0, v64
	v_add_f32_e32 v69, 1.0, v69
	v_add_f32_e32 v65, 1.0, v65
	v_add_f32_e32 v70, 1.0, v70
	v_add_f32_e32 v66, 1.0, v66
	v_add_f32_e32 v71, 1.0, v71
	v_add_f32_e32 v67, 1.0, v67
	v_rcp_f32_e32 v68, v68
	v_rcp_f32_e32 v64, v64
	v_rcp_f32_e32 v69, v69
	v_rcp_f32_e32 v65, v65
	v_rcp_f32_e32 v70, v70
	v_rcp_f32_e32 v66, v66
	v_rcp_f32_e32 v71, v71
	v_rcp_f32_e32 v67, v67
	v_lshl_add_u64 v[76:77], v[142:143], 0, s[2:3]
	v_lshl_add_u64 v[78:79], s[20:21], 0, v[76:77]
	v_lshlrev_b32_e32 v80, 16, v224
	v_and_b32_e32 v72, 0xffff0000, v224
	v_lshlrev_b32_e32 v81, 16, v225
	v_and_b32_e32 v73, 0xffff0000, v225
	v_lshlrev_b32_e32 v82, 16, v226
	v_and_b32_e32 v74, 0xffff0000, v226
	v_lshlrev_b32_e32 v83, 16, v227
	v_and_b32_e32 v75, 0xffff0000, v227
	v_mul_f32_e32 v68, v68, v80
	v_mul_f32_e32 v80, v64, v82
	v_mul_f32_e32 v64, v69, v72
	v_mul_f32_e32 v69, v65, v74
	v_mul_f32_e32 v65, v70, v81
	v_mul_f32_e32 v70, v66, v83
	v_mul_f32_e32 v66, v71, v73
	v_mul_f32_e32 v67, v67, v75
	v_cvt_pk_bf16_f32 v64, v68, v64
	v_cvt_pk_bf16_f32 v65, v65, v66
	v_cvt_pk_bf16_f32 v66, v80, v69
	v_cvt_pk_bf16_f32 v67, v70, v67
	global_store_dwordx4 v[84:85], v[64:67], off offset:256
	global_load_dword v70, v[140:141], off offset:512
	s_nop 0
	global_load_dwordx4 v[64:67], v[78:79], off
	global_load_dwordx4 v[220:223], v[78:79], off offset:256
	v_lshl_add_u64 v[68:69], s[24:25], 0, v[76:77]
	s_waitcnt vmcnt(0)
; __device__ __forceinline__ float bf_lo(unsigned w) { return __uint_as_float(w << 16); }
; __device__ __forceinline__ float bf_hi(unsigned w) { return __uint_as_float(w & 0xffff0000u); }
; __device__ __forceinline__ float fast_rcp(float x) { return __builtin_amdgcn_rcpf(x); }
; __device__ __forceinline__ float fast_exp2(float x) { return __builtin_amdgcn_exp2f(x); }
; __device__ __forceinline__ u32x4 pack8(f32x4 v0, f32x4 v1) { u32x4 w; w.x = cvt_pk_bf16(v0[0], v0[1]); w.y = cvt_pk_bf16(v0[2], v0[3]); w.z = cvt_pk_bf16(v1[0], v1[1]); w.w = cvt_pk_bf16(v1[2], v1[3]); return w; }
;     __device__ __forceinline__ void operator()(const f32x4 (&acc)[2][2][4][2], const Unit& u, int wr, int wc, int fr, int fq) const {
;     ...
;             for (int m = 0; m < 4; ++m) { const size_t ro = (size_t)(row0 + ai * HALF + m * 16) * DM + col0; const float nr = -LOG2E * rs[row0 + ai * HALF + m * 16];
; #pragma unroll
;                 for (int bj = 0; bj < 2; ++bj) {
;                     const u32x4 pw = *(const u32x4*)(PP + ro + bj * HALF);
;                     const float pv[8] = {bf_lo(pw.x), bf_hi(pw.x), bf_lo(pw.y), bf_hi(pw.y), bf_lo(pw.z), bf_hi(pw.z), bf_lo(pw.w), bf_hi(pw.w)};
;                     f32x4 t0, t1;
; #pragma unroll
;                     for (int j = 0; j < 4; ++j) {
;                         t0[j] = fast_rcp(1.0f + fast_exp2(acc[ai][bj][m][0][j] * nr)) * pv[j];
;                         t1[j] = fast_rcp(1.0f + fast_exp2(acc[ai][bj][m][1][j] * nr)) * pv[4 + j]; }
;                     *(u32x4*)(O + ro + bj * HALF) = pack8(t0, t1); } }
	v_mul_f32_e32 v70, 0xbfb8aa3b, v70
	v_mul_f32_e32 v60, v60, v70
	v_mul_f32_e32 v56, v56, v70
	v_mul_f32_e32 v61, v61, v70
	v_mul_f32_e32 v57, v57, v70
	v_mul_f32_e32 v62, v62, v70
	v_mul_f32_e32 v58, v58, v70
	v_mul_f32_e32 v63, v63, v70
	v_mul_f32_e32 v59, v59, v70
	v_exp_f32_e32 v60, v60
	v_exp_f32_e32 v56, v56
	v_exp_f32_e32 v61, v61
	v_exp_f32_e32 v57, v57
	v_exp_f32_e32 v62, v62
	v_exp_f32_e32 v58, v58
	v_exp_f32_e32 v63, v63
	v_exp_f32_e32 v59, v59
	v_add_f32_e32 v60, 1.0, v60
	v_add_f32_e32 v56, 1.0, v56
	v_add_f32_e32 v61, 1.0, v61
	v_add_f32_e32 v57, 1.0, v57
	v_add_f32_e32 v62, 1.0, v62
	v_add_f32_e32 v58, 1.0, v58
	v_add_f32_e32 v63, 1.0, v63
	v_add_f32_e32 v59, 1.0, v59
	v_rcp_f32_e32 v60, v60
	v_rcp_f32_e32 v56, v56
	v_rcp_f32_e32 v61, v61
	v_rcp_f32_e32 v57, v57
	v_rcp_f32_e32 v62, v62
	v_rcp_f32_e32 v58, v58
	v_rcp_f32_e32 v63, v63
	v_rcp_f32_e32 v59, v59
	v_lshlrev_b32_e32 v71, 16, v64
	v_and_b32_e32 v64, 0xffff0000, v64
	v_lshlrev_b32_e32 v72, 16, v65
	v_and_b32_e32 v65, 0xffff0000, v65
	v_lshlrev_b32_e32 v73, 16, v66
	v_and_b32_e32 v66, 0xffff0000, v66
	v_lshlrev_b32_e32 v74, 16, v67
	v_and_b32_e32 v67, 0xffff0000, v67
	v_mul_f32_e32 v60, v60, v71
	v_mul_f32_e32 v71, v56, v73
	v_mul_f32_e32 v56, v61, v64
	v_mul_f32_e32 v61, v57, v66
	v_mul_f32_e32 v57, v62, v72
	v_mul_f32_e32 v62, v58, v74
	v_mul_f32_e32 v58, v63, v65
	v_mul_f32_e32 v59, v59, v67
	v_cvt_pk_bf16_f32 v56, v60, v56
	v_cvt_pk_bf16_f32 v57, v57, v58
	v_cvt_pk_bf16_f32 v58, v71, v61
	v_cvt_pk_bf16_f32 v59, v62, v59
	global_store_dwordx4 v[68:69], v[56:59], off
	v_mul_f32_e32 v52, v52, v70
	v_mul_f32_e32 v48, v48, v70
	v_mul_f32_e32 v53, v53, v70
	v_mul_f32_e32 v49, v49, v70
	v_mul_f32_e32 v54, v54, v70
	v_mul_f32_e32 v50, v50, v70
	v_mul_f32_e32 v55, v55, v70
	v_mul_f32_e32 v51, v51, v70
	v_exp_f32_e32 v52, v52
	v_exp_f32_e32 v48, v48
	v_exp_f32_e32 v53, v53
	v_exp_f32_e32 v49, v49
	v_exp_f32_e32 v54, v54
	v_exp_f32_e32 v50, v50
	v_exp_f32_e32 v55, v55
	v_exp_f32_e32 v51, v51
	v_add_f32_e32 v52, 1.0, v52
	v_add_f32_e32 v48, 1.0, v48
	v_add_f32_e32 v53, 1.0, v53
	v_add_f32_e32 v49, 1.0, v49
	v_add_f32_e32 v54, 1.0, v54
	v_add_f32_e32 v50, 1.0, v50
	v_add_f32_e32 v55, 1.0, v55
	v_add_f32_e32 v51, 1.0, v51
	v_rcp_f32_e32 v52, v52
	v_rcp_f32_e32 v48, v48
	v_rcp_f32_e32 v53, v53
	v_rcp_f32_e32 v49, v49
	v_rcp_f32_e32 v54, v54
	v_rcp_f32_e32 v50, v50
	v_rcp_f32_e32 v55, v55
	v_rcp_f32_e32 v51, v51
	v_lshl_add_u64 v[60:61], v[142:143], 0, s[6:7]
	v_lshl_add_u64 v[62:63], s[20:21], 0, v[60:61]
	v_lshlrev_b32_e32 v64, 16, v220
	v_and_b32_e32 v56, 0xffff0000, v220
	v_lshlrev_b32_e32 v65, 16, v221
	v_and_b32_e32 v57, 0xffff0000, v221
	v_lshlrev_b32_e32 v66, 16, v222
	v_and_b32_e32 v58, 0xffff0000, v222
	v_lshlrev_b32_e32 v67, 16, v223
	v_and_b32_e32 v59, 0xffff0000, v223
	v_mul_f32_e32 v52, v52, v64
	v_mul_f32_e32 v64, v48, v66
	v_mul_f32_e32 v48, v53, v56
	v_mul_f32_e32 v53, v49, v58
	v_mul_f32_e32 v49, v54, v65
	v_mul_f32_e32 v54, v50, v67
	v_mul_f32_e32 v50, v55, v57
	v_mul_f32_e32 v51, v51, v59
	v_cvt_pk_bf16_f32 v48, v52, v48
	v_cvt_pk_bf16_f32 v49, v49, v50
	v_cvt_pk_bf16_f32 v50, v64, v53
	v_cvt_pk_bf16_f32 v51, v54, v51
	global_store_dwordx4 v[68:69], v[48:51], off offset:256
	global_load_dword v54, v[140:141], off offset:576
	s_nop 0
	global_load_dwordx4 v[48:51], v[62:63], off
	global_load_dwordx4 v[224:227], v[62:63], off offset:256
	v_lshl_add_u64 v[52:53], s[24:25], 0, v[60:61]
	s_waitcnt vmcnt(0)
	v_mul_f32_e32 v54, 0xbfb8aa3b, v54
	v_mul_f32_e32 v44, v44, v54
	v_mul_f32_e32 v40, v40, v54
	v_mul_f32_e32 v45, v45, v54
	v_mul_f32_e32 v41, v41, v54
	v_mul_f32_e32 v46, v46, v54
	v_mul_f32_e32 v42, v42, v54
	v_mul_f32_e32 v47, v47, v54
	v_mul_f32_e32 v43, v43, v54
	v_exp_f32_e32 v44, v44
	v_exp_f32_e32 v40, v40
	v_exp_f32_e32 v45, v45
	v_exp_f32_e32 v41, v41
	v_exp_f32_e32 v46, v46
	v_exp_f32_e32 v42, v42
	v_exp_f32_e32 v47, v47
	v_exp_f32_e32 v43, v43
	v_add_f32_e32 v44, 1.0, v44
	v_add_f32_e32 v40, 1.0, v40
	v_add_f32_e32 v45, 1.0, v45
	v_add_f32_e32 v41, 1.0, v41
	v_add_f32_e32 v46, 1.0, v46
	v_add_f32_e32 v42, 1.0, v42
	v_add_f32_e32 v47, 1.0, v47
	v_add_f32_e32 v43, 1.0, v43
	v_rcp_f32_e32 v44, v44
	v_rcp_f32_e32 v40, v40
	v_rcp_f32_e32 v45, v45
	v_rcp_f32_e32 v41, v41
	v_rcp_f32_e32 v46, v46
	v_rcp_f32_e32 v42, v42
	v_rcp_f32_e32 v47, v47
	v_rcp_f32_e32 v43, v43
	v_lshlrev_b32_e32 v55, 16, v48
	v_and_b32_e32 v48, 0xffff0000, v48
	v_lshlrev_b32_e32 v56, 16, v49
	v_and_b32_e32 v49, 0xffff0000, v49
	v_lshlrev_b32_e32 v57, 16, v50
	v_and_b32_e32 v50, 0xffff0000, v50
	v_lshlrev_b32_e32 v58, 16, v51
	v_and_b32_e32 v51, 0xffff0000, v51
	v_mul_f32_e32 v44, v44, v55
	v_mul_f32_e32 v55, v40, v57
	v_mul_f32_e32 v40, v45, v48
	v_mul_f32_e32 v45, v41, v50
	v_mul_f32_e32 v41, v46, v56
	v_mul_f32_e32 v46, v42, v58
	v_mul_f32_e32 v42, v47, v49
	v_mul_f32_e32 v43, v43, v51
	v_cvt_pk_bf16_f32 v40, v44, v40
	v_cvt_pk_bf16_f32 v41, v41, v42
	v_cvt_pk_bf16_f32 v42, v55, v45
	v_cvt_pk_bf16_f32 v43, v46, v43
	global_store_dwordx4 v[52:53], v[40:43], off
	v_mul_f32_e32 v36, v36, v54
	v_mul_f32_e32 v32, v32, v54
	v_mul_f32_e32 v37, v37, v54
	v_mul_f32_e32 v33, v33, v54
	v_mul_f32_e32 v38, v38, v54
	v_mul_f32_e32 v34, v34, v54
	v_mul_f32_e32 v39, v39, v54
	v_mul_f32_e32 v35, v35, v54
	v_exp_f32_e32 v36, v36
	v_exp_f32_e32 v32, v32
	v_exp_f32_e32 v37, v37
	v_exp_f32_e32 v33, v33
	v_exp_f32_e32 v38, v38
	v_exp_f32_e32 v34, v34
	v_exp_f32_e32 v39, v39
	v_exp_f32_e32 v35, v35
	v_add_f32_e32 v36, 1.0, v36
	v_add_f32_e32 v32, 1.0, v32
	v_add_f32_e32 v37, 1.0, v37
	v_add_f32_e32 v33, 1.0, v33
	v_add_f32_e32 v38, 1.0, v38
	v_add_f32_e32 v34, 1.0, v34
	v_add_f32_e32 v39, 1.0, v39
	v_add_f32_e32 v35, 1.0, v35
	v_rcp_f32_e32 v36, v36
	v_rcp_f32_e32 v32, v32
	v_rcp_f32_e32 v37, v37
	v_rcp_f32_e32 v33, v33
	v_rcp_f32_e32 v38, v38
	v_rcp_f32_e32 v34, v34
	v_rcp_f32_e32 v39, v39
	v_rcp_f32_e32 v35, v35
	v_lshl_add_u64 v[44:45], v[142:143], 0, s[8:9]
	v_lshl_add_u64 v[46:47], s[20:21], 0, v[44:45]
	v_lshlrev_b32_e32 v48, 16, v224
	v_and_b32_e32 v40, 0xffff0000, v224
	v_lshlrev_b32_e32 v49, 16, v225
	v_and_b32_e32 v41, 0xffff0000, v225
	v_lshlrev_b32_e32 v50, 16, v226
	v_and_b32_e32 v42, 0xffff0000, v226
	v_lshlrev_b32_e32 v51, 16, v227
	v_and_b32_e32 v43, 0xffff0000, v227
	v_mul_f32_e32 v36, v36, v48
	v_mul_f32_e32 v48, v32, v50
	v_mul_f32_e32 v32, v37, v40
	v_mul_f32_e32 v37, v33, v42
	v_mul_f32_e32 v33, v38, v49
	v_mul_f32_e32 v38, v34, v51
	v_mul_f32_e32 v34, v39, v41
	v_mul_f32_e32 v35, v35, v43
	v_cvt_pk_bf16_f32 v32, v36, v32
	v_cvt_pk_bf16_f32 v33, v33, v34
	v_cvt_pk_bf16_f32 v34, v48, v37
	v_cvt_pk_bf16_f32 v35, v38, v35
	global_store_dwordx4 v[52:53], v[32:35], off offset:256
	global_load_dword v38, v[140:141], off offset:640
	s_nop 0
	global_load_dwordx4 v[32:35], v[46:47], off
	global_load_dwordx4 v[220:223], v[46:47], off offset:256
	v_lshl_add_u64 v[36:37], s[24:25], 0, v[44:45]
	s_waitcnt vmcnt(0)
; __device__ __forceinline__ float bf_lo(unsigned w) { return __uint_as_float(w << 16); }
; __device__ __forceinline__ float bf_hi(unsigned w) { return __uint_as_float(w & 0xffff0000u); }
; __device__ __forceinline__ float fast_rcp(float x) { return __builtin_amdgcn_rcpf(x); }
; __device__ __forceinline__ float fast_exp2(float x) { return __builtin_amdgcn_exp2f(x); }
; #define PG8_WAIT_V(n) asm volatile("s_waitcnt vmcnt(" #n ")" ::: "memory")
; #define PG8_BAR __builtin_amdgcn_s_barrier()
; __device__ __forceinline__ u32x4 pack8(f32x4 v0, f32x4 v1) { u32x4 w; w.x = cvt_pk_bf16(v0[0], v0[1]); w.y = cvt_pk_bf16(v0[2], v0[3]); w.z = cvt_pk_bf16(v1[0], v1[1]); w.w = cvt_pk_bf16(v1[2], v1[3]); return w; }
; template <class Epi>
; __device__ __forceinline__ void gemm_phase(LAS unsigned char* lds, const Gemm g, const StaticOrder& S, const Epi& E) {
;     ...
;         if (!has_next) break;
; #pragma unroll
;         for (int a = 0; a < 2; ++a)
; #pragma unroll
;             for (int b = 0; b < 2; ++b)
; #pragma unroll
;                 for (int m = 0; m < 4; ++m)
; #pragma unroll
;                     for (int n = 0; n < 2; ++n) acc[a][b][m][n] = (f32x4){0.f, 0.f, 0.f, 0.f};
;         cur = nxt; cA = nA; cB = nB; ++ui;
;     }
;     PG8_WAIT_V(0);
;     if (wr == 0) PG8_BAR;
;     PG8_BAR;
;     __device__ __forceinline__ void operator()(const f32x4 (&acc)[2][2][4][2], const Unit& u, int wr, int wc, int fr, int fq) const {
;     ...
;             for (int m = 0; m < 4; ++m) { const size_t ro = (size_t)(row0 + ai * HALF + m * 16) * DM + col0; const float nr = -LOG2E * rs[row0 + ai * HALF + m * 16];
; #pragma unroll
;                 for (int bj = 0; bj < 2; ++bj) {
;                     const u32x4 pw = *(const u32x4*)(PP + ro + bj * HALF);
;                     const float pv[8] = {bf_lo(pw.x), bf_hi(pw.x), bf_lo(pw.y), bf_hi(pw.y), bf_lo(pw.z), bf_hi(pw.z), bf_lo(pw.w), bf_hi(pw.w)};
;                     f32x4 t0, t1;
; #pragma unroll
;                     for (int j = 0; j < 4; ++j) {
;                         t0[j] = fast_rcp(1.0f + fast_exp2(acc[ai][bj][m][0][j] * nr)) * pv[j];
;                         t1[j] = fast_rcp(1.0f + fast_exp2(acc[ai][bj][m][1][j] * nr)) * pv[4 + j]; }
;                     *(u32x4*)(O + ro + bj * HALF) = pack8(t0, t1); } }
	v_mul_f32_e32 v38, 0xbfb8aa3b, v38
	v_mul_f32_e32 v28, v28, v38
	v_mul_f32_e32 v24, v24, v38
	v_mul_f32_e32 v29, v29, v38
	v_mul_f32_e32 v25, v25, v38
	v_mul_f32_e32 v30, v30, v38
	v_mul_f32_e32 v26, v26, v38
	v_mul_f32_e32 v31, v31, v38
	v_mul_f32_e32 v27, v27, v38
	v_exp_f32_e32 v28, v28
	v_exp_f32_e32 v24, v24
	v_exp_f32_e32 v29, v29
	v_exp_f32_e32 v25, v25
	v_exp_f32_e32 v30, v30
	v_exp_f32_e32 v26, v26
	v_exp_f32_e32 v31, v31
	v_exp_f32_e32 v27, v27
	v_add_f32_e32 v28, 1.0, v28
	v_add_f32_e32 v24, 1.0, v24
	v_add_f32_e32 v29, 1.0, v29
	v_add_f32_e32 v25, 1.0, v25
	v_add_f32_e32 v30, 1.0, v30
	v_add_f32_e32 v26, 1.0, v26
	v_add_f32_e32 v31, 1.0, v31
	v_add_f32_e32 v27, 1.0, v27
	v_rcp_f32_e32 v28, v28
	v_rcp_f32_e32 v24, v24
	v_rcp_f32_e32 v29, v29
	v_rcp_f32_e32 v25, v25
	v_rcp_f32_e32 v30, v30
	v_rcp_f32_e32 v26, v26
	v_rcp_f32_e32 v31, v31
	v_rcp_f32_e32 v27, v27
	v_lshlrev_b32_e32 v39, 16, v32
	v_and_b32_e32 v32, 0xffff0000, v32
	v_lshlrev_b32_e32 v40, 16, v33
	v_and_b32_e32 v33, 0xffff0000, v33
	v_lshlrev_b32_e32 v41, 16, v34
	v_and_b32_e32 v34, 0xffff0000, v34
	v_lshlrev_b32_e32 v42, 16, v35
	v_and_b32_e32 v35, 0xffff0000, v35
	v_mul_f32_e32 v28, v28, v39
	v_mul_f32_e32 v39, v24, v41
	v_mul_f32_e32 v24, v29, v32
	v_mul_f32_e32 v29, v25, v34
	v_mul_f32_e32 v25, v30, v40
	v_mul_f32_e32 v30, v26, v42
	v_mul_f32_e32 v26, v31, v33
	v_mul_f32_e32 v27, v27, v35
	v_cvt_pk_bf16_f32 v24, v28, v24
	v_cvt_pk_bf16_f32 v25, v25, v26
	v_cvt_pk_bf16_f32 v26, v39, v29
	v_cvt_pk_bf16_f32 v27, v30, v27
	global_store_dwordx4 v[36:37], v[24:27], off
	v_mul_f32_e32 v20, v20, v38
	v_mul_f32_e32 v16, v16, v38
	v_mul_f32_e32 v21, v21, v38
	v_mul_f32_e32 v17, v17, v38
	v_mul_f32_e32 v22, v22, v38
	v_mul_f32_e32 v18, v18, v38
	v_mul_f32_e32 v23, v23, v38
	v_mul_f32_e32 v19, v19, v38
	v_exp_f32_e32 v20, v20
	v_exp_f32_e32 v16, v16
	v_exp_f32_e32 v21, v21
	v_exp_f32_e32 v17, v17
	v_exp_f32_e32 v22, v22
	v_exp_f32_e32 v18, v18
	v_exp_f32_e32 v23, v23
	v_exp_f32_e32 v19, v19
	v_add_f32_e32 v20, 1.0, v20
	v_add_f32_e32 v16, 1.0, v16
	v_add_f32_e32 v21, 1.0, v21
	v_add_f32_e32 v17, 1.0, v17
	v_add_f32_e32 v22, 1.0, v22
	v_add_f32_e32 v18, 1.0, v18
	v_add_f32_e32 v23, 1.0, v23
	v_add_f32_e32 v19, 1.0, v19
	v_rcp_f32_e32 v20, v20
	v_rcp_f32_e32 v16, v16
	v_rcp_f32_e32 v21, v21
	v_rcp_f32_e32 v17, v17
	v_rcp_f32_e32 v22, v22
	v_rcp_f32_e32 v18, v18
	v_rcp_f32_e32 v23, v23
	v_rcp_f32_e32 v19, v19
	v_lshl_add_u64 v[28:29], v[142:143], 0, s[30:31]
	v_lshl_add_u64 v[30:31], s[20:21], 0, v[28:29]
	v_lshlrev_b32_e32 v32, 16, v220
	v_and_b32_e32 v24, 0xffff0000, v220
	v_lshlrev_b32_e32 v33, 16, v221
	v_and_b32_e32 v25, 0xffff0000, v221
	v_lshlrev_b32_e32 v34, 16, v222
	v_and_b32_e32 v26, 0xffff0000, v222
	v_lshlrev_b32_e32 v35, 16, v223
	v_and_b32_e32 v27, 0xffff0000, v223
	v_mul_f32_e32 v20, v20, v32
	v_mul_f32_e32 v32, v16, v34
	v_mul_f32_e32 v16, v21, v24
	v_mul_f32_e32 v21, v17, v26
	v_mul_f32_e32 v17, v22, v33
	v_mul_f32_e32 v22, v18, v35
	v_mul_f32_e32 v18, v23, v25
	v_mul_f32_e32 v19, v19, v27
	v_cvt_pk_bf16_f32 v16, v20, v16
	v_cvt_pk_bf16_f32 v17, v17, v18
	v_cvt_pk_bf16_f32 v18, v32, v21
	v_cvt_pk_bf16_f32 v19, v22, v19
	global_store_dwordx4 v[36:37], v[16:19], off offset:256
	global_load_dword v22, v[140:141], off offset:704
	s_nop 0
	global_load_dwordx4 v[16:19], v[30:31], off
	global_load_dwordx4 v[224:227], v[30:31], off offset:256
	v_lshl_add_u64 v[20:21], s[24:25], 0, v[28:29]
	s_waitcnt vmcnt(0)
	v_mul_f32_e32 v22, 0xbfb8aa3b, v22
	v_mul_f32_e32 v12, v12, v22
	v_mul_f32_e32 v8, v8, v22
	v_mul_f32_e32 v13, v13, v22
	v_mul_f32_e32 v9, v9, v22
	v_mul_f32_e32 v14, v14, v22
	v_mul_f32_e32 v10, v10, v22
	v_mul_f32_e32 v15, v15, v22
	v_mul_f32_e32 v11, v11, v22
	v_exp_f32_e32 v12, v12
	v_exp_f32_e32 v8, v8
	v_exp_f32_e32 v13, v13
	v_exp_f32_e32 v9, v9
	v_exp_f32_e32 v14, v14
	v_exp_f32_e32 v10, v10
	v_exp_f32_e32 v15, v15
	v_exp_f32_e32 v11, v11
	v_add_f32_e32 v12, 1.0, v12
	v_add_f32_e32 v8, 1.0, v8
	v_add_f32_e32 v13, 1.0, v13
	v_add_f32_e32 v9, 1.0, v9
	v_add_f32_e32 v14, 1.0, v14
	v_add_f32_e32 v10, 1.0, v10
	v_add_f32_e32 v15, 1.0, v15
	v_add_f32_e32 v11, 1.0, v11
	v_rcp_f32_e32 v12, v12
	v_rcp_f32_e32 v8, v8
	v_rcp_f32_e32 v13, v13
	v_rcp_f32_e32 v9, v9
	v_rcp_f32_e32 v14, v14
	v_rcp_f32_e32 v10, v10
	v_rcp_f32_e32 v15, v15
	v_rcp_f32_e32 v11, v11
	v_lshlrev_b32_e32 v23, 16, v16
	v_and_b32_e32 v16, 0xffff0000, v16
	v_lshlrev_b32_e32 v24, 16, v17
	v_and_b32_e32 v17, 0xffff0000, v17
	v_lshlrev_b32_e32 v25, 16, v18
	v_and_b32_e32 v18, 0xffff0000, v18
	v_lshlrev_b32_e32 v26, 16, v19
	v_and_b32_e32 v19, 0xffff0000, v19
	v_mul_f32_e32 v12, v12, v23
	v_mul_f32_e32 v23, v8, v25
	v_mul_f32_e32 v8, v13, v16
	v_mul_f32_e32 v13, v9, v18
	v_mul_f32_e32 v9, v14, v24
	v_mul_f32_e32 v14, v10, v26
	v_mul_f32_e32 v10, v15, v17
	v_mul_f32_e32 v11, v11, v19
	v_cvt_pk_bf16_f32 v8, v12, v8
	v_cvt_pk_bf16_f32 v9, v9, v10
	v_cvt_pk_bf16_f32 v10, v23, v13
	v_cvt_pk_bf16_f32 v11, v14, v11
	global_store_dwordx4 v[20:21], v[8:11], off
	v_mul_f32_e32 v4, v4, v22
	v_mul_f32_e32 v0, v0, v22
	v_mul_f32_e32 v5, v5, v22
	v_mul_f32_e32 v1, v1, v22
	v_mul_f32_e32 v6, v6, v22
	v_mul_f32_e32 v2, v2, v22
	v_mul_f32_e32 v7, v7, v22
	v_mul_f32_e32 v3, v3, v22
	v_exp_f32_e32 v4, v4
	v_exp_f32_e32 v0, v0
	v_exp_f32_e32 v5, v5
	v_exp_f32_e32 v1, v1
	v_exp_f32_e32 v6, v6
	v_exp_f32_e32 v2, v2
	v_exp_f32_e32 v7, v7
	v_exp_f32_e32 v3, v3
	v_add_f32_e32 v4, 1.0, v4
	v_add_f32_e32 v0, 1.0, v0
	v_add_f32_e32 v5, 1.0, v5
	v_add_f32_e32 v1, 1.0, v1
	v_add_f32_e32 v6, 1.0, v6
	v_add_f32_e32 v2, 1.0, v2
	v_add_f32_e32 v7, 1.0, v7
	v_add_f32_e32 v3, 1.0, v3
	v_rcp_f32_e32 v4, v4
	v_rcp_f32_e32 v0, v0
	v_rcp_f32_e32 v5, v5
	v_rcp_f32_e32 v1, v1
	v_rcp_f32_e32 v6, v6
	v_rcp_f32_e32 v2, v2
	v_rcp_f32_e32 v7, v7
	v_rcp_f32_e32 v3, v3
	v_lshlrev_b32_e32 v12, 16, v224
	v_and_b32_e32 v8, 0xffff0000, v224
	v_lshlrev_b32_e32 v13, 16, v225
	v_and_b32_e32 v9, 0xffff0000, v225
	v_lshlrev_b32_e32 v14, 16, v226
	v_and_b32_e32 v10, 0xffff0000, v226
	v_lshlrev_b32_e32 v15, 16, v227
	v_and_b32_e32 v11, 0xffff0000, v227
	v_mul_f32_e32 v4, v4, v12
	v_mul_f32_e32 v12, v0, v14
	v_mul_f32_e32 v0, v5, v8
	v_mul_f32_e32 v5, v1, v10
	v_mul_f32_e32 v1, v6, v13
	v_mul_f32_e32 v6, v2, v15
	v_mul_f32_e32 v2, v7, v9
	v_mul_f32_e32 v3, v3, v11
	v_cvt_pk_bf16_f32 v0, v4, v0
	v_cvt_pk_bf16_f32 v1, v1, v2
	v_cvt_pk_bf16_f32 v2, v12, v5
	v_cvt_pk_bf16_f32 v3, v6, v3
	global_store_dwordx4 v[20:21], v[0:3], off offset:256
	s_cbranch_vccz .LBB0_996
	s_waitcnt vmcnt(0)
	s_cmpk_gt_u32 s10, 0xff
	s_cbranch_scc1 .LBB0_1003
	s_barrier
